# stack10: GEMM K-loops without per-segment s_setprio flips, one static s_setprio 1 per unit for the trailing wave half (waves 4-7), on top of stack8
# speedup vs baseline: 1.0031x; 1.0031x over previous
; #define PG8_STAGE(bufoff, gbase, voff) do { _Pragma("unroll") for (int _i = 0; _i < 2; ++_i) \
;         __builtin_amdgcn_global_load_lds((const unsigned*)((const char*)(gbase) + (voff)[_i]), (PG8_LAS unsigned*)(lds + (bufoff) + ldsw + _i * 8192), 16, 0, 0); } while (0)
; #define PG8_LDA(dst, b, h) do { _Pragma("unroll") for (int m = 0; m < 4; ++m) _Pragma("unroll") for (int k = 0; k < 2; ++k) dst[m][k] = *(const PG8_LAS bf16x8*)(lds + PG8_SA(b, h) + aoff + m * 2048 + k * 1024); } while (0)
; #define PG8_LDB(dst, b, h) do { _Pragma("unroll") for (int n = 0; n < 2; ++n) _Pragma("unroll") for (int k = 0; k < 2; ++k) dst[n][k] = *(const PG8_LAS bf16x8*)(lds + PG8_SB(b, h) + boff + n * 2048 + k * 1024); } while (0)
; #define PG8_MMA(ai, bj, At, Bt) do { __builtin_amdgcn_s_setprio(1); _Pragma("unroll") for (int m = 0; m < 4; ++m) _Pragma("unroll") for (int n = 0; n < 2; ++n) _Pragma("unroll") for (int k = 0; k < 2; ++k) \
;         acc[ai][bj][m][n] = __builtin_amdgcn_mfma_f32_16x16x32_bf16(Bt[n][k], At[m][k], acc[ai][bj][m][n], 0, 0, 0); __builtin_amdgcn_s_setprio(0); } while (0)
; #define PG8_WAIT_V(n) asm volatile("s_waitcnt vmcnt(" #n ")" ::: "memory")
; #define PG8_BAR __builtin_amdgcn_s_barrier()
; template <class Epi, class Sched, bool ALIGN_EPI = false, bool SP2 = false>
; __device__ __forceinline__ void gemm_phase(PG8_LAS unsigned char* lds, const Gemm g, const Sched& S, const Epi& E, const int wid_in) {
;     ...
;         for (int t = 0; t < nt; t += 2) {
;             const bool last = (t == nt - 2);
;             const char* a1 = cA + (size_t)(t + 1) * kstep;
;             const char* a2 = last ? nA : cA + (size_t)(t + 2) * kstep; const char* b2 = last ? nB : cB + (size_t)(t + 2) * kstep;
;             const char* a3 = a2 + kstep; const char* b3 = b2 + kstep;
;             if (last && has_next) S.a_ready(nxt);
;             if constexpr (SP2) {
;             PG8_LDB(B0, 0, 0); PG8_LDB(B1, 0, 1); PG8_SCHED; PG8_LDA(At, 0, 0); PG8_STAGE(PG8_SA(1, 1), a1 + hstep, voffA);
;             PG8_WAIT_V(8); PG8_WAIT_L(0); PG8_BAR; PG8_MMA(0, 0, At, B0); PG8_MMA(0, 1, At, B1); PG8_BAR; PG8_SCHED;
;             PG8_LDA(At, 0, 1); PG8_STAGE(PG8_SB(0, 0), b2, voffB); PG8_STAGE(PG8_SB(0, 1), b2 + hstep, voffB); PG8_STAGE(PG8_SA(0, 0), a2, voffA);
;             PG8_WAIT_V(8); PG8_WAIT_L(0); PG8_BAR; PG8_MMA(1, 0, At, B0); PG8_MMA(1, 1, At, B1); PG8_BAR; PG8_SCHED;
.LBB0_104:
	s_ashr_i32 s43, s42, 31
	s_lshl_b64 s[22:23], s[42:43], 19
	v_readlane_b32 s8, v243, 52
	v_readlane_b32 s9, v243, 53
	s_add_u32 s44, s8, s22
	s_addc_u32 s45, s9, s23
	s_and_b64 s[22:23], s[38:39], exec
	s_cselect_b32 s43, s45, s49
	s_cselect_b32 s57, s44, s48
	s_ashr_i32 s41, s40, 31
	s_lshl_b64 s[22:23], s[40:41], 19
	v_readlane_b32 s2, v243, 18
	s_add_u32 s46, s2, s22
	v_readlane_b32 s2, v243, 19
	s_addc_u32 s47, s2, s23
	s_and_b64 s[22:23], s[38:39], exec
	s_cselect_b32 s16, s47, s51
	s_cselect_b32 s41, s46, s50
	s_add_u32 s48, s48, 0x40080
	s_addc_u32 s49, s49, 0
	s_add_u32 s58, s50, 0x100
	s_addc_u32 s59, s51, 0
	s_mov_b32 s60, -2
	v_readlane_b32 s100, v243, 63
	v_readlane_b32 s101, v242, 0
	s_cmp_lg_u64 s[100:101], 0
	s_cbranch_scc1 .Lprio_done_105
	s_setprio 1
.Lprio_done_105:
	s_add_u32 s2, s48, 0xfffc0080
	s_addc_u32 s8, s49, -1
	s_add_i32 s22, 0, 0x10000
	s_cmp_eq_u32 s60, 12
	s_cselect_b32 s53, s43, s8
	s_cselect_b32 s52, s57, s2
	s_cselect_b32 s51, s16, s59
	s_cselect_b32 s50, s41, s58
	s_add_i32 s2, 0, 0x14000
	v_add_u32_e32 v154, s22, v144
	v_add_u32_e32 v170, s2, v144
	ds_read_b128 v[140:143], v154
	ds_read_b128 v[146:149], v154 offset:1024
	ds_read_b128 v[150:153], v154 offset:2048
	ds_read_b128 v[154:157], v154 offset:3072
	ds_read_b128 v[158:161], v170
	ds_read_b128 v[162:165], v170 offset:1024
	ds_read_b128 v[166:169], v170 offset:2048
	ds_read_b128 v[170:173], v170 offset:3072
	v_lshl_add_u64 v[228:229], s[48:49], 0, v[136:137]
	s_add_i32 m0, s4, 0xc000
	ds_read_b128 v[174:177], v145
	ds_read_b128 v[190:193], v145 offset:1024
	ds_read_b128 v[194:197], v145 offset:2048
	ds_read_b128 v[198:201], v145 offset:3072
	ds_read_b128 v[212:215], v145 offset:4096
	ds_read_b128 v[216:219], v145 offset:5120
	ds_read_b128 v[220:223], v145 offset:6144
	ds_read_b128 v[224:227], v145 offset:7168
	global_load_lds_dwordx4 v[228:229], off
	v_lshl_add_u64 v[228:229], s[48:49], 0, v[138:139]
	s_add_i32 m0, s4, 0xe000
	s_nop 0
	global_load_lds_dwordx4 v[228:229], off
	s_waitcnt vmcnt(8)
	s_waitcnt lgkmcnt(0)
	s_barrier
	s_waitcnt lgkmcnt(0)
	v_mfma_f32_16x16x32_bf16 v[126:129], v[140:143], v[174:177], 0
	v_mfma_f32_16x16x32_bf16 v[122:125], v[150:153], v[174:177], 0
	v_mfma_f32_16x16x32_bf16 v[114:117], v[140:143], v[194:197], 0
	v_mfma_f32_16x16x32_bf16 v[110:113], v[150:153], v[194:197], 0
	v_mfma_f32_16x16x32_bf16 v[98:101], v[140:143], v[212:215], 0
	v_mfma_f32_16x16x32_bf16 v[94:97], v[150:153], v[212:215], 0
	v_mfma_f32_16x16x32_bf16 v[82:85], v[140:143], v[220:223], 0
	v_mfma_f32_16x16x32_bf16 v[78:81], v[150:153], v[220:223], 0
	v_mfma_f32_16x16x32_bf16 v[126:129], v[146:149], v[190:193], v[126:129]
	v_mfma_f32_16x16x32_bf16 v[122:125], v[154:157], v[190:193], v[122:125]
	v_mfma_f32_16x16x32_bf16 v[114:117], v[146:149], v[198:201], v[114:117]
	v_mfma_f32_16x16x32_bf16 v[110:113], v[154:157], v[198:201], v[110:113]
	v_mfma_f32_16x16x32_bf16 v[98:101], v[146:149], v[216:219], v[98:101]
	v_mfma_f32_16x16x32_bf16 v[94:97], v[154:157], v[216:219], v[94:97]
	v_mfma_f32_16x16x32_bf16 v[82:85], v[146:149], v[224:227], v[82:85]
	v_mfma_f32_16x16x32_bf16 v[78:81], v[154:157], v[224:227], v[78:81]
	v_mfma_f32_16x16x32_bf16 v[106:109], v[158:161], v[174:177], 0
	v_mfma_f32_16x16x32_bf16 v[118:121], v[166:169], v[174:177], 0
	v_mfma_f32_16x16x32_bf16 v[90:93], v[158:161], v[194:197], 0
	v_mfma_f32_16x16x32_bf16 v[102:105], v[166:169], v[194:197], 0
	v_mfma_f32_16x16x32_bf16 v[74:77], v[158:161], v[212:215], 0
	v_mfma_f32_16x16x32_bf16 v[86:89], v[166:169], v[212:215], 0
	v_mfma_f32_16x16x32_bf16 v[66:69], v[158:161], v[220:223], 0
	v_mfma_f32_16x16x32_bf16 v[70:73], v[166:169], v[220:223], 0
	v_mfma_f32_16x16x32_bf16 v[106:109], v[162:165], v[190:193], v[106:109]
	v_mfma_f32_16x16x32_bf16 v[118:121], v[170:173], v[190:193], v[118:121]
	v_mfma_f32_16x16x32_bf16 v[90:93], v[162:165], v[198:201], v[90:93]
	v_mfma_f32_16x16x32_bf16 v[102:105], v[170:173], v[198:201], v[102:105]
	v_mfma_f32_16x16x32_bf16 v[74:77], v[162:165], v[216:219], v[74:77]
	v_mfma_f32_16x16x32_bf16 v[86:89], v[170:173], v[216:219], v[86:89]
	v_mfma_f32_16x16x32_bf16 v[66:69], v[162:165], v[224:227], v[66:69]
	v_mfma_f32_16x16x32_bf16 v[70:73], v[170:173], v[224:227], v[70:73]
	s_barrier
	s_add_i32 s8, s22, s3
	v_lshl_add_u64 v[228:229], s[50:51], 0, v[0:1]
	s_mov_b32 m0, s8
	ds_read_b128 v[174:177], v145 offset:16384
	ds_read_b128 v[190:193], v145 offset:17408
	ds_read_b128 v[194:197], v145 offset:18432
	ds_read_b128 v[198:201], v145 offset:19456
	ds_read_b128 v[212:215], v145 offset:20480
	ds_read_b128 v[216:219], v145 offset:21504
	ds_read_b128 v[220:223], v145 offset:22528
	ds_read_b128 v[224:227], v145 offset:23552
	global_load_lds_dwordx4 v[228:229], off
	s_add_i32 m0, s8, 0x2000
	s_add_u32 s22, s50, 0x40000
	v_lshl_add_u64 v[230:231], s[50:51], 0, v[130:131]
	s_addc_u32 s23, s51, 0
	s_add_i32 s2, s2, s3
	global_load_lds_dwordx4 v[230:231], off
	v_lshl_add_u64 v[232:233], s[22:23], 0, v[0:1]
	s_mov_b32 m0, s2
	v_lshl_add_u64 v[234:235], s[52:53], 0, v[132:133]
	global_load_lds_dwordx4 v[232:233], off
	v_lshl_add_u64 v[232:233], s[22:23], 0, v[130:131]
	s_add_i32 m0, s2, 0x2000
	s_nop 0
	global_load_lds_dwordx4 v[232:233], off
	v_lshl_add_u64 v[232:233], s[52:53], 0, v[134:135]
	s_mov_b32 m0, s4
	s_nop 0
	global_load_lds_dwordx4 v[232:233], off
	s_mov_b32 m0, s5
	s_nop 0
	global_load_lds_dwordx4 v[234:235], off
	s_waitcnt vmcnt(8)
	s_waitcnt lgkmcnt(0)
	s_barrier
; #define PG8_STAGE(bufoff, gbase, voff) do { _Pragma("unroll") for (int _i = 0; _i < 2; ++_i) \
;         __builtin_amdgcn_global_load_lds((const unsigned*)((const char*)(gbase) + (voff)[_i]), (PG8_LAS unsigned*)(lds + (bufoff) + ldsw + _i * 8192), 16, 0, 0); } while (0)
; #define PG8_LDA(dst, b, h) do { _Pragma("unroll") for (int m = 0; m < 4; ++m) _Pragma("unroll") for (int k = 0; k < 2; ++k) dst[m][k] = *(const PG8_LAS bf16x8*)(lds + PG8_SA(b, h) + aoff + m * 2048 + k * 1024); } while (0)
; #define PG8_LDB(dst, b, h) do { _Pragma("unroll") for (int n = 0; n < 2; ++n) _Pragma("unroll") for (int k = 0; k < 2; ++k) dst[n][k] = *(const PG8_LAS bf16x8*)(lds + PG8_SB(b, h) + boff + n * 2048 + k * 1024); } while (0)
; #define PG8_MMA(ai, bj, At, Bt) do { __builtin_amdgcn_s_setprio(1); _Pragma("unroll") for (int m = 0; m < 4; ++m) _Pragma("unroll") for (int n = 0; n < 2; ++n) _Pragma("unroll") for (int k = 0; k < 2; ++k) \
;         acc[ai][bj][m][n] = __builtin_amdgcn_mfma_f32_16x16x32_bf16(Bt[n][k], At[m][k], acc[ai][bj][m][n], 0, 0, 0); __builtin_amdgcn_s_setprio(0); } while (0)
; #define PG8_WAIT_V(n) asm volatile("s_waitcnt vmcnt(" #n ")" ::: "memory")
; #define PG8_WAIT_L(n) asm volatile("s_waitcnt lgkmcnt(" #n ")" ::: "memory")
; #define PG8_BAR __builtin_amdgcn_s_barrier()
; #define PG8_SCHED __builtin_amdgcn_sched_barrier(0)
; template <class Epi, class Sched, bool ALIGN_EPI = false, bool SP2 = false>
; __device__ __forceinline__ void gemm_phase(PG8_LAS unsigned char* lds, const Gemm g, const Sched& S, const Epi& E, const int wid_in) {
;     ...
;             PG8_WAIT_V(8); PG8_WAIT_L(0); PG8_BAR; PG8_MMA(1, 0, At, B0); PG8_MMA(1, 1, At, B1); PG8_BAR; PG8_SCHED;
;             PG8_LDB(B0, 1, 0); PG8_LDB(B1, 1, 1); PG8_SCHED; PG8_LDA(At, 1, 0); PG8_STAGE(PG8_SA(0, 1), a2 + hstep, voffA);
;             PG8_WAIT_V(8); PG8_WAIT_L(0); PG8_BAR; PG8_MMA(0, 0, At, B0); PG8_MMA(0, 1, At, B1); PG8_BAR; PG8_SCHED;
;             PG8_LDA(At, 1, 1); PG8_STAGE(PG8_SB(1, 0), b3, voffB); PG8_STAGE(PG8_SB(1, 1), b3 + hstep, voffB); PG8_STAGE(PG8_SA(1, 0), a3, voffA);
;             PG8_WAIT_V(8); PG8_WAIT_L(0); PG8_BAR; PG8_MMA(1, 0, At, B0); PG8_MMA(1, 1, At, B1); PG8_BAR; PG8_SCHED;
	s_waitcnt lgkmcnt(0)
	v_mfma_f32_16x16x32_bf16 v[62:65], v[140:143], v[174:177], 0
	v_mfma_f32_16x16x32_bf16 v[58:61], v[150:153], v[174:177], 0
	v_mfma_f32_16x16x32_bf16 v[50:53], v[140:143], v[194:197], 0
	v_mfma_f32_16x16x32_bf16 v[46:49], v[150:153], v[194:197], 0
	v_mfma_f32_16x16x32_bf16 v[34:37], v[140:143], v[212:215], 0
	v_mfma_f32_16x16x32_bf16 v[30:33], v[150:153], v[212:215], 0
	v_mfma_f32_16x16x32_bf16 v[18:21], v[140:143], v[220:223], 0
	v_mfma_f32_16x16x32_bf16 v[14:17], v[150:153], v[220:223], 0
	v_mfma_f32_16x16x32_bf16 v[62:65], v[146:149], v[190:193], v[62:65]
	v_mfma_f32_16x16x32_bf16 v[58:61], v[154:157], v[190:193], v[58:61]
	v_mfma_f32_16x16x32_bf16 v[50:53], v[146:149], v[198:201], v[50:53]
	v_mfma_f32_16x16x32_bf16 v[46:49], v[154:157], v[198:201], v[46:49]
	v_mfma_f32_16x16x32_bf16 v[34:37], v[146:149], v[216:219], v[34:37]
	v_mfma_f32_16x16x32_bf16 v[30:33], v[154:157], v[216:219], v[30:33]
	v_mfma_f32_16x16x32_bf16 v[18:21], v[146:149], v[224:227], v[18:21]
	v_mfma_f32_16x16x32_bf16 v[14:17], v[154:157], v[224:227], v[14:17]
	v_mfma_f32_16x16x32_bf16 v[42:45], v[158:161], v[174:177], 0
	v_mfma_f32_16x16x32_bf16 v[54:57], v[166:169], v[174:177], 0
	v_mfma_f32_16x16x32_bf16 v[26:29], v[158:161], v[194:197], 0
	v_mfma_f32_16x16x32_bf16 v[38:41], v[166:169], v[194:197], 0
	v_mfma_f32_16x16x32_bf16 v[10:13], v[158:161], v[212:215], 0
	v_mfma_f32_16x16x32_bf16 v[22:25], v[166:169], v[212:215], 0
	v_mfma_f32_16x16x32_bf16 v[2:5], v[158:161], v[220:223], 0
	v_mfma_f32_16x16x32_bf16 v[6:9], v[166:169], v[220:223], 0
	v_mfma_f32_16x16x32_bf16 v[42:45], v[162:165], v[190:193], v[42:45]
	v_mfma_f32_16x16x32_bf16 v[54:57], v[170:173], v[190:193], v[54:57]
	v_mfma_f32_16x16x32_bf16 v[26:29], v[162:165], v[198:201], v[26:29]
	v_mfma_f32_16x16x32_bf16 v[38:41], v[170:173], v[198:201], v[38:41]
	v_mfma_f32_16x16x32_bf16 v[10:13], v[162:165], v[216:219], v[10:13]
	v_mfma_f32_16x16x32_bf16 v[22:25], v[170:173], v[216:219], v[22:25]
	v_mfma_f32_16x16x32_bf16 v[2:5], v[162:165], v[224:227], v[2:5]
	v_mfma_f32_16x16x32_bf16 v[6:9], v[170:173], v[224:227], v[6:9]
	s_barrier
	s_add_i32 s2, 0, 0x18000
	s_add_i32 s8, 0, 0x1c000
	v_add_u32_e32 v154, s2, v144
	v_add_u32_e32 v170, s8, v144
	ds_read_b128 v[140:143], v154
	ds_read_b128 v[146:149], v154 offset:1024
	ds_read_b128 v[150:153], v154 offset:2048
	ds_read_b128 v[154:157], v154 offset:3072
	ds_read_b128 v[158:161], v170
	ds_read_b128 v[162:165], v170 offset:1024
	ds_read_b128 v[166:169], v170 offset:2048
	ds_read_b128 v[170:173], v170 offset:3072
	s_add_u32 s22, s52, 0x40000
	s_addc_u32 s23, s53, 0
	s_mov_b32 m0, s12
	v_lshl_add_u64 v[236:237], s[22:23], 0, v[134:135]
	ds_read_b128 v[174:177], v145 offset:32768
	ds_read_b128 v[190:193], v145 offset:33792
	ds_read_b128 v[194:197], v145 offset:34816
	ds_read_b128 v[198:201], v145 offset:35840
	ds_read_b128 v[212:215], v145 offset:36864
	ds_read_b128 v[216:219], v145 offset:37888
	ds_read_b128 v[220:223], v145 offset:38912
	ds_read_b128 v[224:227], v145 offset:39936
	global_load_lds_dwordx4 v[236:237], off
	v_lshl_add_u64 v[236:237], s[22:23], 0, v[132:133]
	s_mov_b32 m0, s13
	s_nop 0
	global_load_lds_dwordx4 v[236:237], off
	s_waitcnt vmcnt(8)
	s_waitcnt lgkmcnt(0)
	s_barrier
	s_waitcnt lgkmcnt(0)
	v_mfma_f32_16x16x32_bf16 v[126:129], v[140:143], v[174:177], v[126:129]
	v_mfma_f32_16x16x32_bf16 v[122:125], v[150:153], v[174:177], v[122:125]
	v_mfma_f32_16x16x32_bf16 v[114:117], v[140:143], v[194:197], v[114:117]
	v_mfma_f32_16x16x32_bf16 v[110:113], v[150:153], v[194:197], v[110:113]
	v_mfma_f32_16x16x32_bf16 v[98:101], v[140:143], v[212:215], v[98:101]
	v_mfma_f32_16x16x32_bf16 v[94:97], v[150:153], v[212:215], v[94:97]
	v_mfma_f32_16x16x32_bf16 v[82:85], v[140:143], v[220:223], v[82:85]
	v_mfma_f32_16x16x32_bf16 v[78:81], v[150:153], v[220:223], v[78:81]
	v_mfma_f32_16x16x32_bf16 v[126:129], v[146:149], v[190:193], v[126:129]
	v_mfma_f32_16x16x32_bf16 v[122:125], v[154:157], v[190:193], v[122:125]
	v_mfma_f32_16x16x32_bf16 v[114:117], v[146:149], v[198:201], v[114:117]
	v_mfma_f32_16x16x32_bf16 v[110:113], v[154:157], v[198:201], v[110:113]
	v_mfma_f32_16x16x32_bf16 v[98:101], v[146:149], v[216:219], v[98:101]
	v_mfma_f32_16x16x32_bf16 v[94:97], v[154:157], v[216:219], v[94:97]
	v_mfma_f32_16x16x32_bf16 v[82:85], v[146:149], v[224:227], v[82:85]
	v_mfma_f32_16x16x32_bf16 v[78:81], v[154:157], v[224:227], v[78:81]
	v_mfma_f32_16x16x32_bf16 v[106:109], v[158:161], v[174:177], v[106:109]
	v_mfma_f32_16x16x32_bf16 v[118:121], v[166:169], v[174:177], v[118:121]
	v_mfma_f32_16x16x32_bf16 v[90:93], v[158:161], v[194:197], v[90:93]
	v_mfma_f32_16x16x32_bf16 v[102:105], v[166:169], v[194:197], v[102:105]
	v_mfma_f32_16x16x32_bf16 v[74:77], v[158:161], v[212:215], v[74:77]
	v_mfma_f32_16x16x32_bf16 v[86:89], v[166:169], v[212:215], v[86:89]
	v_mfma_f32_16x16x32_bf16 v[66:69], v[158:161], v[220:223], v[66:69]
	v_mfma_f32_16x16x32_bf16 v[70:73], v[166:169], v[220:223], v[70:73]
	v_mfma_f32_16x16x32_bf16 v[106:109], v[162:165], v[190:193], v[106:109]
	v_mfma_f32_16x16x32_bf16 v[118:121], v[170:173], v[190:193], v[118:121]
	v_mfma_f32_16x16x32_bf16 v[90:93], v[162:165], v[198:201], v[90:93]
	v_mfma_f32_16x16x32_bf16 v[102:105], v[170:173], v[198:201], v[102:105]
	v_mfma_f32_16x16x32_bf16 v[74:77], v[162:165], v[216:219], v[74:77]
	v_mfma_f32_16x16x32_bf16 v[86:89], v[170:173], v[216:219], v[86:89]
	v_mfma_f32_16x16x32_bf16 v[66:69], v[162:165], v[224:227], v[66:69]
	v_mfma_f32_16x16x32_bf16 v[70:73], v[170:173], v[224:227], v[70:73]
	s_barrier
; #define PG8_STAGE(bufoff, gbase, voff) do { _Pragma("unroll") for (int _i = 0; _i < 2; ++_i) \
;         __builtin_amdgcn_global_load_lds((const unsigned*)((const char*)(gbase) + (voff)[_i]), (PG8_LAS unsigned*)(lds + (bufoff) + ldsw + _i * 8192), 16, 0, 0); } while (0)
; #define PG8_LDA(dst, b, h) do { _Pragma("unroll") for (int m = 0; m < 4; ++m) _Pragma("unroll") for (int k = 0; k < 2; ++k) dst[m][k] = *(const PG8_LAS bf16x8*)(lds + PG8_SA(b, h) + aoff + m * 2048 + k * 1024); } while (0)
; #define PG8_LDB(dst, b, h) do { _Pragma("unroll") for (int n = 0; n < 2; ++n) _Pragma("unroll") for (int k = 0; k < 2; ++k) dst[n][k] = *(const PG8_LAS bf16x8*)(lds + PG8_SB(b, h) + boff + n * 2048 + k * 1024); } while (0)
; #define PG8_MMA(ai, bj, At, Bt) do { __builtin_amdgcn_s_setprio(1); _Pragma("unroll") for (int m = 0; m < 4; ++m) _Pragma("unroll") for (int n = 0; n < 2; ++n) _Pragma("unroll") for (int k = 0; k < 2; ++k) \
;         acc[ai][bj][m][n] = __builtin_amdgcn_mfma_f32_16x16x32_bf16(Bt[n][k], At[m][k], acc[ai][bj][m][n], 0, 0, 0); __builtin_amdgcn_s_setprio(0); } while (0)
; #define PG8_WAIT_V(n) asm volatile("s_waitcnt vmcnt(" #n ")" ::: "memory")
; #define PG8_WAIT_L(n) asm volatile("s_waitcnt lgkmcnt(" #n ")" ::: "memory")
; #define PG8_BAR __builtin_amdgcn_s_barrier()
; #define PG8_SCHED __builtin_amdgcn_sched_barrier(0)
; template <class Epi, class Sched, bool ALIGN_EPI = false, bool SP2 = false>
; __device__ __forceinline__ void gemm_phase(PG8_LAS unsigned char* lds, const Gemm g, const Sched& S, const Epi& E, const int wid_in) {
;     ...
;             PG8_LDB(B0, 0, 0); PG8_LDB(B1, 0, 1); PG8_SCHED; PG8_LDA(At, 0, 0); PG8_STAGE(PG8_SA(1, 1), a1 + hstep, voffA);
;             PG8_WAIT_V(8); PG8_WAIT_L(0); PG8_BAR; PG8_MMA(0, 0, At, B0); PG8_MMA(0, 1, At, B1); PG8_BAR; PG8_SCHED;
;     ...
;             PG8_WAIT_V(8); PG8_WAIT_L(0); PG8_BAR; PG8_MMA(0, 0, At, B0); PG8_MMA(0, 1, At, B1); PG8_BAR; PG8_SCHED;
;             PG8_LDA(At, 1, 1); PG8_STAGE(PG8_SB(1, 0), b3, voffB); PG8_STAGE(PG8_SB(1, 1), b3 + hstep, voffB); PG8_STAGE(PG8_SA(1, 0), a3, voffA);
;             PG8_WAIT_V(8); PG8_WAIT_L(0); PG8_BAR; PG8_MMA(1, 0, At, B0); PG8_MMA(1, 1, At, B1); PG8_BAR; PG8_SCHED;
	s_add_i32 s2, s2, s3
	v_lshl_add_u64 v[228:229], v[228:229], 0, s[64:65]
	s_mov_b32 m0, s2
	ds_read_b128 v[174:177], v145 offset:49152
	ds_read_b128 v[190:193], v145 offset:50176
	ds_read_b128 v[194:197], v145 offset:51200
	ds_read_b128 v[198:201], v145 offset:52224
	ds_read_b128 v[212:215], v145 offset:53248
	ds_read_b128 v[216:219], v145 offset:54272
	ds_read_b128 v[220:223], v145 offset:55296
	ds_read_b128 v[224:227], v145 offset:56320
	global_load_lds_dwordx4 v[228:229], off
	s_add_i32 m0, s2, 0x2000
	s_add_u32 s22, s50, 0x40080
	v_lshl_add_u64 v[228:229], v[230:231], 0, s[64:65]
	s_addc_u32 s23, s51, 0
	s_add_i32 s2, s8, s3
	global_load_lds_dwordx4 v[228:229], off
	v_lshl_add_u64 v[228:229], s[22:23], 0, v[0:1]
	s_mov_b32 m0, s2
	s_nop 0
	global_load_lds_dwordx4 v[228:229], off
	v_lshl_add_u64 v[228:229], s[22:23], 0, v[130:131]
	s_add_i32 m0, s2, 0x2000
	s_nop 0
	global_load_lds_dwordx4 v[228:229], off
	v_lshl_add_u64 v[228:229], v[232:233], 0, s[64:65]
	s_mov_b32 m0, s36
	s_nop 0
	global_load_lds_dwordx4 v[228:229], off
	v_lshl_add_u64 v[228:229], v[234:235], 0, s[64:65]
	s_mov_b32 m0, s37
	s_nop 0
	global_load_lds_dwordx4 v[228:229], off
	s_waitcnt vmcnt(8)
	s_waitcnt lgkmcnt(0)
	s_barrier
	s_waitcnt lgkmcnt(0)
	v_mfma_f32_16x16x32_bf16 v[62:65], v[140:143], v[174:177], v[62:65]
	v_mfma_f32_16x16x32_bf16 v[58:61], v[150:153], v[174:177], v[58:61]
	v_mfma_f32_16x16x32_bf16 v[50:53], v[140:143], v[194:197], v[50:53]
	v_mfma_f32_16x16x32_bf16 v[46:49], v[150:153], v[194:197], v[46:49]
	v_mfma_f32_16x16x32_bf16 v[34:37], v[140:143], v[212:215], v[34:37]
	v_mfma_f32_16x16x32_bf16 v[30:33], v[150:153], v[212:215], v[30:33]
	v_mfma_f32_16x16x32_bf16 v[18:21], v[140:143], v[220:223], v[18:21]
	v_mfma_f32_16x16x32_bf16 v[14:17], v[150:153], v[220:223], v[14:17]
	v_mfma_f32_16x16x32_bf16 v[62:65], v[146:149], v[190:193], v[62:65]
	v_mfma_f32_16x16x32_bf16 v[58:61], v[154:157], v[190:193], v[58:61]
	v_mfma_f32_16x16x32_bf16 v[50:53], v[146:149], v[198:201], v[50:53]
	v_mfma_f32_16x16x32_bf16 v[46:49], v[154:157], v[198:201], v[46:49]
	v_mfma_f32_16x16x32_bf16 v[34:37], v[146:149], v[216:219], v[34:37]
	v_mfma_f32_16x16x32_bf16 v[30:33], v[154:157], v[216:219], v[30:33]
	v_mfma_f32_16x16x32_bf16 v[18:21], v[146:149], v[224:227], v[18:21]
	v_mfma_f32_16x16x32_bf16 v[14:17], v[154:157], v[224:227], v[14:17]
	v_mfma_f32_16x16x32_bf16 v[42:45], v[158:161], v[174:177], v[42:45]
	v_mfma_f32_16x16x32_bf16 v[54:57], v[166:169], v[174:177], v[54:57]
	v_mfma_f32_16x16x32_bf16 v[26:29], v[158:161], v[194:197], v[26:29]
	v_mfma_f32_16x16x32_bf16 v[38:41], v[166:169], v[194:197], v[38:41]
	v_mfma_f32_16x16x32_bf16 v[10:13], v[158:161], v[212:215], v[10:13]
	v_mfma_f32_16x16x32_bf16 v[22:25], v[166:169], v[212:215], v[22:25]
	v_mfma_f32_16x16x32_bf16 v[2:5], v[158:161], v[220:223], v[2:5]
	v_mfma_f32_16x16x32_bf16 v[6:9], v[166:169], v[220:223], v[6:9]
	v_mfma_f32_16x16x32_bf16 v[42:45], v[162:165], v[190:193], v[42:45]
	v_mfma_f32_16x16x32_bf16 v[54:57], v[170:173], v[190:193], v[54:57]
	v_mfma_f32_16x16x32_bf16 v[26:29], v[162:165], v[198:201], v[26:29]
	v_mfma_f32_16x16x32_bf16 v[38:41], v[170:173], v[198:201], v[38:41]
	v_mfma_f32_16x16x32_bf16 v[10:13], v[162:165], v[216:219], v[10:13]
	v_mfma_f32_16x16x32_bf16 v[22:25], v[170:173], v[216:219], v[22:25]
	v_mfma_f32_16x16x32_bf16 v[2:5], v[162:165], v[224:227], v[2:5]
	v_mfma_f32_16x16x32_bf16 v[6:9], v[170:173], v[224:227], v[6:9]
	s_barrier
	s_add_i32 s60, s60, 2
	s_add_u32 s48, s48, 0x100
	s_addc_u32 s49, s49, 0
	s_add_u32 s58, s58, 0x100
	s_addc_u32 s59, s59, 0
	s_cmp_gt_u32 s60, 13
.LBB0_105:
	s_add_u32 s2, s48, 0xfffc0080
	s_addc_u32 s8, s49, -1
	s_add_i32 s22, 0, 0x10000
	s_cmp_eq_u32 s60, 12
	s_cselect_b32 s53, s43, s8
	s_cselect_b32 s52, s57, s2
	s_cselect_b32 s51, s16, s59
	s_cselect_b32 s50, s41, s58
	s_add_i32 s2, 0, 0x14000
	v_add_u32_e32 v154, s22, v144
	v_add_u32_e32 v170, s2, v144
	ds_read_b128 v[140:143], v154
	ds_read_b128 v[146:149], v154 offset:1024
	ds_read_b128 v[150:153], v154 offset:2048
	ds_read_b128 v[154:157], v154 offset:3072
	ds_read_b128 v[158:161], v170
	ds_read_b128 v[162:165], v170 offset:1024
	ds_read_b128 v[166:169], v170 offset:2048
	ds_read_b128 v[170:173], v170 offset:3072
	v_lshl_add_u64 v[228:229], s[48:49], 0, v[136:137]
	s_add_i32 m0, s4, 0xc000
	ds_read_b128 v[174:177], v145
	ds_read_b128 v[190:193], v145 offset:1024
	ds_read_b128 v[194:197], v145 offset:2048
	ds_read_b128 v[198:201], v145 offset:3072
	ds_read_b128 v[212:215], v145 offset:4096
	ds_read_b128 v[216:219], v145 offset:5120
	ds_read_b128 v[220:223], v145 offset:6144
	ds_read_b128 v[224:227], v145 offset:7168
	global_load_lds_dwordx4 v[228:229], off
	v_lshl_add_u64 v[228:229], s[48:49], 0, v[138:139]
	s_add_i32 m0, s4, 0xe000
	s_nop 0
	global_load_lds_dwordx4 v[228:229], off
	s_waitcnt vmcnt(8)
	s_waitcnt lgkmcnt(0)
	s_barrier
; #define PG8_STAGE(bufoff, gbase, voff) do { _Pragma("unroll") for (int _i = 0; _i < 2; ++_i) \
;         __builtin_amdgcn_global_load_lds((const unsigned*)((const char*)(gbase) + (voff)[_i]), (PG8_LAS unsigned*)(lds + (bufoff) + ldsw + _i * 8192), 16, 0, 0); } while (0)
; #define PG8_LDA(dst, b, h) do { _Pragma("unroll") for (int m = 0; m < 4; ++m) _Pragma("unroll") for (int k = 0; k < 2; ++k) dst[m][k] = *(const PG8_LAS bf16x8*)(lds + PG8_SA(b, h) + aoff + m * 2048 + k * 1024); } while (0)
; #define PG8_LDB(dst, b, h) do { _Pragma("unroll") for (int n = 0; n < 2; ++n) _Pragma("unroll") for (int k = 0; k < 2; ++k) dst[n][k] = *(const PG8_LAS bf16x8*)(lds + PG8_SB(b, h) + boff + n * 2048 + k * 1024); } while (0)
; #define PG8_MMA(ai, bj, At, Bt) do { __builtin_amdgcn_s_setprio(1); _Pragma("unroll") for (int m = 0; m < 4; ++m) _Pragma("unroll") for (int n = 0; n < 2; ++n) _Pragma("unroll") for (int k = 0; k < 2; ++k) \
;         acc[ai][bj][m][n] = __builtin_amdgcn_mfma_f32_16x16x32_bf16(Bt[n][k], At[m][k], acc[ai][bj][m][n], 0, 0, 0); __builtin_amdgcn_s_setprio(0); } while (0)
; #define PG8_WAIT_V(n) asm volatile("s_waitcnt vmcnt(" #n ")" ::: "memory")
; #define PG8_WAIT_L(n) asm volatile("s_waitcnt lgkmcnt(" #n ")" ::: "memory")
; #define PG8_BAR __builtin_amdgcn_s_barrier()
; #define PG8_SCHED __builtin_amdgcn_sched_barrier(0)
; template <class Epi, class Sched, bool ALIGN_EPI = false, bool SP2 = false>
; __device__ __forceinline__ void gemm_phase(PG8_LAS unsigned char* lds, const Gemm g, const Sched& S, const Epi& E, const int wid_in) {
;     ...
;             PG8_WAIT_V(8); PG8_WAIT_L(0); PG8_BAR; PG8_MMA(0, 0, At, B0); PG8_MMA(0, 1, At, B1); PG8_BAR; PG8_SCHED;
;             PG8_LDA(At, 0, 1); PG8_STAGE(PG8_SB(0, 0), b2, voffB); PG8_STAGE(PG8_SB(0, 1), b2 + hstep, voffB); PG8_STAGE(PG8_SA(0, 0), a2, voffA);
;             PG8_WAIT_V(8); PG8_WAIT_L(0); PG8_BAR; PG8_MMA(1, 0, At, B0); PG8_MMA(1, 1, At, B1); PG8_BAR; PG8_SCHED;
;             PG8_LDB(B0, 1, 0); PG8_LDB(B1, 1, 1); PG8_SCHED; PG8_LDA(At, 1, 0); PG8_STAGE(PG8_SA(0, 1), a2 + hstep, voffA);
;             PG8_WAIT_V(8); PG8_WAIT_L(0); PG8_BAR; PG8_MMA(0, 0, At, B0); PG8_MMA(0, 1, At, B1); PG8_BAR; PG8_SCHED;
	s_waitcnt lgkmcnt(0)
	v_mfma_f32_16x16x32_bf16 v[126:129], v[140:143], v[174:177], v[126:129]
	v_mfma_f32_16x16x32_bf16 v[122:125], v[150:153], v[174:177], v[122:125]
	v_mfma_f32_16x16x32_bf16 v[114:117], v[140:143], v[194:197], v[114:117]
	v_mfma_f32_16x16x32_bf16 v[110:113], v[150:153], v[194:197], v[110:113]
	v_mfma_f32_16x16x32_bf16 v[98:101], v[140:143], v[212:215], v[98:101]
	v_mfma_f32_16x16x32_bf16 v[94:97], v[150:153], v[212:215], v[94:97]
	v_mfma_f32_16x16x32_bf16 v[82:85], v[140:143], v[220:223], v[82:85]
	v_mfma_f32_16x16x32_bf16 v[78:81], v[150:153], v[220:223], v[78:81]
	v_mfma_f32_16x16x32_bf16 v[126:129], v[146:149], v[190:193], v[126:129]
	v_mfma_f32_16x16x32_bf16 v[122:125], v[154:157], v[190:193], v[122:125]
	v_mfma_f32_16x16x32_bf16 v[114:117], v[146:149], v[198:201], v[114:117]
	v_mfma_f32_16x16x32_bf16 v[110:113], v[154:157], v[198:201], v[110:113]
	v_mfma_f32_16x16x32_bf16 v[98:101], v[146:149], v[216:219], v[98:101]
	v_mfma_f32_16x16x32_bf16 v[94:97], v[154:157], v[216:219], v[94:97]
	v_mfma_f32_16x16x32_bf16 v[82:85], v[146:149], v[224:227], v[82:85]
	v_mfma_f32_16x16x32_bf16 v[78:81], v[154:157], v[224:227], v[78:81]
	v_mfma_f32_16x16x32_bf16 v[106:109], v[158:161], v[174:177], v[106:109]
	v_mfma_f32_16x16x32_bf16 v[118:121], v[166:169], v[174:177], v[118:121]
	v_mfma_f32_16x16x32_bf16 v[90:93], v[158:161], v[194:197], v[90:93]
	v_mfma_f32_16x16x32_bf16 v[102:105], v[166:169], v[194:197], v[102:105]
	v_mfma_f32_16x16x32_bf16 v[74:77], v[158:161], v[212:215], v[74:77]
	v_mfma_f32_16x16x32_bf16 v[86:89], v[166:169], v[212:215], v[86:89]
	v_mfma_f32_16x16x32_bf16 v[66:69], v[158:161], v[220:223], v[66:69]
	v_mfma_f32_16x16x32_bf16 v[70:73], v[166:169], v[220:223], v[70:73]
	v_mfma_f32_16x16x32_bf16 v[106:109], v[162:165], v[190:193], v[106:109]
	v_mfma_f32_16x16x32_bf16 v[118:121], v[170:173], v[190:193], v[118:121]
	v_mfma_f32_16x16x32_bf16 v[90:93], v[162:165], v[198:201], v[90:93]
	v_mfma_f32_16x16x32_bf16 v[102:105], v[170:173], v[198:201], v[102:105]
	v_mfma_f32_16x16x32_bf16 v[74:77], v[162:165], v[216:219], v[74:77]
	v_mfma_f32_16x16x32_bf16 v[86:89], v[170:173], v[216:219], v[86:89]
	v_mfma_f32_16x16x32_bf16 v[66:69], v[162:165], v[224:227], v[66:69]
	v_mfma_f32_16x16x32_bf16 v[70:73], v[170:173], v[224:227], v[70:73]
	s_barrier
	s_add_i32 s8, s22, s3
	v_lshl_add_u64 v[228:229], s[50:51], 0, v[0:1]
	s_mov_b32 m0, s8
	ds_read_b128 v[174:177], v145 offset:16384
	ds_read_b128 v[190:193], v145 offset:17408
	ds_read_b128 v[194:197], v145 offset:18432
	ds_read_b128 v[198:201], v145 offset:19456
	ds_read_b128 v[212:215], v145 offset:20480
	ds_read_b128 v[216:219], v145 offset:21504
	ds_read_b128 v[220:223], v145 offset:22528
	ds_read_b128 v[224:227], v145 offset:23552
	global_load_lds_dwordx4 v[228:229], off
	s_add_i32 m0, s8, 0x2000
	s_add_u32 s22, s50, 0x40000
	v_lshl_add_u64 v[230:231], s[50:51], 0, v[130:131]
	s_addc_u32 s23, s51, 0
	s_add_i32 s2, s2, s3
	global_load_lds_dwordx4 v[230:231], off
	v_lshl_add_u64 v[232:233], s[22:23], 0, v[0:1]
	s_mov_b32 m0, s2
	v_lshl_add_u64 v[234:235], s[52:53], 0, v[132:133]
	global_load_lds_dwordx4 v[232:233], off
	v_lshl_add_u64 v[232:233], s[22:23], 0, v[130:131]
	s_add_i32 m0, s2, 0x2000
	s_nop 0
	global_load_lds_dwordx4 v[232:233], off
	v_lshl_add_u64 v[232:233], s[52:53], 0, v[134:135]
	s_mov_b32 m0, s4
	s_nop 0
	global_load_lds_dwordx4 v[232:233], off
	s_mov_b32 m0, s5
	s_nop 0
	global_load_lds_dwordx4 v[234:235], off
	s_waitcnt vmcnt(8)
	s_waitcnt lgkmcnt(0)
	s_barrier
	s_waitcnt lgkmcnt(0)
	v_mfma_f32_16x16x32_bf16 v[62:65], v[140:143], v[174:177], v[62:65]
	v_mfma_f32_16x16x32_bf16 v[58:61], v[150:153], v[174:177], v[58:61]
	v_mfma_f32_16x16x32_bf16 v[50:53], v[140:143], v[194:197], v[50:53]
	v_mfma_f32_16x16x32_bf16 v[46:49], v[150:153], v[194:197], v[46:49]
	v_mfma_f32_16x16x32_bf16 v[34:37], v[140:143], v[212:215], v[34:37]
	v_mfma_f32_16x16x32_bf16 v[30:33], v[150:153], v[212:215], v[30:33]
	v_mfma_f32_16x16x32_bf16 v[18:21], v[140:143], v[220:223], v[18:21]
	v_mfma_f32_16x16x32_bf16 v[14:17], v[150:153], v[220:223], v[14:17]
	v_mfma_f32_16x16x32_bf16 v[62:65], v[146:149], v[190:193], v[62:65]
	v_mfma_f32_16x16x32_bf16 v[58:61], v[154:157], v[190:193], v[58:61]
	v_mfma_f32_16x16x32_bf16 v[50:53], v[146:149], v[198:201], v[50:53]
	v_mfma_f32_16x16x32_bf16 v[46:49], v[154:157], v[198:201], v[46:49]
	v_mfma_f32_16x16x32_bf16 v[34:37], v[146:149], v[216:219], v[34:37]
	v_mfma_f32_16x16x32_bf16 v[30:33], v[154:157], v[216:219], v[30:33]
	v_mfma_f32_16x16x32_bf16 v[18:21], v[146:149], v[224:227], v[18:21]
	v_mfma_f32_16x16x32_bf16 v[14:17], v[154:157], v[224:227], v[14:17]
	v_mfma_f32_16x16x32_bf16 v[42:45], v[158:161], v[174:177], v[42:45]
	v_mfma_f32_16x16x32_bf16 v[54:57], v[166:169], v[174:177], v[54:57]
	v_mfma_f32_16x16x32_bf16 v[26:29], v[158:161], v[194:197], v[26:29]
	v_mfma_f32_16x16x32_bf16 v[38:41], v[166:169], v[194:197], v[38:41]
	v_mfma_f32_16x16x32_bf16 v[10:13], v[158:161], v[212:215], v[10:13]
	v_mfma_f32_16x16x32_bf16 v[22:25], v[166:169], v[212:215], v[22:25]
	v_mfma_f32_16x16x32_bf16 v[2:5], v[158:161], v[220:223], v[2:5]
	v_mfma_f32_16x16x32_bf16 v[6:9], v[166:169], v[220:223], v[6:9]
	v_mfma_f32_16x16x32_bf16 v[42:45], v[162:165], v[190:193], v[42:45]
	v_mfma_f32_16x16x32_bf16 v[54:57], v[170:173], v[190:193], v[54:57]
	v_mfma_f32_16x16x32_bf16 v[26:29], v[162:165], v[198:201], v[26:29]
	v_mfma_f32_16x16x32_bf16 v[38:41], v[170:173], v[198:201], v[38:41]
	v_mfma_f32_16x16x32_bf16 v[10:13], v[162:165], v[216:219], v[10:13]
	v_mfma_f32_16x16x32_bf16 v[22:25], v[170:173], v[216:219], v[22:25]
	v_mfma_f32_16x16x32_bf16 v[2:5], v[162:165], v[224:227], v[2:5]
	v_mfma_f32_16x16x32_bf16 v[6:9], v[170:173], v[224:227], v[6:9]
	s_barrier
; #define PG8_STAGE(bufoff, gbase, voff) do { _Pragma("unroll") for (int _i = 0; _i < 2; ++_i) \
;         __builtin_amdgcn_global_load_lds((const unsigned*)((const char*)(gbase) + (voff)[_i]), (PG8_LAS unsigned*)(lds + (bufoff) + ldsw + _i * 8192), 16, 0, 0); } while (0)
; #define PG8_LDA(dst, b, h) do { _Pragma("unroll") for (int m = 0; m < 4; ++m) _Pragma("unroll") for (int k = 0; k < 2; ++k) dst[m][k] = *(const PG8_LAS bf16x8*)(lds + PG8_SA(b, h) + aoff + m * 2048 + k * 1024); } while (0)
; #define PG8_LDB(dst, b, h) do { _Pragma("unroll") for (int n = 0; n < 2; ++n) _Pragma("unroll") for (int k = 0; k < 2; ++k) dst[n][k] = *(const PG8_LAS bf16x8*)(lds + PG8_SB(b, h) + boff + n * 2048 + k * 1024); } while (0)
; #define PG8_MMA(ai, bj, At, Bt) do { __builtin_amdgcn_s_setprio(1); _Pragma("unroll") for (int m = 0; m < 4; ++m) _Pragma("unroll") for (int n = 0; n < 2; ++n) _Pragma("unroll") for (int k = 0; k < 2; ++k) \
;         acc[ai][bj][m][n] = __builtin_amdgcn_mfma_f32_16x16x32_bf16(Bt[n][k], At[m][k], acc[ai][bj][m][n], 0, 0, 0); __builtin_amdgcn_s_setprio(0); } while (0)
; #define PG8_WAIT_V(n) asm volatile("s_waitcnt vmcnt(" #n ")" ::: "memory")
; #define PG8_WAIT_L(n) asm volatile("s_waitcnt lgkmcnt(" #n ")" ::: "memory")
; #define PG8_BAR __builtin_amdgcn_s_barrier()
; #define PG8_SCHED __builtin_amdgcn_sched_barrier(0)
; template <class Epi, class Sched, bool ALIGN_EPI = false, bool SP2 = false>
; __device__ __forceinline__ void gemm_phase(PG8_LAS unsigned char* lds, const Gemm g, const Sched& S, const Epi& E, const int wid_in) {
;     ...
;             PG8_LDB(B0, 1, 0); PG8_LDB(B1, 1, 1); PG8_SCHED; PG8_LDA(At, 1, 0); PG8_STAGE(PG8_SA(0, 1), a2 + hstep, voffA);
;             PG8_WAIT_V(8); PG8_WAIT_L(0); PG8_BAR; PG8_MMA(0, 0, At, B0); PG8_MMA(0, 1, At, B1); PG8_BAR; PG8_SCHED;
	s_add_i32 s2, 0, 0x18000
	s_add_i32 s8, 0, 0x1c000
	v_add_u32_e32 v154, s2, v144
	v_add_u32_e32 v170, s8, v144
	ds_read_b128 v[140:143], v154
	ds_read_b128 v[146:149], v154 offset:1024
	ds_read_b128 v[150:153], v154 offset:2048
	ds_read_b128 v[154:157], v154 offset:3072
	ds_read_b128 v[158:161], v170
	ds_read_b128 v[162:165], v170 offset:1024
	ds_read_b128 v[166:169], v170 offset:2048
	ds_read_b128 v[170:173], v170 offset:3072
	s_add_u32 s22, s52, 0x40000
	s_addc_u32 s23, s53, 0
	s_mov_b32 m0, s12
	v_lshl_add_u64 v[236:237], s[22:23], 0, v[134:135]
	ds_read_b128 v[174:177], v145 offset:32768
	ds_read_b128 v[190:193], v145 offset:33792
	ds_read_b128 v[194:197], v145 offset:34816
	ds_read_b128 v[198:201], v145 offset:35840
	ds_read_b128 v[212:215], v145 offset:36864
	ds_read_b128 v[216:219], v145 offset:37888
	ds_read_b128 v[220:223], v145 offset:38912
	ds_read_b128 v[224:227], v145 offset:39936
	global_load_lds_dwordx4 v[236:237], off
	v_lshl_add_u64 v[236:237], s[22:23], 0, v[132:133]
	s_mov_b32 m0, s13
	s_nop 0
	global_load_lds_dwordx4 v[236:237], off
	s_waitcnt vmcnt(8)
	s_waitcnt lgkmcnt(0)
	s_barrier
	s_waitcnt lgkmcnt(0)
	v_mfma_f32_16x16x32_bf16 v[126:129], v[140:143], v[174:177], v[126:129]
	v_mfma_f32_16x16x32_bf16 v[122:125], v[150:153], v[174:177], v[122:125]
	v_mfma_f32_16x16x32_bf16 v[114:117], v[140:143], v[194:197], v[114:117]
	v_mfma_f32_16x16x32_bf16 v[110:113], v[150:153], v[194:197], v[110:113]
	v_mfma_f32_16x16x32_bf16 v[98:101], v[140:143], v[212:215], v[98:101]
	v_mfma_f32_16x16x32_bf16 v[94:97], v[150:153], v[212:215], v[94:97]
	v_mfma_f32_16x16x32_bf16 v[82:85], v[140:143], v[220:223], v[82:85]
	v_mfma_f32_16x16x32_bf16 v[78:81], v[150:153], v[220:223], v[78:81]
	v_mfma_f32_16x16x32_bf16 v[126:129], v[146:149], v[190:193], v[126:129]
	v_mfma_f32_16x16x32_bf16 v[122:125], v[154:157], v[190:193], v[122:125]
	v_mfma_f32_16x16x32_bf16 v[114:117], v[146:149], v[198:201], v[114:117]
	v_mfma_f32_16x16x32_bf16 v[110:113], v[154:157], v[198:201], v[110:113]
	v_mfma_f32_16x16x32_bf16 v[98:101], v[146:149], v[216:219], v[98:101]
	v_mfma_f32_16x16x32_bf16 v[94:97], v[154:157], v[216:219], v[94:97]
	v_mfma_f32_16x16x32_bf16 v[82:85], v[146:149], v[224:227], v[82:85]
	v_mfma_f32_16x16x32_bf16 v[78:81], v[154:157], v[224:227], v[78:81]
	v_mfma_f32_16x16x32_bf16 v[106:109], v[158:161], v[174:177], v[106:109]
	v_mfma_f32_16x16x32_bf16 v[118:121], v[166:169], v[174:177], v[118:121]
	v_mfma_f32_16x16x32_bf16 v[90:93], v[158:161], v[194:197], v[90:93]
	v_mfma_f32_16x16x32_bf16 v[102:105], v[166:169], v[194:197], v[102:105]
	v_mfma_f32_16x16x32_bf16 v[74:77], v[158:161], v[212:215], v[74:77]
	v_mfma_f32_16x16x32_bf16 v[86:89], v[166:169], v[212:215], v[86:89]
	v_mfma_f32_16x16x32_bf16 v[66:69], v[158:161], v[220:223], v[66:69]
	v_mfma_f32_16x16x32_bf16 v[70:73], v[166:169], v[220:223], v[70:73]
	v_mfma_f32_16x16x32_bf16 v[106:109], v[162:165], v[190:193], v[106:109]
	v_mfma_f32_16x16x32_bf16 v[118:121], v[170:173], v[190:193], v[118:121]
	v_mfma_f32_16x16x32_bf16 v[90:93], v[162:165], v[198:201], v[90:93]
	v_mfma_f32_16x16x32_bf16 v[102:105], v[170:173], v[198:201], v[102:105]
	v_mfma_f32_16x16x32_bf16 v[74:77], v[162:165], v[216:219], v[74:77]
	v_mfma_f32_16x16x32_bf16 v[86:89], v[170:173], v[216:219], v[86:89]
	v_mfma_f32_16x16x32_bf16 v[66:69], v[162:165], v[224:227], v[66:69]
	v_mfma_f32_16x16x32_bf16 v[70:73], v[170:173], v[224:227], v[70:73]
	s_barrier
; #define PG8_STAGE(bufoff, gbase, voff) do { _Pragma("unroll") for (int _i = 0; _i < 2; ++_i) \
;         __builtin_amdgcn_global_load_lds((const unsigned*)((const char*)(gbase) + (voff)[_i]), (PG8_LAS unsigned*)(lds + (bufoff) + ldsw + _i * 8192), 16, 0, 0); } while (0)
; #define PG8_LDA(dst, b, h) do { _Pragma("unroll") for (int m = 0; m < 4; ++m) _Pragma("unroll") for (int k = 0; k < 2; ++k) dst[m][k] = *(const PG8_LAS bf16x8*)(lds + PG8_SA(b, h) + aoff + m * 2048 + k * 1024); } while (0)
; #define PG8_MMA(ai, bj, At, Bt) do { __builtin_amdgcn_s_setprio(1); _Pragma("unroll") for (int m = 0; m < 4; ++m) _Pragma("unroll") for (int n = 0; n < 2; ++n) _Pragma("unroll") for (int k = 0; k < 2; ++k) \
;         acc[ai][bj][m][n] = __builtin_amdgcn_mfma_f32_16x16x32_bf16(Bt[n][k], At[m][k], acc[ai][bj][m][n], 0, 0, 0); __builtin_amdgcn_s_setprio(0); } while (0)
; #define PG8_WAIT_V(n) asm volatile("s_waitcnt vmcnt(" #n ")" ::: "memory")
; #define PG8_WAIT_L(n) asm volatile("s_waitcnt lgkmcnt(" #n ")" ::: "memory")
; #define PG8_BAR __builtin_amdgcn_s_barrier()
; #define PG8_SCHED __builtin_amdgcn_sched_barrier(0)
; template <class Epi, class Sched, bool ALIGN_EPI = false, bool SP2 = false>
; __device__ __forceinline__ void gemm_phase(PG8_LAS unsigned char* lds, const Gemm g, const Sched& S, const Epi& E, const int wid_in) {
;     ...
;             PG8_LDA(At, 1, 1); PG8_STAGE(PG8_SB(1, 0), b3, voffB); PG8_STAGE(PG8_SB(1, 1), b3 + hstep, voffB); PG8_STAGE(PG8_SA(1, 0), a3, voffA);
;             PG8_WAIT_V(8); PG8_WAIT_L(0); PG8_BAR; PG8_MMA(1, 0, At, B0); PG8_MMA(1, 1, At, B1); PG8_BAR; PG8_SCHED;
;     ...
;         if constexpr (ALIGN_EPI) { if (wr == 0) PG8_BAR; }
	s_add_i32 s2, s2, s3
	v_lshl_add_u64 v[228:229], v[228:229], 0, s[64:65]
	s_mov_b32 m0, s2
	ds_read_b128 v[174:177], v145 offset:49152
	ds_read_b128 v[190:193], v145 offset:50176
	ds_read_b128 v[194:197], v145 offset:51200
	ds_read_b128 v[198:201], v145 offset:52224
	ds_read_b128 v[212:215], v145 offset:53248
	ds_read_b128 v[216:219], v145 offset:54272
	ds_read_b128 v[220:223], v145 offset:55296
	ds_read_b128 v[224:227], v145 offset:56320
	global_load_lds_dwordx4 v[228:229], off
	s_add_i32 m0, s2, 0x2000
	s_add_u32 s22, s50, 0x40080
	v_lshl_add_u64 v[228:229], v[230:231], 0, s[64:65]
	s_addc_u32 s23, s51, 0
	s_add_i32 s2, s8, s3
	global_load_lds_dwordx4 v[228:229], off
	v_lshl_add_u64 v[228:229], s[22:23], 0, v[0:1]
	s_mov_b32 m0, s2
	s_nop 0
	global_load_lds_dwordx4 v[228:229], off
	v_lshl_add_u64 v[228:229], s[22:23], 0, v[130:131]
	s_add_i32 m0, s2, 0x2000
	s_nop 0
	global_load_lds_dwordx4 v[228:229], off
	v_lshl_add_u64 v[228:229], v[232:233], 0, s[64:65]
	s_mov_b32 m0, s36
	s_nop 0
	global_load_lds_dwordx4 v[228:229], off
	v_lshl_add_u64 v[228:229], v[234:235], 0, s[64:65]
	s_mov_b32 m0, s37
	s_nop 0
	global_load_lds_dwordx4 v[228:229], off
	s_waitcnt vmcnt(8)
	s_waitcnt lgkmcnt(0)
	s_barrier
	s_waitcnt lgkmcnt(0)
	v_mfma_f32_16x16x32_bf16 v[62:65], v[140:143], v[174:177], v[62:65]
	v_mfma_f32_16x16x32_bf16 v[58:61], v[150:153], v[174:177], v[58:61]
	v_mfma_f32_16x16x32_bf16 v[50:53], v[140:143], v[194:197], v[50:53]
	v_mfma_f32_16x16x32_bf16 v[46:49], v[150:153], v[194:197], v[46:49]
	v_mfma_f32_16x16x32_bf16 v[34:37], v[140:143], v[212:215], v[34:37]
	v_mfma_f32_16x16x32_bf16 v[30:33], v[150:153], v[212:215], v[30:33]
	v_mfma_f32_16x16x32_bf16 v[18:21], v[140:143], v[220:223], v[18:21]
	v_mfma_f32_16x16x32_bf16 v[14:17], v[150:153], v[220:223], v[14:17]
	v_mfma_f32_16x16x32_bf16 v[62:65], v[146:149], v[190:193], v[62:65]
	v_mfma_f32_16x16x32_bf16 v[58:61], v[154:157], v[190:193], v[58:61]
	v_mfma_f32_16x16x32_bf16 v[50:53], v[146:149], v[198:201], v[50:53]
	v_mfma_f32_16x16x32_bf16 v[46:49], v[154:157], v[198:201], v[46:49]
	v_mfma_f32_16x16x32_bf16 v[34:37], v[146:149], v[216:219], v[34:37]
	v_mfma_f32_16x16x32_bf16 v[30:33], v[154:157], v[216:219], v[30:33]
	v_mfma_f32_16x16x32_bf16 v[18:21], v[146:149], v[224:227], v[18:21]
	v_mfma_f32_16x16x32_bf16 v[14:17], v[154:157], v[224:227], v[14:17]
	v_mfma_f32_16x16x32_bf16 v[42:45], v[158:161], v[174:177], v[42:45]
	v_mfma_f32_16x16x32_bf16 v[54:57], v[166:169], v[174:177], v[54:57]
	v_mfma_f32_16x16x32_bf16 v[26:29], v[158:161], v[194:197], v[26:29]
	v_mfma_f32_16x16x32_bf16 v[38:41], v[166:169], v[194:197], v[38:41]
	v_mfma_f32_16x16x32_bf16 v[10:13], v[158:161], v[212:215], v[10:13]
	v_mfma_f32_16x16x32_bf16 v[22:25], v[166:169], v[212:215], v[22:25]
	v_mfma_f32_16x16x32_bf16 v[2:5], v[158:161], v[220:223], v[2:5]
	v_mfma_f32_16x16x32_bf16 v[6:9], v[166:169], v[220:223], v[6:9]
	v_mfma_f32_16x16x32_bf16 v[42:45], v[162:165], v[190:193], v[42:45]
	v_mfma_f32_16x16x32_bf16 v[54:57], v[170:173], v[190:193], v[54:57]
	v_mfma_f32_16x16x32_bf16 v[26:29], v[162:165], v[198:201], v[26:29]
	v_mfma_f32_16x16x32_bf16 v[38:41], v[170:173], v[198:201], v[38:41]
	v_mfma_f32_16x16x32_bf16 v[10:13], v[162:165], v[216:219], v[10:13]
	v_mfma_f32_16x16x32_bf16 v[22:25], v[170:173], v[216:219], v[22:25]
	v_mfma_f32_16x16x32_bf16 v[2:5], v[162:165], v[224:227], v[2:5]
	v_mfma_f32_16x16x32_bf16 v[6:9], v[170:173], v[224:227], v[6:9]
	s_barrier
	s_add_i32 s60, s60, 2
	s_add_u32 s48, s48, 0x100
	s_addc_u32 s49, s49, 0
	s_add_u32 s58, s58, 0x100
	s_addc_u32 s59, s59, 0
	s_cmp_gt_u32 s60, 13
	s_cbranch_scc0 .LBB0_105
	s_setprio 0
	v_readlane_b32 s8, v243, 63
	v_readlane_b32 s9, v242, 0
	s_and_b64 vcc, exec, s[8:9]
	s_cbranch_vccz .LBB0_108
	s_barrier

; #define PG8_STAGE(bufoff, gbase, voff) do { _Pragma("unroll") for (int _i = 0; _i < 2; ++_i) \
;         __builtin_amdgcn_global_load_lds((const unsigned*)((const char*)(gbase) + (voff)[_i]), (PG8_LAS unsigned*)(lds + (bufoff) + ldsw + _i * 8192), 16, 0, 0); } while (0)
; #define PG8_LDA(dst, b, h) do { _Pragma("unroll") for (int m = 0; m < 4; ++m) _Pragma("unroll") for (int k = 0; k < 2; ++k) dst[m][k] = *(const PG8_LAS bf16x8*)(lds + PG8_SA(b, h) + aoff + m * 2048 + k * 1024); } while (0)
; #define PG8_LDB(dst, b, h) do { _Pragma("unroll") for (int n = 0; n < 2; ++n) _Pragma("unroll") for (int k = 0; k < 2; ++k) dst[n][k] = *(const PG8_LAS bf16x8*)(lds + PG8_SB(b, h) + boff + n * 2048 + k * 1024); } while (0)
; #define PG8_MMA(ai, bj, At, Bt) do { __builtin_amdgcn_s_setprio(1); _Pragma("unroll") for (int m = 0; m < 4; ++m) _Pragma("unroll") for (int n = 0; n < 2; ++n) _Pragma("unroll") for (int k = 0; k < 2; ++k) \
;         acc[ai][bj][m][n] = __builtin_amdgcn_mfma_f32_16x16x32_bf16(Bt[n][k], At[m][k], acc[ai][bj][m][n], 0, 0, 0); __builtin_amdgcn_s_setprio(0); } while (0)
; #define PG8_WAIT_V(n) asm volatile("s_waitcnt vmcnt(" #n ")" ::: "memory")
; template <class Epi, class Sched, bool ALIGN_EPI = false, bool SP2 = false>
; __device__ __forceinline__ void gemm_phase(PG8_LAS unsigned char* lds, const Gemm g, const Sched& S, const Epi& E, const int wid_in) {
;     ...
;         for (int t = 0; t < nt; t += 2) {
;             const bool last = (t == nt - 2);
;             const char* a1 = cA + (size_t)(t + 1) * kstep;
;             const char* a2 = last ? nA : cA + (size_t)(t + 2) * kstep; const char* b2 = last ? nB : cB + (size_t)(t + 2) * kstep;
;             const char* a3 = a2 + kstep; const char* b3 = b2 + kstep;
;             if (last && has_next) S.a_ready(nxt);
;             if constexpr (SP2) {
;             PG8_LDB(B0, 0, 0); PG8_LDB(B1, 0, 1); PG8_SCHED; PG8_LDA(At, 0, 0); PG8_STAGE(PG8_SA(1, 1), a1 + hstep, voffA);
;             PG8_WAIT_V(8); PG8_WAIT_L(0); PG8_BAR; PG8_MMA(0, 0, At, B0); PG8_MMA(0, 1, At, B1); PG8_BAR; PG8_SCHED;
;     ...
; #pragma unroll
;         for (int a = 0; a < 2; ++a)
; #pragma unroll
;             for (int b = 0; b < 2; ++b)
; #pragma unroll
;                 for (int m = 0; m < 4; ++m)
; #pragma unroll
;                     for (int n = 0; n < 2; ++n) acc[a][b][m][n] = (f32x4){0.f, 0.f, 0.f, 0.f};
.Lp4_qunit:
	v_mov_b32_e32 v3, v2
	v_mov_b32_e32 v4, v2
	v_mov_b32_e32 v5, v2
	v_mov_b32_e32 v6, v2
	v_mov_b32_e32 v7, v2
	v_mov_b32_e32 v8, v2
	v_mov_b32_e32 v9, v2
	v_mov_b32_e32 v10, v2
	v_mov_b32_e32 v11, v2
	v_mov_b32_e32 v12, v2
	v_mov_b32_e32 v13, v2
	v_mov_b32_e32 v14, v2
	v_mov_b32_e32 v15, v2
	v_mov_b32_e32 v16, v2
	v_mov_b32_e32 v17, v2
	v_mov_b32_e32 v18, v2
	v_mov_b32_e32 v19, v2
	v_mov_b32_e32 v20, v2
	v_mov_b32_e32 v21, v2
	v_mov_b32_e32 v22, v2
	v_mov_b32_e32 v23, v2
	v_mov_b32_e32 v24, v2
	v_mov_b32_e32 v25, v2
	v_mov_b32_e32 v26, v2
	v_mov_b32_e32 v27, v2
	v_mov_b32_e32 v28, v2
	v_mov_b32_e32 v29, v2
	v_mov_b32_e32 v30, v2
	v_mov_b32_e32 v31, v2
	v_mov_b32_e32 v32, v2
	v_mov_b32_e32 v33, v2
	v_mov_b32_e32 v74, v2
	v_mov_b32_e32 v75, v2
	v_mov_b32_e32 v76, v2
	v_mov_b32_e32 v77, v2
	v_mov_b32_e32 v78, v2
	v_mov_b32_e32 v79, v2
	v_mov_b32_e32 v80, v2
	v_mov_b32_e32 v81, v2
	v_mov_b32_e32 v106, v2
	v_mov_b32_e32 v107, v2
	v_mov_b32_e32 v108, v2
	v_mov_b32_e32 v109, v2
	v_mov_b32_e32 v110, v2
	v_mov_b32_e32 v111, v2
	v_mov_b32_e32 v112, v2
	v_mov_b32_e32 v113, v2
	v_mov_b32_e32 v114, v2
	v_mov_b32_e32 v115, v2
	v_mov_b32_e32 v116, v2
	v_mov_b32_e32 v117, v2
	v_mov_b32_e32 v118, v2
	v_mov_b32_e32 v119, v2
	v_mov_b32_e32 v120, v2
	v_mov_b32_e32 v121, v2
	v_mov_b32_e32 v122, v2
	v_mov_b32_e32 v123, v2
	v_mov_b32_e32 v124, v2
	v_mov_b32_e32 v125, v2
	v_mov_b32_e32 v126, v2
	v_mov_b32_e32 v127, v2
	v_mov_b32_e32 v128, v2
	v_mov_b32_e32 v129, v2
	v_mov_b32_e32 v34, v2
	v_mov_b32_e32 v35, v2
	v_mov_b32_e32 v36, v2
	v_mov_b32_e32 v37, v2
	v_mov_b32_e32 v38, v2
	v_mov_b32_e32 v39, v2
	v_mov_b32_e32 v40, v2
	v_mov_b32_e32 v41, v2
	v_mov_b32_e32 v42, v2
	v_mov_b32_e32 v43, v2
	v_mov_b32_e32 v44, v2
	v_mov_b32_e32 v45, v2
	v_mov_b32_e32 v46, v2
	v_mov_b32_e32 v47, v2
	v_mov_b32_e32 v48, v2
	v_mov_b32_e32 v49, v2
	v_mov_b32_e32 v50, v2
	v_mov_b32_e32 v51, v2
	v_mov_b32_e32 v52, v2
	v_mov_b32_e32 v53, v2
	v_mov_b32_e32 v54, v2
	v_mov_b32_e32 v55, v2
	v_mov_b32_e32 v56, v2
	v_mov_b32_e32 v57, v2
	v_mov_b32_e32 v58, v2
	v_mov_b32_e32 v59, v2
	v_mov_b32_e32 v60, v2
	v_mov_b32_e32 v61, v2
	v_mov_b32_e32 v62, v2
	v_mov_b32_e32 v63, v2
	v_mov_b32_e32 v64, v2
	v_mov_b32_e32 v65, v2
	v_mov_b32_e32 v130, v2
	v_mov_b32_e32 v131, v2
	v_mov_b32_e32 v132, v2
	v_mov_b32_e32 v133, v2
	v_mov_b32_e32 v134, v2
	v_mov_b32_e32 v135, v2
	v_mov_b32_e32 v136, v2
	v_mov_b32_e32 v137, v2
	v_mov_b32_e32 v138, v2
	v_mov_b32_e32 v139, v2
	v_mov_b32_e32 v140, v2
	v_mov_b32_e32 v141, v2
	v_mov_b32_e32 v142, v2
	v_mov_b32_e32 v143, v2
	v_mov_b32_e32 v144, v2
	v_mov_b32_e32 v145, v2
	v_mov_b32_e32 v146, v2
	v_mov_b32_e32 v147, v2
	v_mov_b32_e32 v148, v2
	v_mov_b32_e32 v149, v2
	v_mov_b32_e32 v150, v2
	v_mov_b32_e32 v151, v2
	v_mov_b32_e32 v152, v2
	v_mov_b32_e32 v153, v2
	v_mov_b32_e32 v154, v2
	v_mov_b32_e32 v155, v2
	v_mov_b32_e32 v156, v2
	v_mov_b32_e32 v157, v2
	v_mov_b32_e32 v158, v2
	v_mov_b32_e32 v159, v2
	v_mov_b32_e32 v160, v2
	v_mov_b32_e32 v161, v2
	v_readlane_b32 s100, v243, 63
	v_readlane_b32 s101, v242, 0
	s_cmp_lg_u64 s[100:101], 0
	s_cbranch_scc1 .Lprio_done_267
	s_setprio 1
.Lprio_done_267:
.LBB0_267:
	s_add_u32 s2, s50, s56
	s_addc_u32 s8, s51, s57
	s_add_u32 s25, s2, 0x100
	s_addc_u32 s26, s8, 0
	s_and_b64 s[22:23], s[54:55], exec
	s_cselect_b32 s59, s39, s26
	s_cselect_b32 s58, s62, s25
	s_add_u32 s22, s40, s56
	s_addc_u32 s23, s41, s57
	s_add_u32 s25, s22, 0x100
	s_addc_u32 s26, s23, 0
	s_add_i32 s31, 0, 0x10000
	s_and_b64 s[22:23], s[54:55], exec
	s_cselect_b32 s61, s43, s26
	s_cselect_b32 s60, s16, s25
	s_add_i32 s55, 0, 0x14000
	s_add_u32 s78, s2, 0x10080
	s_addc_u32 s79, s8, 0
	s_add_i32 s23, s31, s3
	s_add_i32 m0, s9, 0xc000
	s_add_i32 s36, s9, 0xe000
	s_add_i32 s27, s23, 0x2000
	v_add_u32_e32 v0, s31, v196
	s_add_u32 vcc_lo, s60, 0x10000
	ds_read_b128 v[66:69], v0
	ds_read_b128 v[70:73], v0 offset:1024
	ds_read_b128 v[82:85], v0 offset:2048
	ds_read_b128 v[86:89], v0 offset:3072
	v_add_u32_e32 v0, s55, v196
	s_addc_u32 vcc_hi, s61, 0
	s_add_i32 s25, s55, s3
	ds_read_b128 v[90:93], v0
	ds_read_b128 v[94:97], v0 offset:1024
	ds_read_b128 v[98:101], v0 offset:2048
	ds_read_b128 v[102:105], v0 offset:3072
	s_add_i32 s26, s25, 0x2000
	s_add_i32 s2, 0, 0x18000
	s_add_i32 s67, 0, 0x1c000
	s_add_u32 s56, s58, 0x10000
	s_addc_u32 s57, s59, 0
	s_add_i32 s66, s2, s3
	s_add_i32 s22, s66, 0x2000
	s_add_u32 s54, s60, 0x10080
	s_addc_u32 s55, s61, 0
	s_add_i32 s31, s67, s3
	s_add_i32 s8, s31, 0x2000
	v_lshl_add_u64 v[194:195], s[78:79], 0, v[172:173]
	ds_read_b128 v[162:165], v197
	ds_read_b128 v[166:169], v197 offset:1024
	ds_read_b128 v[174:177], v197 offset:2048
	ds_read_b128 v[190:193], v197 offset:3072
	ds_read_b128 v[198:201], v197 offset:4096
	ds_read_b128 v[212:215], v197 offset:5120
	ds_read_b128 v[216:219], v197 offset:6144
	ds_read_b128 v[220:223], v197 offset:7168
	global_load_lds_dwordx4 v[194:195], off
	v_lshl_add_u64 v[194:195], s[78:79], 0, v[170:171]
	s_mov_b32 m0, s36
	s_nop 0
	global_load_lds_dwordx4 v[194:195], off
	s_waitcnt vmcnt(8)
	s_waitcnt lgkmcnt(0)
	s_barrier
; #define PG8_STAGE(bufoff, gbase, voff) do { _Pragma("unroll") for (int _i = 0; _i < 2; ++_i) \
;         __builtin_amdgcn_global_load_lds((const unsigned*)((const char*)(gbase) + (voff)[_i]), (PG8_LAS unsigned*)(lds + (bufoff) + ldsw + _i * 8192), 16, 0, 0); } while (0)
; #define PG8_LDA(dst, b, h) do { _Pragma("unroll") for (int m = 0; m < 4; ++m) _Pragma("unroll") for (int k = 0; k < 2; ++k) dst[m][k] = *(const PG8_LAS bf16x8*)(lds + PG8_SA(b, h) + aoff + m * 2048 + k * 1024); } while (0)
; #define PG8_LDB(dst, b, h) do { _Pragma("unroll") for (int n = 0; n < 2; ++n) _Pragma("unroll") for (int k = 0; k < 2; ++k) dst[n][k] = *(const PG8_LAS bf16x8*)(lds + PG8_SB(b, h) + boff + n * 2048 + k * 1024); } while (0)
; #define PG8_MMA(ai, bj, At, Bt) do { __builtin_amdgcn_s_setprio(1); _Pragma("unroll") for (int m = 0; m < 4; ++m) _Pragma("unroll") for (int n = 0; n < 2; ++n) _Pragma("unroll") for (int k = 0; k < 2; ++k) \
;         acc[ai][bj][m][n] = __builtin_amdgcn_mfma_f32_16x16x32_bf16(Bt[n][k], At[m][k], acc[ai][bj][m][n], 0, 0, 0); __builtin_amdgcn_s_setprio(0); } while (0)
; #define PG8_WAIT_V(n) asm volatile("s_waitcnt vmcnt(" #n ")" ::: "memory")
; #define PG8_WAIT_L(n) asm volatile("s_waitcnt lgkmcnt(" #n ")" ::: "memory")
; #define PG8_BAR __builtin_amdgcn_s_barrier()
; #define PG8_SCHED __builtin_amdgcn_sched_barrier(0)
; template <class Epi, class Sched, bool ALIGN_EPI = false, bool SP2 = false>
; __device__ __forceinline__ void gemm_phase(PG8_LAS unsigned char* lds, const Gemm g, const Sched& S, const Epi& E, const int wid_in) {
;     ...
;             PG8_LDB(B0, 0, 0); PG8_LDB(B1, 0, 1); PG8_SCHED; PG8_LDA(At, 0, 0); PG8_STAGE(PG8_SA(1, 1), a1 + hstep, voffA);
;             PG8_WAIT_V(8); PG8_WAIT_L(0); PG8_BAR; PG8_MMA(0, 0, At, B0); PG8_MMA(0, 1, At, B1); PG8_BAR; PG8_SCHED;
;             PG8_LDA(At, 0, 1); PG8_STAGE(PG8_SB(0, 0), b2, voffB); PG8_STAGE(PG8_SB(0, 1), b2 + hstep, voffB); PG8_STAGE(PG8_SA(0, 0), a2, voffA);
;             PG8_WAIT_V(8); PG8_WAIT_L(0); PG8_BAR; PG8_MMA(1, 0, At, B0); PG8_MMA(1, 1, At, B1); PG8_BAR; PG8_SCHED;
	s_waitcnt lgkmcnt(0)
	v_mfma_f32_16x16x32_bf16 v[158:161], v[66:69], v[162:165], v[158:161]
	v_mfma_f32_16x16x32_bf16 v[154:157], v[82:85], v[162:165], v[154:157]
	v_mfma_f32_16x16x32_bf16 v[150:153], v[66:69], v[174:177], v[150:153]
	v_mfma_f32_16x16x32_bf16 v[146:149], v[82:85], v[174:177], v[146:149]
	v_mfma_f32_16x16x32_bf16 v[142:145], v[66:69], v[198:201], v[142:145]
	v_mfma_f32_16x16x32_bf16 v[138:141], v[82:85], v[198:201], v[138:141]
	v_mfma_f32_16x16x32_bf16 v[134:137], v[66:69], v[216:219], v[134:137]
	v_mfma_f32_16x16x32_bf16 v[130:133], v[82:85], v[216:219], v[130:133]
	v_mfma_f32_16x16x32_bf16 v[158:161], v[70:73], v[166:169], v[158:161]
	v_mfma_f32_16x16x32_bf16 v[154:157], v[86:89], v[166:169], v[154:157]
	v_mfma_f32_16x16x32_bf16 v[150:153], v[70:73], v[190:193], v[150:153]
	v_mfma_f32_16x16x32_bf16 v[146:149], v[86:89], v[190:193], v[146:149]
	v_mfma_f32_16x16x32_bf16 v[142:145], v[70:73], v[212:215], v[142:145]
	v_mfma_f32_16x16x32_bf16 v[138:141], v[86:89], v[212:215], v[138:141]
	v_mfma_f32_16x16x32_bf16 v[134:137], v[70:73], v[220:223], v[134:137]
	v_mfma_f32_16x16x32_bf16 v[130:133], v[86:89], v[220:223], v[130:133]
	v_mfma_f32_16x16x32_bf16 v[62:65], v[90:93], v[162:165], v[62:65]
	v_mfma_f32_16x16x32_bf16 v[58:61], v[98:101], v[162:165], v[58:61]
	v_mfma_f32_16x16x32_bf16 v[54:57], v[90:93], v[174:177], v[54:57]
	v_mfma_f32_16x16x32_bf16 v[50:53], v[98:101], v[174:177], v[50:53]
	v_mfma_f32_16x16x32_bf16 v[46:49], v[90:93], v[198:201], v[46:49]
	v_mfma_f32_16x16x32_bf16 v[42:45], v[98:101], v[198:201], v[42:45]
	v_mfma_f32_16x16x32_bf16 v[38:41], v[90:93], v[216:219], v[38:41]
	v_mfma_f32_16x16x32_bf16 v[34:37], v[98:101], v[216:219], v[34:37]
	v_mfma_f32_16x16x32_bf16 v[62:65], v[94:97], v[166:169], v[62:65]
	v_mfma_f32_16x16x32_bf16 v[58:61], v[102:105], v[166:169], v[58:61]
	v_mfma_f32_16x16x32_bf16 v[54:57], v[94:97], v[190:193], v[54:57]
	v_mfma_f32_16x16x32_bf16 v[50:53], v[102:105], v[190:193], v[50:53]
	v_mfma_f32_16x16x32_bf16 v[46:49], v[94:97], v[212:215], v[46:49]
	v_mfma_f32_16x16x32_bf16 v[42:45], v[102:105], v[212:215], v[42:45]
	v_mfma_f32_16x16x32_bf16 v[38:41], v[94:97], v[220:223], v[38:41]
	v_mfma_f32_16x16x32_bf16 v[34:37], v[102:105], v[220:223], v[34:37]
	s_barrier
	s_mov_b32 m0, s23
	v_lshl_add_u64 v[194:195], s[60:61], 0, v[172:173]
	ds_read_b128 v[162:165], v197 offset:16384
	ds_read_b128 v[166:169], v197 offset:17408
	ds_read_b128 v[174:177], v197 offset:18432
	ds_read_b128 v[190:193], v197 offset:19456
	ds_read_b128 v[198:201], v197 offset:20480
	ds_read_b128 v[212:215], v197 offset:21504
	ds_read_b128 v[216:219], v197 offset:22528
	ds_read_b128 v[220:223], v197 offset:23552
	global_load_lds_dwordx4 v[194:195], off
	v_lshl_add_u64 v[224:225], s[60:61], 0, v[170:171]
	s_mov_b32 m0, s27
	v_lshl_add_u64 v[226:227], vcc, 0, v[172:173]
	global_load_lds_dwordx4 v[224:225], off
	s_mov_b32 m0, s25
	v_lshl_add_u64 v[228:229], s[58:59], 0, v[170:171]
	global_load_lds_dwordx4 v[226:227], off
	v_lshl_add_u64 v[226:227], vcc, 0, v[170:171]
	s_mov_b32 m0, s26
	s_nop 0
	global_load_lds_dwordx4 v[226:227], off
	v_lshl_add_u64 v[226:227], s[58:59], 0, v[172:173]
	s_mov_b32 m0, s9
	s_nop 0
	global_load_lds_dwordx4 v[226:227], off
	s_mov_b32 m0, s37
	s_nop 0
	global_load_lds_dwordx4 v[228:229], off
	s_waitcnt vmcnt(8)
	s_waitcnt lgkmcnt(0)
	s_barrier
	s_waitcnt lgkmcnt(0)
	v_mfma_f32_16x16x32_bf16 v[126:129], v[66:69], v[162:165], v[126:129]
	v_mfma_f32_16x16x32_bf16 v[122:125], v[82:85], v[162:165], v[122:125]
	v_mfma_f32_16x16x32_bf16 v[118:121], v[66:69], v[174:177], v[118:121]
	v_mfma_f32_16x16x32_bf16 v[114:117], v[82:85], v[174:177], v[114:117]
	v_mfma_f32_16x16x32_bf16 v[110:113], v[66:69], v[198:201], v[110:113]
	v_mfma_f32_16x16x32_bf16 v[106:109], v[82:85], v[198:201], v[106:109]
	v_mfma_f32_16x16x32_bf16 v[66:69], v[66:69], v[216:219], v[78:81]
	v_mfma_f32_16x16x32_bf16 v[126:129], v[70:73], v[166:169], v[126:129]
	v_mfma_f32_16x16x32_bf16 v[122:125], v[86:89], v[166:169], v[122:125]
	v_mfma_f32_16x16x32_bf16 v[118:121], v[70:73], v[190:193], v[118:121]
	v_mfma_f32_16x16x32_bf16 v[114:117], v[86:89], v[190:193], v[114:117]
	v_mfma_f32_16x16x32_bf16 v[110:113], v[70:73], v[212:215], v[110:113]
	v_mfma_f32_16x16x32_bf16 v[106:109], v[86:89], v[212:215], v[106:109]
	v_mfma_f32_16x16x32_bf16 v[66:69], v[70:73], v[220:223], v[66:69]
	v_mfma_f32_16x16x32_bf16 v[70:73], v[82:85], v[216:219], v[74:77]
	v_mfma_f32_16x16x32_bf16 v[70:73], v[86:89], v[220:223], v[70:73]
	v_mfma_f32_16x16x32_bf16 v[30:33], v[90:93], v[162:165], v[30:33]
	v_mfma_f32_16x16x32_bf16 v[26:29], v[98:101], v[162:165], v[26:29]
	v_mfma_f32_16x16x32_bf16 v[22:25], v[90:93], v[174:177], v[22:25]
	v_mfma_f32_16x16x32_bf16 v[18:21], v[98:101], v[174:177], v[18:21]
	v_mfma_f32_16x16x32_bf16 v[14:17], v[90:93], v[198:201], v[14:17]
	v_mfma_f32_16x16x32_bf16 v[10:13], v[98:101], v[198:201], v[10:13]
	v_mfma_f32_16x16x32_bf16 v[6:9], v[90:93], v[216:219], v[6:9]
	v_mfma_f32_16x16x32_bf16 v[2:5], v[98:101], v[216:219], v[2:5]
	v_mfma_f32_16x16x32_bf16 v[30:33], v[94:97], v[166:169], v[30:33]
	v_mfma_f32_16x16x32_bf16 v[26:29], v[102:105], v[166:169], v[26:29]
	v_mfma_f32_16x16x32_bf16 v[22:25], v[94:97], v[190:193], v[22:25]
	v_mfma_f32_16x16x32_bf16 v[18:21], v[102:105], v[190:193], v[18:21]
	v_mfma_f32_16x16x32_bf16 v[14:17], v[94:97], v[212:215], v[14:17]
	v_mfma_f32_16x16x32_bf16 v[10:13], v[102:105], v[212:215], v[10:13]
	v_mfma_f32_16x16x32_bf16 v[6:9], v[94:97], v[220:223], v[6:9]
	v_mfma_f32_16x16x32_bf16 v[2:5], v[102:105], v[220:223], v[2:5]
	s_barrier
; #define PG8_STAGE(bufoff, gbase, voff) do { _Pragma("unroll") for (int _i = 0; _i < 2; ++_i) \
;         __builtin_amdgcn_global_load_lds((const unsigned*)((const char*)(gbase) + (voff)[_i]), (PG8_LAS unsigned*)(lds + (bufoff) + ldsw + _i * 8192), 16, 0, 0); } while (0)
; #define PG8_LDA(dst, b, h) do { _Pragma("unroll") for (int m = 0; m < 4; ++m) _Pragma("unroll") for (int k = 0; k < 2; ++k) dst[m][k] = *(const PG8_LAS bf16x8*)(lds + PG8_SA(b, h) + aoff + m * 2048 + k * 1024); } while (0)
; #define PG8_LDB(dst, b, h) do { _Pragma("unroll") for (int n = 0; n < 2; ++n) _Pragma("unroll") for (int k = 0; k < 2; ++k) dst[n][k] = *(const PG8_LAS bf16x8*)(lds + PG8_SB(b, h) + boff + n * 2048 + k * 1024); } while (0)
; #define PG8_MMA(ai, bj, At, Bt) do { __builtin_amdgcn_s_setprio(1); _Pragma("unroll") for (int m = 0; m < 4; ++m) _Pragma("unroll") for (int n = 0; n < 2; ++n) _Pragma("unroll") for (int k = 0; k < 2; ++k) \
;         acc[ai][bj][m][n] = __builtin_amdgcn_mfma_f32_16x16x32_bf16(Bt[n][k], At[m][k], acc[ai][bj][m][n], 0, 0, 0); __builtin_amdgcn_s_setprio(0); } while (0)
; #define PG8_WAIT_V(n) asm volatile("s_waitcnt vmcnt(" #n ")" ::: "memory")
; #define PG8_WAIT_L(n) asm volatile("s_waitcnt lgkmcnt(" #n ")" ::: "memory")
; #define PG8_BAR __builtin_amdgcn_s_barrier()
; #define PG8_SCHED __builtin_amdgcn_sched_barrier(0)
; template <class Epi, class Sched, bool ALIGN_EPI = false, bool SP2 = false>
; __device__ __forceinline__ void gemm_phase(PG8_LAS unsigned char* lds, const Gemm g, const Sched& S, const Epi& E, const int wid_in) {
;     ...
;             PG8_LDB(B0, 1, 0); PG8_LDB(B1, 1, 1); PG8_SCHED; PG8_LDA(At, 1, 0); PG8_STAGE(PG8_SA(0, 1), a2 + hstep, voffA);
;             PG8_WAIT_V(8); PG8_WAIT_L(0); PG8_BAR; PG8_MMA(0, 0, At, B0); PG8_MMA(0, 1, At, B1); PG8_BAR; PG8_SCHED;
;             PG8_LDA(At, 1, 1); PG8_STAGE(PG8_SB(1, 0), b3, voffB); PG8_STAGE(PG8_SB(1, 1), b3 + hstep, voffB); PG8_STAGE(PG8_SA(1, 0), a3, voffA);
;             PG8_WAIT_V(8); PG8_WAIT_L(0); PG8_BAR; PG8_MMA(1, 0, At, B0); PG8_MMA(1, 1, At, B1); PG8_BAR; PG8_SCHED;
;     ...
;         }
;         if constexpr (ALIGN_EPI) { if (wr == 0) PG8_BAR; }
	v_add_u32_e32 v0, s2, v196
	ds_read_b128 v[74:77], v0
	ds_read_b128 v[78:81], v0 offset:1024
	ds_read_b128 v[82:85], v0 offset:2048
	ds_read_b128 v[86:89], v0 offset:3072
	v_add_u32_e32 v0, s67, v196
	ds_read_b128 v[90:93], v0
	ds_read_b128 v[94:97], v0 offset:1024
	ds_read_b128 v[98:101], v0 offset:2048
	ds_read_b128 v[102:105], v0 offset:3072
	s_mov_b32 m0, s96
	v_lshl_add_u64 v[230:231], s[56:57], 0, v[172:173]
	ds_read_b128 v[162:165], v197 offset:32768
	ds_read_b128 v[166:169], v197 offset:33792
	ds_read_b128 v[174:177], v197 offset:34816
	ds_read_b128 v[190:193], v197 offset:35840
	ds_read_b128 v[198:201], v197 offset:36864
	ds_read_b128 v[212:215], v197 offset:37888
	ds_read_b128 v[216:219], v197 offset:38912
	ds_read_b128 v[220:223], v197 offset:39936
	global_load_lds_dwordx4 v[230:231], off
	v_lshl_add_u64 v[230:231], s[56:57], 0, v[170:171]
	s_mov_b32 m0, s97
	s_nop 0
	global_load_lds_dwordx4 v[230:231], off
	s_waitcnt vmcnt(8)
	s_waitcnt lgkmcnt(0)
	s_barrier
	s_waitcnt lgkmcnt(0)
	v_mfma_f32_16x16x32_bf16 v[158:161], v[74:77], v[162:165], v[158:161]
	v_mfma_f32_16x16x32_bf16 v[154:157], v[82:85], v[162:165], v[154:157]
	v_mfma_f32_16x16x32_bf16 v[150:153], v[74:77], v[174:177], v[150:153]
	v_mfma_f32_16x16x32_bf16 v[146:149], v[82:85], v[174:177], v[146:149]
	v_mfma_f32_16x16x32_bf16 v[142:145], v[74:77], v[198:201], v[142:145]
	v_mfma_f32_16x16x32_bf16 v[138:141], v[82:85], v[198:201], v[138:141]
	v_mfma_f32_16x16x32_bf16 v[134:137], v[74:77], v[216:219], v[134:137]
	v_mfma_f32_16x16x32_bf16 v[130:133], v[82:85], v[216:219], v[130:133]
	v_mfma_f32_16x16x32_bf16 v[158:161], v[78:81], v[166:169], v[158:161]
	v_mfma_f32_16x16x32_bf16 v[154:157], v[86:89], v[166:169], v[154:157]
	v_mfma_f32_16x16x32_bf16 v[150:153], v[78:81], v[190:193], v[150:153]
	v_mfma_f32_16x16x32_bf16 v[146:149], v[86:89], v[190:193], v[146:149]
	v_mfma_f32_16x16x32_bf16 v[142:145], v[78:81], v[212:215], v[142:145]
	v_mfma_f32_16x16x32_bf16 v[138:141], v[86:89], v[212:215], v[138:141]
	v_mfma_f32_16x16x32_bf16 v[134:137], v[78:81], v[220:223], v[134:137]
	v_mfma_f32_16x16x32_bf16 v[130:133], v[86:89], v[220:223], v[130:133]
	v_mfma_f32_16x16x32_bf16 v[62:65], v[90:93], v[162:165], v[62:65]
	v_mfma_f32_16x16x32_bf16 v[58:61], v[98:101], v[162:165], v[58:61]
	v_mfma_f32_16x16x32_bf16 v[54:57], v[90:93], v[174:177], v[54:57]
	v_mfma_f32_16x16x32_bf16 v[50:53], v[98:101], v[174:177], v[50:53]
	v_mfma_f32_16x16x32_bf16 v[46:49], v[90:93], v[198:201], v[46:49]
	v_mfma_f32_16x16x32_bf16 v[42:45], v[98:101], v[198:201], v[42:45]
	v_mfma_f32_16x16x32_bf16 v[38:41], v[90:93], v[216:219], v[38:41]
	v_mfma_f32_16x16x32_bf16 v[34:37], v[98:101], v[216:219], v[34:37]
	v_mfma_f32_16x16x32_bf16 v[62:65], v[94:97], v[166:169], v[62:65]
	v_mfma_f32_16x16x32_bf16 v[58:61], v[102:105], v[166:169], v[58:61]
	v_mfma_f32_16x16x32_bf16 v[54:57], v[94:97], v[190:193], v[54:57]
	v_mfma_f32_16x16x32_bf16 v[50:53], v[102:105], v[190:193], v[50:53]
	v_mfma_f32_16x16x32_bf16 v[46:49], v[94:97], v[212:215], v[46:49]
	v_mfma_f32_16x16x32_bf16 v[42:45], v[102:105], v[212:215], v[42:45]
	v_mfma_f32_16x16x32_bf16 v[38:41], v[94:97], v[220:223], v[38:41]
	v_mfma_f32_16x16x32_bf16 v[34:37], v[102:105], v[220:223], v[34:37]
	s_barrier
	s_mov_b32 m0, s66
	v_lshl_add_u64 v[194:195], v[194:195], 0, s[64:65]
	ds_read_b128 v[162:165], v197 offset:49152
	ds_read_b128 v[166:169], v197 offset:50176
	ds_read_b128 v[174:177], v197 offset:51200
	ds_read_b128 v[190:193], v197 offset:52224
	ds_read_b128 v[198:201], v197 offset:53248
	ds_read_b128 v[212:215], v197 offset:54272
	ds_read_b128 v[216:219], v197 offset:55296
	ds_read_b128 v[220:223], v197 offset:56320
	global_load_lds_dwordx4 v[194:195], off
	v_lshl_add_u64 v[194:195], v[224:225], 0, s[64:65]
	s_mov_b32 m0, s22
	s_nop 0
	global_load_lds_dwordx4 v[194:195], off
	v_lshl_add_u64 v[194:195], s[54:55], 0, v[172:173]
	s_mov_b32 m0, s31
	s_nop 0
	global_load_lds_dwordx4 v[194:195], off
	v_lshl_add_u64 v[194:195], s[54:55], 0, v[170:171]
	s_mov_b32 m0, s8
	s_nop 0
	global_load_lds_dwordx4 v[194:195], off
	v_lshl_add_u64 v[194:195], v[226:227], 0, s[64:65]
	s_mov_b32 m0, s13
	s_nop 0
	global_load_lds_dwordx4 v[194:195], off
	v_lshl_add_u64 v[194:195], v[228:229], 0, s[64:65]
	s_mov_b32 m0, s12
	s_nop 0
	global_load_lds_dwordx4 v[194:195], off
	s_waitcnt vmcnt(8)
	s_waitcnt lgkmcnt(0)
	s_barrier
	s_waitcnt lgkmcnt(0)
	v_mfma_f32_16x16x32_bf16 v[126:129], v[74:77], v[162:165], v[126:129]
	v_mfma_f32_16x16x32_bf16 v[118:121], v[74:77], v[174:177], v[118:121]
	v_mfma_f32_16x16x32_bf16 v[110:113], v[74:77], v[198:201], v[110:113]
	v_mfma_f32_16x16x32_bf16 v[66:69], v[74:77], v[216:219], v[66:69]
	v_mfma_f32_16x16x32_bf16 v[126:129], v[78:81], v[166:169], v[126:129]
	v_mfma_f32_16x16x32_bf16 v[122:125], v[82:85], v[162:165], v[122:125]
	v_mfma_f32_16x16x32_bf16 v[118:121], v[78:81], v[190:193], v[118:121]
	v_mfma_f32_16x16x32_bf16 v[114:117], v[82:85], v[174:177], v[114:117]
	v_mfma_f32_16x16x32_bf16 v[110:113], v[78:81], v[212:215], v[110:113]
	v_mfma_f32_16x16x32_bf16 v[106:109], v[82:85], v[198:201], v[106:109]
	v_mfma_f32_16x16x32_bf16 v[78:81], v[78:81], v[220:223], v[66:69]
	v_mfma_f32_16x16x32_bf16 v[66:69], v[82:85], v[216:219], v[70:73]
	v_mfma_f32_16x16x32_bf16 v[122:125], v[86:89], v[166:169], v[122:125]
	v_mfma_f32_16x16x32_bf16 v[114:117], v[86:89], v[190:193], v[114:117]
	v_mfma_f32_16x16x32_bf16 v[106:109], v[86:89], v[212:215], v[106:109]
	v_mfma_f32_16x16x32_bf16 v[74:77], v[86:89], v[220:223], v[66:69]
	v_mfma_f32_16x16x32_bf16 v[30:33], v[90:93], v[162:165], v[30:33]
	v_mfma_f32_16x16x32_bf16 v[26:29], v[98:101], v[162:165], v[26:29]
	v_mfma_f32_16x16x32_bf16 v[22:25], v[90:93], v[174:177], v[22:25]
	v_mfma_f32_16x16x32_bf16 v[18:21], v[98:101], v[174:177], v[18:21]
	v_mfma_f32_16x16x32_bf16 v[14:17], v[90:93], v[198:201], v[14:17]
	v_mfma_f32_16x16x32_bf16 v[10:13], v[98:101], v[198:201], v[10:13]
	v_mfma_f32_16x16x32_bf16 v[6:9], v[90:93], v[216:219], v[6:9]
	v_mfma_f32_16x16x32_bf16 v[2:5], v[98:101], v[216:219], v[2:5]
	v_mfma_f32_16x16x32_bf16 v[30:33], v[94:97], v[166:169], v[30:33]
	v_mfma_f32_16x16x32_bf16 v[26:29], v[102:105], v[166:169], v[26:29]
	v_mfma_f32_16x16x32_bf16 v[22:25], v[94:97], v[190:193], v[22:25]
	v_mfma_f32_16x16x32_bf16 v[18:21], v[102:105], v[190:193], v[18:21]
	v_mfma_f32_16x16x32_bf16 v[14:17], v[94:97], v[212:215], v[14:17]
	v_mfma_f32_16x16x32_bf16 v[10:13], v[102:105], v[212:215], v[10:13]
	v_mfma_f32_16x16x32_bf16 v[6:9], v[94:97], v[220:223], v[6:9]
	v_mfma_f32_16x16x32_bf16 v[2:5], v[102:105], v[220:223], v[2:5]
	s_barrier
	s_andn2_b64 vcc, exec, s[52:53]
	s_mov_b64 s[54:55], -1
	s_mov_b64 s[52:53], 0
	s_mov_b64 s[56:57], 0x100
	s_cbranch_vccz .LBB0_267
	s_setprio 0
	v_readlane_b32 s22, v243, 63
	v_readlane_b32 s23, v242, 0
	s_and_b64 vcc, exec, s[22:23]
	s_cbranch_vccz .LBB0_270
	s_barrier

; #define PG8_STAGE(bufoff, gbase, voff) do { _Pragma("unroll") for (int _i = 0; _i < 2; ++_i) \
;         __builtin_amdgcn_global_load_lds((const unsigned*)((const char*)(gbase) + (voff)[_i]), (PG8_LAS unsigned*)(lds + (bufoff) + ldsw + _i * 8192), 16, 0, 0); } while (0)
; #define PG8_LDA(dst, b, h) do { _Pragma("unroll") for (int m = 0; m < 4; ++m) _Pragma("unroll") for (int k = 0; k < 2; ++k) dst[m][k] = *(const PG8_LAS bf16x8*)(lds + PG8_SA(b, h) + aoff + m * 2048 + k * 1024); } while (0)
; #define PG8_LDB(dst, b, h) do { _Pragma("unroll") for (int n = 0; n < 2; ++n) _Pragma("unroll") for (int k = 0; k < 2; ++k) dst[n][k] = *(const PG8_LAS bf16x8*)(lds + PG8_SB(b, h) + boff + n * 2048 + k * 1024); } while (0)
; #define PG8_MMA(ai, bj, At, Bt) do { __builtin_amdgcn_s_setprio(1); _Pragma("unroll") for (int m = 0; m < 4; ++m) _Pragma("unroll") for (int n = 0; n < 2; ++n) _Pragma("unroll") for (int k = 0; k < 2; ++k) \
;         acc[ai][bj][m][n] = __builtin_amdgcn_mfma_f32_16x16x32_bf16(Bt[n][k], At[m][k], acc[ai][bj][m][n], 0, 0, 0); __builtin_amdgcn_s_setprio(0); } while (0)
; template <class Epi, class Sched, bool ALIGN_EPI = false, bool SP2 = false>
; __device__ __forceinline__ void gemm_phase(PG8_LAS unsigned char* lds, const Gemm g, const Sched& S, const Epi& E, const int wid_in) {
;     ...
;         const bool has_next = S.next(ui + 1, nxt);
;         const char* nA = has_next ? (const char*)g.A + (size_t)nxt.pm * tstep : cA; const char* nB = has_next ? (const char*)g.Bt + (size_t)nxt.pn * tstep : cB;
; #pragma unroll 1
;         for (int t = 0; t < nt; t += 2) {
;             const bool last = (t == nt - 2);
;             const char* a1 = cA + (size_t)(t + 1) * kstep;
;             const char* a2 = last ? nA : cA + (size_t)(t + 2) * kstep; const char* b2 = last ? nB : cB + (size_t)(t + 2) * kstep;
;             const char* a3 = a2 + kstep; const char* b3 = b2 + kstep;
;             if (last && has_next) S.a_ready(nxt);
;             if constexpr (SP2) {
;             PG8_LDB(B0, 0, 0); PG8_LDB(B1, 0, 1); PG8_SCHED; PG8_LDA(At, 0, 0); PG8_STAGE(PG8_SA(1, 1), a1 + hstep, voffA);
;             PG8_WAIT_V(8); PG8_WAIT_L(0); PG8_BAR; PG8_MMA(0, 0, At, B0); PG8_MMA(0, 1, At, B1); PG8_BAR; PG8_SCHED;
;             PG8_LDA(At, 0, 1); PG8_STAGE(PG8_SB(0, 0), b2, voffB); PG8_STAGE(PG8_SB(0, 1), b2 + hstep, voffB); PG8_STAGE(PG8_SA(0, 0), a2, voffA);
.LBB0_536:
	s_ashr_i32 s43, s42, 31
	s_lshl_b64 s[22:23], s[42:43], 19
	v_readlane_b32 s2, v240, 12
	s_add_u32 s44, s2, s22
	v_readlane_b32 s2, v240, 13
	s_addc_u32 s45, s2, s23
	s_and_b64 s[22:23], s[40:41], exec
	s_cselect_b32 s43, s45, s49
	s_cselect_b32 s57, s44, s48
	s_ashr_i32 s39, s38, 31
	s_lshl_b64 s[22:23], s[38:39], 19
	v_readlane_b32 s2, v243, 22
	s_add_u32 s46, s2, s22
	v_readlane_b32 s2, v243, 23
	s_addc_u32 s47, s2, s23
	s_and_b64 s[22:23], s[40:41], exec
	s_cselect_b32 s16, s47, s51
	s_cselect_b32 s39, s46, s50
	s_add_u32 s48, s48, 0x40080
	s_addc_u32 s49, s49, 0
	s_add_u32 s58, s50, 0x100
	s_addc_u32 s59, s51, 0
	s_mov_b32 s60, -2
	v_readlane_b32 s100, v243, 63
	v_readlane_b32 s101, v242, 0
	s_cmp_lg_u64 s[100:101], 0
	s_cbranch_scc1 .Lprio_done_537
	s_setprio 1
.Lprio_done_537:
	s_add_u32 s2, s48, 0xfffc0080
	s_addc_u32 s8, s49, -1
	s_add_i32 s9, 0, 0x10000
	s_cmp_eq_u32 s60, 12
	s_cselect_b32 s53, s43, s8
	s_cselect_b32 s52, s57, s2
	v_add_u32_e32 v140, s9, v142
	s_cselect_b32 s51, s16, s59
	s_cselect_b32 s50, s39, s58
	s_add_i32 s2, 0, 0x14000
	ds_read_b128 v[144:147], v140
	ds_read_b128 v[148:151], v140 offset:1024
	ds_read_b128 v[152:155], v140 offset:2048
	ds_read_b128 v[156:159], v140 offset:3072
	v_add_u32_e32 v140, s2, v142
	ds_read_b128 v[160:163], v140
	ds_read_b128 v[164:167], v140 offset:1024
	ds_read_b128 v[168:171], v140 offset:2048
	ds_read_b128 v[172:175], v140 offset:3072
	v_lshl_add_u64 v[140:141], s[48:49], 0, v[136:137]
	s_add_i32 m0, s4, 0xc000
	ds_read_b128 v[190:193], v143
	ds_read_b128 v[194:197], v143 offset:1024
	ds_read_b128 v[198:201], v143 offset:2048
	ds_read_b128 v[212:215], v143 offset:3072
	ds_read_b128 v[216:219], v143 offset:4096
	ds_read_b128 v[220:223], v143 offset:5120
	ds_read_b128 v[224:227], v143 offset:6144
	ds_read_b128 v[228:231], v143 offset:7168
	global_load_lds_dwordx4 v[140:141], off
	v_lshl_add_u64 v[140:141], s[48:49], 0, v[138:139]
	s_add_i32 m0, s4, 0xe000
	s_nop 0
	global_load_lds_dwordx4 v[140:141], off
	s_waitcnt vmcnt(8)
	s_waitcnt lgkmcnt(0)
	s_barrier
	s_waitcnt lgkmcnt(0)
	v_mfma_f32_16x16x32_bf16 v[126:129], v[144:147], v[190:193], 0
	v_mfma_f32_16x16x32_bf16 v[122:125], v[152:155], v[190:193], 0
	v_mfma_f32_16x16x32_bf16 v[118:121], v[144:147], v[198:201], 0
	v_mfma_f32_16x16x32_bf16 v[110:113], v[152:155], v[198:201], 0
	v_mfma_f32_16x16x32_bf16 v[102:105], v[144:147], v[216:219], 0
	v_mfma_f32_16x16x32_bf16 v[94:97], v[152:155], v[216:219], 0
	v_mfma_f32_16x16x32_bf16 v[82:85], v[144:147], v[224:227], 0
	v_mfma_f32_16x16x32_bf16 v[74:77], v[152:155], v[224:227], 0
	v_mfma_f32_16x16x32_bf16 v[126:129], v[148:151], v[194:197], v[126:129]
	v_mfma_f32_16x16x32_bf16 v[122:125], v[156:159], v[194:197], v[122:125]
	v_mfma_f32_16x16x32_bf16 v[118:121], v[148:151], v[212:215], v[118:121]
	v_mfma_f32_16x16x32_bf16 v[110:113], v[156:159], v[212:215], v[110:113]
	v_mfma_f32_16x16x32_bf16 v[102:105], v[148:151], v[220:223], v[102:105]
	v_mfma_f32_16x16x32_bf16 v[94:97], v[156:159], v[220:223], v[94:97]
	v_mfma_f32_16x16x32_bf16 v[82:85], v[148:151], v[228:231], v[82:85]
	v_mfma_f32_16x16x32_bf16 v[74:77], v[156:159], v[228:231], v[74:77]
	v_mfma_f32_16x16x32_bf16 v[114:117], v[160:163], v[190:193], 0
	v_mfma_f32_16x16x32_bf16 v[106:109], v[168:171], v[190:193], 0
	v_mfma_f32_16x16x32_bf16 v[98:101], v[160:163], v[198:201], 0
	v_mfma_f32_16x16x32_bf16 v[90:93], v[168:171], v[198:201], 0
	v_mfma_f32_16x16x32_bf16 v[86:89], v[160:163], v[216:219], 0
	v_mfma_f32_16x16x32_bf16 v[78:81], v[168:171], v[216:219], 0
	v_mfma_f32_16x16x32_bf16 v[70:73], v[160:163], v[224:227], 0
	v_mfma_f32_16x16x32_bf16 v[66:69], v[168:171], v[224:227], 0
	v_mfma_f32_16x16x32_bf16 v[114:117], v[164:167], v[194:197], v[114:117]
	v_mfma_f32_16x16x32_bf16 v[106:109], v[172:175], v[194:197], v[106:109]
	v_mfma_f32_16x16x32_bf16 v[98:101], v[164:167], v[212:215], v[98:101]
	v_mfma_f32_16x16x32_bf16 v[90:93], v[172:175], v[212:215], v[90:93]
	v_mfma_f32_16x16x32_bf16 v[86:89], v[164:167], v[220:223], v[86:89]
	v_mfma_f32_16x16x32_bf16 v[78:81], v[172:175], v[220:223], v[78:81]
	v_mfma_f32_16x16x32_bf16 v[70:73], v[164:167], v[228:231], v[70:73]
	v_mfma_f32_16x16x32_bf16 v[66:69], v[172:175], v[228:231], v[66:69]
	s_barrier
	s_add_i32 s8, s9, s3
	v_lshl_add_u64 v[140:141], s[50:51], 0, v[0:1]
	s_mov_b32 m0, s8
	ds_read_b128 v[190:193], v143 offset:16384
	ds_read_b128 v[194:197], v143 offset:17408
	ds_read_b128 v[198:201], v143 offset:18432
	ds_read_b128 v[212:215], v143 offset:19456
	ds_read_b128 v[216:219], v143 offset:20480
	ds_read_b128 v[220:223], v143 offset:21504
	ds_read_b128 v[224:227], v143 offset:22528
	ds_read_b128 v[228:231], v143 offset:23552
	global_load_lds_dwordx4 v[140:141], off
	s_add_i32 m0, s8, 0x2000
	s_add_u32 s22, s50, 0x40000
	v_lshl_add_u64 v[176:177], s[50:51], 0, v[130:131]
	s_addc_u32 s23, s51, 0
	s_add_i32 s2, s2, s3
	global_load_lds_dwordx4 v[176:177], off
	v_lshl_add_u64 v[232:233], s[22:23], 0, v[0:1]
	s_mov_b32 m0, s2
	v_lshl_add_u64 v[234:235], s[52:53], 0, v[132:133]
	global_load_lds_dwordx4 v[232:233], off
	v_lshl_add_u64 v[232:233], s[22:23], 0, v[130:131]
	s_add_i32 m0, s2, 0x2000
	s_nop 0
	global_load_lds_dwordx4 v[232:233], off
	v_lshl_add_u64 v[232:233], s[52:53], 0, v[134:135]
	s_mov_b32 m0, s4
	s_nop 0
	global_load_lds_dwordx4 v[232:233], off
	s_mov_b32 m0, s5
	s_nop 0
	global_load_lds_dwordx4 v[234:235], off
	s_waitcnt vmcnt(8)
	s_waitcnt lgkmcnt(0)
	s_barrier
; #define PG8_STAGE(bufoff, gbase, voff) do { _Pragma("unroll") for (int _i = 0; _i < 2; ++_i) \
;         __builtin_amdgcn_global_load_lds((const unsigned*)((const char*)(gbase) + (voff)[_i]), (PG8_LAS unsigned*)(lds + (bufoff) + ldsw + _i * 8192), 16, 0, 0); } while (0)
; #define PG8_LDA(dst, b, h) do { _Pragma("unroll") for (int m = 0; m < 4; ++m) _Pragma("unroll") for (int k = 0; k < 2; ++k) dst[m][k] = *(const PG8_LAS bf16x8*)(lds + PG8_SA(b, h) + aoff + m * 2048 + k * 1024); } while (0)
; #define PG8_LDB(dst, b, h) do { _Pragma("unroll") for (int n = 0; n < 2; ++n) _Pragma("unroll") for (int k = 0; k < 2; ++k) dst[n][k] = *(const PG8_LAS bf16x8*)(lds + PG8_SB(b, h) + boff + n * 2048 + k * 1024); } while (0)
; #define PG8_MMA(ai, bj, At, Bt) do { __builtin_amdgcn_s_setprio(1); _Pragma("unroll") for (int m = 0; m < 4; ++m) _Pragma("unroll") for (int n = 0; n < 2; ++n) _Pragma("unroll") for (int k = 0; k < 2; ++k) \
;         acc[ai][bj][m][n] = __builtin_amdgcn_mfma_f32_16x16x32_bf16(Bt[n][k], At[m][k], acc[ai][bj][m][n], 0, 0, 0); __builtin_amdgcn_s_setprio(0); } while (0)
; #define PG8_WAIT_V(n) asm volatile("s_waitcnt vmcnt(" #n ")" ::: "memory")
; #define PG8_WAIT_L(n) asm volatile("s_waitcnt lgkmcnt(" #n ")" ::: "memory")
; #define PG8_BAR __builtin_amdgcn_s_barrier()
; #define PG8_SCHED __builtin_amdgcn_sched_barrier(0)
; template <class Epi, class Sched, bool ALIGN_EPI = false, bool SP2 = false>
; __device__ __forceinline__ void gemm_phase(PG8_LAS unsigned char* lds, const Gemm g, const Sched& S, const Epi& E, const int wid_in) {
;     ...
;             PG8_WAIT_V(8); PG8_WAIT_L(0); PG8_BAR; PG8_MMA(0, 0, At, B0); PG8_MMA(0, 1, At, B1); PG8_BAR; PG8_SCHED;
;             PG8_LDA(At, 0, 1); PG8_STAGE(PG8_SB(0, 0), b2, voffB); PG8_STAGE(PG8_SB(0, 1), b2 + hstep, voffB); PG8_STAGE(PG8_SA(0, 0), a2, voffA);
;             PG8_WAIT_V(8); PG8_WAIT_L(0); PG8_BAR; PG8_MMA(1, 0, At, B0); PG8_MMA(1, 1, At, B1); PG8_BAR; PG8_SCHED;
;             PG8_LDB(B0, 1, 0); PG8_LDB(B1, 1, 1); PG8_SCHED; PG8_LDA(At, 1, 0); PG8_STAGE(PG8_SA(0, 1), a2 + hstep, voffA);
;             PG8_WAIT_V(8); PG8_WAIT_L(0); PG8_BAR; PG8_MMA(0, 0, At, B0); PG8_MMA(0, 1, At, B1); PG8_BAR; PG8_SCHED;
	s_waitcnt lgkmcnt(0)
	v_mfma_f32_16x16x32_bf16 v[62:65], v[144:147], v[190:193], 0
	v_mfma_f32_16x16x32_bf16 v[58:61], v[152:155], v[190:193], 0
	v_mfma_f32_16x16x32_bf16 v[54:57], v[144:147], v[198:201], 0
	v_mfma_f32_16x16x32_bf16 v[46:49], v[152:155], v[198:201], 0
	v_mfma_f32_16x16x32_bf16 v[38:41], v[144:147], v[216:219], 0
	v_mfma_f32_16x16x32_bf16 v[30:33], v[152:155], v[216:219], 0
	v_mfma_f32_16x16x32_bf16 v[22:25], v[144:147], v[224:227], 0
	v_mfma_f32_16x16x32_bf16 v[14:17], v[152:155], v[224:227], 0
	v_mfma_f32_16x16x32_bf16 v[62:65], v[148:151], v[194:197], v[62:65]
	v_mfma_f32_16x16x32_bf16 v[58:61], v[156:159], v[194:197], v[58:61]
	v_mfma_f32_16x16x32_bf16 v[54:57], v[148:151], v[212:215], v[54:57]
	v_mfma_f32_16x16x32_bf16 v[46:49], v[156:159], v[212:215], v[46:49]
	v_mfma_f32_16x16x32_bf16 v[38:41], v[148:151], v[220:223], v[38:41]
	v_mfma_f32_16x16x32_bf16 v[30:33], v[156:159], v[220:223], v[30:33]
	v_mfma_f32_16x16x32_bf16 v[22:25], v[148:151], v[228:231], v[22:25]
	v_mfma_f32_16x16x32_bf16 v[14:17], v[156:159], v[228:231], v[14:17]
	v_mfma_f32_16x16x32_bf16 v[50:53], v[160:163], v[190:193], 0
	v_mfma_f32_16x16x32_bf16 v[42:45], v[168:171], v[190:193], 0
	v_mfma_f32_16x16x32_bf16 v[34:37], v[160:163], v[198:201], 0
	v_mfma_f32_16x16x32_bf16 v[26:29], v[168:171], v[198:201], 0
	v_mfma_f32_16x16x32_bf16 v[18:21], v[160:163], v[216:219], 0
	v_mfma_f32_16x16x32_bf16 v[10:13], v[168:171], v[216:219], 0
	v_mfma_f32_16x16x32_bf16 v[6:9], v[160:163], v[224:227], 0
	v_mfma_f32_16x16x32_bf16 v[2:5], v[168:171], v[224:227], 0
	v_mfma_f32_16x16x32_bf16 v[50:53], v[164:167], v[194:197], v[50:53]
	v_mfma_f32_16x16x32_bf16 v[42:45], v[172:175], v[194:197], v[42:45]
	v_mfma_f32_16x16x32_bf16 v[34:37], v[164:167], v[212:215], v[34:37]
	v_mfma_f32_16x16x32_bf16 v[26:29], v[172:175], v[212:215], v[26:29]
	v_mfma_f32_16x16x32_bf16 v[18:21], v[164:167], v[220:223], v[18:21]
	v_mfma_f32_16x16x32_bf16 v[10:13], v[172:175], v[220:223], v[10:13]
	v_mfma_f32_16x16x32_bf16 v[6:9], v[164:167], v[228:231], v[6:9]
	v_mfma_f32_16x16x32_bf16 v[2:5], v[172:175], v[228:231], v[2:5]
	s_barrier
	s_add_i32 s2, 0, 0x18000
	s_add_i32 s8, 0, 0x1c000
	v_add_u32_e32 v156, s2, v142
	v_add_u32_e32 v172, s8, v142
	ds_read_b128 v[144:147], v156
	ds_read_b128 v[148:151], v156 offset:1024
	ds_read_b128 v[152:155], v156 offset:2048
	ds_read_b128 v[156:159], v156 offset:3072
	ds_read_b128 v[160:163], v172
	ds_read_b128 v[164:167], v172 offset:1024
	ds_read_b128 v[168:171], v172 offset:2048
	ds_read_b128 v[172:175], v172 offset:3072
	s_add_u32 s22, s52, 0x40000
	s_addc_u32 s23, s53, 0
	s_mov_b32 m0, s12
	v_lshl_add_u64 v[236:237], s[22:23], 0, v[134:135]
	ds_read_b128 v[190:193], v143 offset:32768
	ds_read_b128 v[194:197], v143 offset:33792
	ds_read_b128 v[198:201], v143 offset:34816
	ds_read_b128 v[212:215], v143 offset:35840
	ds_read_b128 v[216:219], v143 offset:36864
	ds_read_b128 v[220:223], v143 offset:37888
	ds_read_b128 v[224:227], v143 offset:38912
	ds_read_b128 v[228:231], v143 offset:39936
	global_load_lds_dwordx4 v[236:237], off
	v_lshl_add_u64 v[236:237], s[22:23], 0, v[132:133]
	s_mov_b32 m0, s13
	s_nop 0
	global_load_lds_dwordx4 v[236:237], off
	s_waitcnt vmcnt(8)
	s_waitcnt lgkmcnt(0)
	s_barrier
	s_waitcnt lgkmcnt(0)
	v_mfma_f32_16x16x32_bf16 v[126:129], v[144:147], v[190:193], v[126:129]
	v_mfma_f32_16x16x32_bf16 v[122:125], v[152:155], v[190:193], v[122:125]
	v_mfma_f32_16x16x32_bf16 v[118:121], v[144:147], v[198:201], v[118:121]
	v_mfma_f32_16x16x32_bf16 v[110:113], v[152:155], v[198:201], v[110:113]
	v_mfma_f32_16x16x32_bf16 v[102:105], v[144:147], v[216:219], v[102:105]
	v_mfma_f32_16x16x32_bf16 v[94:97], v[152:155], v[216:219], v[94:97]
	v_mfma_f32_16x16x32_bf16 v[82:85], v[144:147], v[224:227], v[82:85]
	v_mfma_f32_16x16x32_bf16 v[74:77], v[152:155], v[224:227], v[74:77]
	v_mfma_f32_16x16x32_bf16 v[126:129], v[148:151], v[194:197], v[126:129]
	v_mfma_f32_16x16x32_bf16 v[122:125], v[156:159], v[194:197], v[122:125]
	v_mfma_f32_16x16x32_bf16 v[118:121], v[148:151], v[212:215], v[118:121]
	v_mfma_f32_16x16x32_bf16 v[110:113], v[156:159], v[212:215], v[110:113]
	v_mfma_f32_16x16x32_bf16 v[102:105], v[148:151], v[220:223], v[102:105]
	v_mfma_f32_16x16x32_bf16 v[94:97], v[156:159], v[220:223], v[94:97]
	v_mfma_f32_16x16x32_bf16 v[82:85], v[148:151], v[228:231], v[82:85]
	v_mfma_f32_16x16x32_bf16 v[74:77], v[156:159], v[228:231], v[74:77]
	v_mfma_f32_16x16x32_bf16 v[114:117], v[160:163], v[190:193], v[114:117]
	v_mfma_f32_16x16x32_bf16 v[106:109], v[168:171], v[190:193], v[106:109]
	v_mfma_f32_16x16x32_bf16 v[98:101], v[160:163], v[198:201], v[98:101]
	v_mfma_f32_16x16x32_bf16 v[90:93], v[168:171], v[198:201], v[90:93]
	v_mfma_f32_16x16x32_bf16 v[86:89], v[160:163], v[216:219], v[86:89]
	v_mfma_f32_16x16x32_bf16 v[78:81], v[168:171], v[216:219], v[78:81]
	v_mfma_f32_16x16x32_bf16 v[70:73], v[160:163], v[224:227], v[70:73]
	v_mfma_f32_16x16x32_bf16 v[66:69], v[168:171], v[224:227], v[66:69]
	v_mfma_f32_16x16x32_bf16 v[114:117], v[164:167], v[194:197], v[114:117]
	v_mfma_f32_16x16x32_bf16 v[106:109], v[172:175], v[194:197], v[106:109]
	v_mfma_f32_16x16x32_bf16 v[98:101], v[164:167], v[212:215], v[98:101]
	v_mfma_f32_16x16x32_bf16 v[90:93], v[172:175], v[212:215], v[90:93]
	v_mfma_f32_16x16x32_bf16 v[86:89], v[164:167], v[220:223], v[86:89]
	v_mfma_f32_16x16x32_bf16 v[78:81], v[172:175], v[220:223], v[78:81]
	v_mfma_f32_16x16x32_bf16 v[70:73], v[164:167], v[228:231], v[70:73]
	v_mfma_f32_16x16x32_bf16 v[66:69], v[172:175], v[228:231], v[66:69]
	s_barrier
; #define PG8_STAGE(bufoff, gbase, voff) do { _Pragma("unroll") for (int _i = 0; _i < 2; ++_i) \
;         __builtin_amdgcn_global_load_lds((const unsigned*)((const char*)(gbase) + (voff)[_i]), (PG8_LAS unsigned*)(lds + (bufoff) + ldsw + _i * 8192), 16, 0, 0); } while (0)
; #define PG8_LDA(dst, b, h) do { _Pragma("unroll") for (int m = 0; m < 4; ++m) _Pragma("unroll") for (int k = 0; k < 2; ++k) dst[m][k] = *(const PG8_LAS bf16x8*)(lds + PG8_SA(b, h) + aoff + m * 2048 + k * 1024); } while (0)
; #define PG8_LDB(dst, b, h) do { _Pragma("unroll") for (int n = 0; n < 2; ++n) _Pragma("unroll") for (int k = 0; k < 2; ++k) dst[n][k] = *(const PG8_LAS bf16x8*)(lds + PG8_SB(b, h) + boff + n * 2048 + k * 1024); } while (0)
; #define PG8_WAIT_V(n) asm volatile("s_waitcnt vmcnt(" #n ")" ::: "memory")
; template <class Epi, class Sched, bool ALIGN_EPI = false, bool SP2 = false>
; __device__ __forceinline__ void gemm_phase(PG8_LAS unsigned char* lds, const Gemm g, const Sched& S, const Epi& E, const int wid_in) {
;     ...
;         for (int t = 0; t < nt; t += 2) {
;             const bool last = (t == nt - 2);
;             const char* a1 = cA + (size_t)(t + 1) * kstep;
;             const char* a2 = last ? nA : cA + (size_t)(t + 2) * kstep; const char* b2 = last ? nB : cB + (size_t)(t + 2) * kstep;
;             const char* a3 = a2 + kstep; const char* b3 = b2 + kstep;
;             if (last && has_next) S.a_ready(nxt);
;             if constexpr (SP2) {
;             PG8_LDB(B0, 0, 0); PG8_LDB(B1, 0, 1); PG8_SCHED; PG8_LDA(At, 0, 0); PG8_STAGE(PG8_SA(1, 1), a1 + hstep, voffA);
;             PG8_WAIT_V(8); PG8_WAIT_L(0); PG8_BAR; PG8_MMA(0, 0, At, B0); PG8_MMA(0, 1, At, B1); PG8_BAR; PG8_SCHED;
;             PG8_LDA(At, 0, 1); PG8_STAGE(PG8_SB(0, 0), b2, voffB); PG8_STAGE(PG8_SB(0, 1), b2 + hstep, voffB); PG8_STAGE(PG8_SA(0, 0), a2, voffA);
;             PG8_WAIT_V(8); PG8_WAIT_L(0); PG8_BAR; PG8_MMA(1, 0, At, B0); PG8_MMA(1, 1, At, B1); PG8_BAR; PG8_SCHED;
;             PG8_LDB(B0, 1, 0); PG8_LDB(B1, 1, 1); PG8_SCHED; PG8_LDA(At, 1, 0); PG8_STAGE(PG8_SA(0, 1), a2 + hstep, voffA);
;             PG8_WAIT_V(8); PG8_WAIT_L(0); PG8_BAR; PG8_MMA(0, 0, At, B0); PG8_MMA(0, 1, At, B1); PG8_BAR; PG8_SCHED;
;             PG8_LDA(At, 1, 1); PG8_STAGE(PG8_SB(1, 0), b3, voffB); PG8_STAGE(PG8_SB(1, 1), b3 + hstep, voffB); PG8_STAGE(PG8_SA(1, 0), a3, voffA);
	s_add_i32 s2, s2, s3
	v_lshl_add_u64 v[140:141], v[140:141], 0, s[64:65]
	s_mov_b32 m0, s2
	ds_read_b128 v[190:193], v143 offset:49152
	ds_read_b128 v[194:197], v143 offset:50176
	ds_read_b128 v[198:201], v143 offset:51200
	ds_read_b128 v[212:215], v143 offset:52224
	ds_read_b128 v[216:219], v143 offset:53248
	ds_read_b128 v[220:223], v143 offset:54272
	ds_read_b128 v[224:227], v143 offset:55296
	ds_read_b128 v[228:231], v143 offset:56320
	global_load_lds_dwordx4 v[140:141], off
	s_add_i32 m0, s2, 0x2000
	s_add_u32 s22, s50, 0x40080
	v_lshl_add_u64 v[140:141], v[176:177], 0, s[64:65]
	s_addc_u32 s23, s51, 0
	s_add_i32 s2, s8, s3
	global_load_lds_dwordx4 v[140:141], off
	v_lshl_add_u64 v[140:141], s[22:23], 0, v[0:1]
	s_mov_b32 m0, s2
	s_nop 0
	global_load_lds_dwordx4 v[140:141], off
	v_lshl_add_u64 v[140:141], s[22:23], 0, v[130:131]
	s_add_i32 m0, s2, 0x2000
	s_nop 0
	global_load_lds_dwordx4 v[140:141], off
	v_lshl_add_u64 v[140:141], v[232:233], 0, s[64:65]
	s_mov_b32 m0, s36
	s_nop 0
	global_load_lds_dwordx4 v[140:141], off
	v_lshl_add_u64 v[140:141], v[234:235], 0, s[64:65]
	s_mov_b32 m0, s37
	s_nop 0
	global_load_lds_dwordx4 v[140:141], off
	s_waitcnt vmcnt(8)
	s_waitcnt lgkmcnt(0)
	s_barrier
	s_waitcnt lgkmcnt(0)
	v_mfma_f32_16x16x32_bf16 v[62:65], v[144:147], v[190:193], v[62:65]
	v_mfma_f32_16x16x32_bf16 v[58:61], v[152:155], v[190:193], v[58:61]
	v_mfma_f32_16x16x32_bf16 v[54:57], v[144:147], v[198:201], v[54:57]
	v_mfma_f32_16x16x32_bf16 v[46:49], v[152:155], v[198:201], v[46:49]
	v_mfma_f32_16x16x32_bf16 v[38:41], v[144:147], v[216:219], v[38:41]
	v_mfma_f32_16x16x32_bf16 v[30:33], v[152:155], v[216:219], v[30:33]
	v_mfma_f32_16x16x32_bf16 v[22:25], v[144:147], v[224:227], v[22:25]
	v_mfma_f32_16x16x32_bf16 v[14:17], v[152:155], v[224:227], v[14:17]
	v_mfma_f32_16x16x32_bf16 v[62:65], v[148:151], v[194:197], v[62:65]
	v_mfma_f32_16x16x32_bf16 v[58:61], v[156:159], v[194:197], v[58:61]
	v_mfma_f32_16x16x32_bf16 v[54:57], v[148:151], v[212:215], v[54:57]
	v_mfma_f32_16x16x32_bf16 v[46:49], v[156:159], v[212:215], v[46:49]
	v_mfma_f32_16x16x32_bf16 v[38:41], v[148:151], v[220:223], v[38:41]
	v_mfma_f32_16x16x32_bf16 v[30:33], v[156:159], v[220:223], v[30:33]
	v_mfma_f32_16x16x32_bf16 v[22:25], v[148:151], v[228:231], v[22:25]
	v_mfma_f32_16x16x32_bf16 v[14:17], v[156:159], v[228:231], v[14:17]
	v_mfma_f32_16x16x32_bf16 v[50:53], v[160:163], v[190:193], v[50:53]
	v_mfma_f32_16x16x32_bf16 v[42:45], v[168:171], v[190:193], v[42:45]
	v_mfma_f32_16x16x32_bf16 v[34:37], v[160:163], v[198:201], v[34:37]
	v_mfma_f32_16x16x32_bf16 v[26:29], v[168:171], v[198:201], v[26:29]
	v_mfma_f32_16x16x32_bf16 v[18:21], v[160:163], v[216:219], v[18:21]
	v_mfma_f32_16x16x32_bf16 v[10:13], v[168:171], v[216:219], v[10:13]
	v_mfma_f32_16x16x32_bf16 v[6:9], v[160:163], v[224:227], v[6:9]
	v_mfma_f32_16x16x32_bf16 v[2:5], v[168:171], v[224:227], v[2:5]
	v_mfma_f32_16x16x32_bf16 v[50:53], v[164:167], v[194:197], v[50:53]
	v_mfma_f32_16x16x32_bf16 v[42:45], v[172:175], v[194:197], v[42:45]
	v_mfma_f32_16x16x32_bf16 v[34:37], v[164:167], v[212:215], v[34:37]
	v_mfma_f32_16x16x32_bf16 v[26:29], v[172:175], v[212:215], v[26:29]
	v_mfma_f32_16x16x32_bf16 v[18:21], v[164:167], v[220:223], v[18:21]
	v_mfma_f32_16x16x32_bf16 v[10:13], v[172:175], v[220:223], v[10:13]
	v_mfma_f32_16x16x32_bf16 v[6:9], v[164:167], v[228:231], v[6:9]
	v_mfma_f32_16x16x32_bf16 v[2:5], v[172:175], v[228:231], v[2:5]
	s_barrier
	s_add_i32 s60, s60, 2
	s_add_u32 s48, s48, 0x100
	s_addc_u32 s49, s49, 0
	s_add_u32 s58, s58, 0x100
	s_addc_u32 s59, s59, 0
	s_cmp_gt_u32 s60, 13
.LBB0_537:
	s_add_u32 s2, s48, 0xfffc0080
	s_addc_u32 s8, s49, -1
	s_add_i32 s9, 0, 0x10000
	s_cmp_eq_u32 s60, 12
	s_cselect_b32 s53, s43, s8
	s_cselect_b32 s52, s57, s2
	v_add_u32_e32 v140, s9, v142
	s_cselect_b32 s51, s16, s59
	s_cselect_b32 s50, s39, s58
	s_add_i32 s2, 0, 0x14000
	ds_read_b128 v[144:147], v140
	ds_read_b128 v[148:151], v140 offset:1024
	ds_read_b128 v[152:155], v140 offset:2048
	ds_read_b128 v[156:159], v140 offset:3072
	v_add_u32_e32 v140, s2, v142
	ds_read_b128 v[160:163], v140
	ds_read_b128 v[164:167], v140 offset:1024
	ds_read_b128 v[168:171], v140 offset:2048
	ds_read_b128 v[172:175], v140 offset:3072
	v_lshl_add_u64 v[140:141], s[48:49], 0, v[136:137]
	s_add_i32 m0, s4, 0xc000
	ds_read_b128 v[190:193], v143
	ds_read_b128 v[194:197], v143 offset:1024
	ds_read_b128 v[198:201], v143 offset:2048
	ds_read_b128 v[212:215], v143 offset:3072
	ds_read_b128 v[216:219], v143 offset:4096
	ds_read_b128 v[220:223], v143 offset:5120
	ds_read_b128 v[224:227], v143 offset:6144
	ds_read_b128 v[228:231], v143 offset:7168
	global_load_lds_dwordx4 v[140:141], off
	v_lshl_add_u64 v[140:141], s[48:49], 0, v[138:139]
	s_add_i32 m0, s4, 0xe000
	s_nop 0
	global_load_lds_dwordx4 v[140:141], off
	s_waitcnt vmcnt(8)
	s_waitcnt lgkmcnt(0)
	s_barrier
; #define PG8_STAGE(bufoff, gbase, voff) do { _Pragma("unroll") for (int _i = 0; _i < 2; ++_i) \
;         __builtin_amdgcn_global_load_lds((const unsigned*)((const char*)(gbase) + (voff)[_i]), (PG8_LAS unsigned*)(lds + (bufoff) + ldsw + _i * 8192), 16, 0, 0); } while (0)
; #define PG8_LDA(dst, b, h) do { _Pragma("unroll") for (int m = 0; m < 4; ++m) _Pragma("unroll") for (int k = 0; k < 2; ++k) dst[m][k] = *(const PG8_LAS bf16x8*)(lds + PG8_SA(b, h) + aoff + m * 2048 + k * 1024); } while (0)
; #define PG8_LDB(dst, b, h) do { _Pragma("unroll") for (int n = 0; n < 2; ++n) _Pragma("unroll") for (int k = 0; k < 2; ++k) dst[n][k] = *(const PG8_LAS bf16x8*)(lds + PG8_SB(b, h) + boff + n * 2048 + k * 1024); } while (0)
; #define PG8_MMA(ai, bj, At, Bt) do { __builtin_amdgcn_s_setprio(1); _Pragma("unroll") for (int m = 0; m < 4; ++m) _Pragma("unroll") for (int n = 0; n < 2; ++n) _Pragma("unroll") for (int k = 0; k < 2; ++k) \
;         acc[ai][bj][m][n] = __builtin_amdgcn_mfma_f32_16x16x32_bf16(Bt[n][k], At[m][k], acc[ai][bj][m][n], 0, 0, 0); __builtin_amdgcn_s_setprio(0); } while (0)
; #define PG8_WAIT_V(n) asm volatile("s_waitcnt vmcnt(" #n ")" ::: "memory")
; #define PG8_WAIT_L(n) asm volatile("s_waitcnt lgkmcnt(" #n ")" ::: "memory")
; #define PG8_BAR __builtin_amdgcn_s_barrier()
; #define PG8_SCHED __builtin_amdgcn_sched_barrier(0)
; template <class Epi, class Sched, bool ALIGN_EPI = false, bool SP2 = false>
; __device__ __forceinline__ void gemm_phase(PG8_LAS unsigned char* lds, const Gemm g, const Sched& S, const Epi& E, const int wid_in) {
;     ...
;             PG8_LDB(B0, 0, 0); PG8_LDB(B1, 0, 1); PG8_SCHED; PG8_LDA(At, 0, 0); PG8_STAGE(PG8_SA(1, 1), a1 + hstep, voffA);
;             PG8_WAIT_V(8); PG8_WAIT_L(0); PG8_BAR; PG8_MMA(0, 0, At, B0); PG8_MMA(0, 1, At, B1); PG8_BAR; PG8_SCHED;
;             PG8_LDA(At, 0, 1); PG8_STAGE(PG8_SB(0, 0), b2, voffB); PG8_STAGE(PG8_SB(0, 1), b2 + hstep, voffB); PG8_STAGE(PG8_SA(0, 0), a2, voffA);
;             PG8_WAIT_V(8); PG8_WAIT_L(0); PG8_BAR; PG8_MMA(1, 0, At, B0); PG8_MMA(1, 1, At, B1); PG8_BAR; PG8_SCHED;
	s_waitcnt lgkmcnt(0)
	v_mfma_f32_16x16x32_bf16 v[126:129], v[144:147], v[190:193], v[126:129]
	v_mfma_f32_16x16x32_bf16 v[122:125], v[152:155], v[190:193], v[122:125]
	v_mfma_f32_16x16x32_bf16 v[118:121], v[144:147], v[198:201], v[118:121]
	v_mfma_f32_16x16x32_bf16 v[110:113], v[152:155], v[198:201], v[110:113]
	v_mfma_f32_16x16x32_bf16 v[102:105], v[144:147], v[216:219], v[102:105]
	v_mfma_f32_16x16x32_bf16 v[94:97], v[152:155], v[216:219], v[94:97]
	v_mfma_f32_16x16x32_bf16 v[82:85], v[144:147], v[224:227], v[82:85]
	v_mfma_f32_16x16x32_bf16 v[74:77], v[152:155], v[224:227], v[74:77]
	v_mfma_f32_16x16x32_bf16 v[126:129], v[148:151], v[194:197], v[126:129]
	v_mfma_f32_16x16x32_bf16 v[122:125], v[156:159], v[194:197], v[122:125]
	v_mfma_f32_16x16x32_bf16 v[118:121], v[148:151], v[212:215], v[118:121]
	v_mfma_f32_16x16x32_bf16 v[110:113], v[156:159], v[212:215], v[110:113]
	v_mfma_f32_16x16x32_bf16 v[102:105], v[148:151], v[220:223], v[102:105]
	v_mfma_f32_16x16x32_bf16 v[94:97], v[156:159], v[220:223], v[94:97]
	v_mfma_f32_16x16x32_bf16 v[82:85], v[148:151], v[228:231], v[82:85]
	v_mfma_f32_16x16x32_bf16 v[74:77], v[156:159], v[228:231], v[74:77]
	v_mfma_f32_16x16x32_bf16 v[114:117], v[160:163], v[190:193], v[114:117]
	v_mfma_f32_16x16x32_bf16 v[106:109], v[168:171], v[190:193], v[106:109]
	v_mfma_f32_16x16x32_bf16 v[98:101], v[160:163], v[198:201], v[98:101]
	v_mfma_f32_16x16x32_bf16 v[90:93], v[168:171], v[198:201], v[90:93]
	v_mfma_f32_16x16x32_bf16 v[86:89], v[160:163], v[216:219], v[86:89]
	v_mfma_f32_16x16x32_bf16 v[78:81], v[168:171], v[216:219], v[78:81]
	v_mfma_f32_16x16x32_bf16 v[70:73], v[160:163], v[224:227], v[70:73]
	v_mfma_f32_16x16x32_bf16 v[66:69], v[168:171], v[224:227], v[66:69]
	v_mfma_f32_16x16x32_bf16 v[114:117], v[164:167], v[194:197], v[114:117]
	v_mfma_f32_16x16x32_bf16 v[106:109], v[172:175], v[194:197], v[106:109]
	v_mfma_f32_16x16x32_bf16 v[98:101], v[164:167], v[212:215], v[98:101]
	v_mfma_f32_16x16x32_bf16 v[90:93], v[172:175], v[212:215], v[90:93]
	v_mfma_f32_16x16x32_bf16 v[86:89], v[164:167], v[220:223], v[86:89]
	v_mfma_f32_16x16x32_bf16 v[78:81], v[172:175], v[220:223], v[78:81]
	v_mfma_f32_16x16x32_bf16 v[70:73], v[164:167], v[228:231], v[70:73]
	v_mfma_f32_16x16x32_bf16 v[66:69], v[172:175], v[228:231], v[66:69]
	s_barrier
	s_add_i32 s8, s9, s3
	v_lshl_add_u64 v[140:141], s[50:51], 0, v[0:1]
	s_mov_b32 m0, s8
	ds_read_b128 v[190:193], v143 offset:16384
	ds_read_b128 v[194:197], v143 offset:17408
	ds_read_b128 v[198:201], v143 offset:18432
	ds_read_b128 v[212:215], v143 offset:19456
	ds_read_b128 v[216:219], v143 offset:20480
	ds_read_b128 v[220:223], v143 offset:21504
	ds_read_b128 v[224:227], v143 offset:22528
	ds_read_b128 v[228:231], v143 offset:23552
	global_load_lds_dwordx4 v[140:141], off
	s_add_i32 m0, s8, 0x2000
	s_add_u32 s22, s50, 0x40000
	v_lshl_add_u64 v[176:177], s[50:51], 0, v[130:131]
	s_addc_u32 s23, s51, 0
	s_add_i32 s2, s2, s3
	global_load_lds_dwordx4 v[176:177], off
	v_lshl_add_u64 v[232:233], s[22:23], 0, v[0:1]
	s_mov_b32 m0, s2
	v_lshl_add_u64 v[234:235], s[52:53], 0, v[132:133]
	global_load_lds_dwordx4 v[232:233], off
	v_lshl_add_u64 v[232:233], s[22:23], 0, v[130:131]
	s_add_i32 m0, s2, 0x2000
	s_nop 0
	global_load_lds_dwordx4 v[232:233], off
	v_lshl_add_u64 v[232:233], s[52:53], 0, v[134:135]
	s_mov_b32 m0, s4
	s_nop 0
	global_load_lds_dwordx4 v[232:233], off
	s_mov_b32 m0, s5
	s_nop 0
	global_load_lds_dwordx4 v[234:235], off
	s_waitcnt vmcnt(8)
	s_waitcnt lgkmcnt(0)
	s_barrier
	s_waitcnt lgkmcnt(0)
	v_mfma_f32_16x16x32_bf16 v[62:65], v[144:147], v[190:193], v[62:65]
	v_mfma_f32_16x16x32_bf16 v[58:61], v[152:155], v[190:193], v[58:61]
	v_mfma_f32_16x16x32_bf16 v[54:57], v[144:147], v[198:201], v[54:57]
	v_mfma_f32_16x16x32_bf16 v[46:49], v[152:155], v[198:201], v[46:49]
	v_mfma_f32_16x16x32_bf16 v[38:41], v[144:147], v[216:219], v[38:41]
	v_mfma_f32_16x16x32_bf16 v[30:33], v[152:155], v[216:219], v[30:33]
	v_mfma_f32_16x16x32_bf16 v[22:25], v[144:147], v[224:227], v[22:25]
	v_mfma_f32_16x16x32_bf16 v[14:17], v[152:155], v[224:227], v[14:17]
	v_mfma_f32_16x16x32_bf16 v[62:65], v[148:151], v[194:197], v[62:65]
	v_mfma_f32_16x16x32_bf16 v[58:61], v[156:159], v[194:197], v[58:61]
	v_mfma_f32_16x16x32_bf16 v[54:57], v[148:151], v[212:215], v[54:57]
	v_mfma_f32_16x16x32_bf16 v[46:49], v[156:159], v[212:215], v[46:49]
	v_mfma_f32_16x16x32_bf16 v[38:41], v[148:151], v[220:223], v[38:41]
	v_mfma_f32_16x16x32_bf16 v[30:33], v[156:159], v[220:223], v[30:33]
	v_mfma_f32_16x16x32_bf16 v[22:25], v[148:151], v[228:231], v[22:25]
	v_mfma_f32_16x16x32_bf16 v[14:17], v[156:159], v[228:231], v[14:17]
	v_mfma_f32_16x16x32_bf16 v[50:53], v[160:163], v[190:193], v[50:53]
	v_mfma_f32_16x16x32_bf16 v[42:45], v[168:171], v[190:193], v[42:45]
	v_mfma_f32_16x16x32_bf16 v[34:37], v[160:163], v[198:201], v[34:37]
	v_mfma_f32_16x16x32_bf16 v[26:29], v[168:171], v[198:201], v[26:29]
	v_mfma_f32_16x16x32_bf16 v[18:21], v[160:163], v[216:219], v[18:21]
	v_mfma_f32_16x16x32_bf16 v[10:13], v[168:171], v[216:219], v[10:13]
	v_mfma_f32_16x16x32_bf16 v[6:9], v[160:163], v[224:227], v[6:9]
	v_mfma_f32_16x16x32_bf16 v[2:5], v[168:171], v[224:227], v[2:5]
	v_mfma_f32_16x16x32_bf16 v[50:53], v[164:167], v[194:197], v[50:53]
	v_mfma_f32_16x16x32_bf16 v[42:45], v[172:175], v[194:197], v[42:45]
	v_mfma_f32_16x16x32_bf16 v[34:37], v[164:167], v[212:215], v[34:37]
	v_mfma_f32_16x16x32_bf16 v[26:29], v[172:175], v[212:215], v[26:29]
	v_mfma_f32_16x16x32_bf16 v[18:21], v[164:167], v[220:223], v[18:21]
	v_mfma_f32_16x16x32_bf16 v[10:13], v[172:175], v[220:223], v[10:13]
	v_mfma_f32_16x16x32_bf16 v[6:9], v[164:167], v[228:231], v[6:9]
	v_mfma_f32_16x16x32_bf16 v[2:5], v[172:175], v[228:231], v[2:5]
	s_barrier
; #define PG8_STAGE(bufoff, gbase, voff) do { _Pragma("unroll") for (int _i = 0; _i < 2; ++_i) \
;         __builtin_amdgcn_global_load_lds((const unsigned*)((const char*)(gbase) + (voff)[_i]), (PG8_LAS unsigned*)(lds + (bufoff) + ldsw + _i * 8192), 16, 0, 0); } while (0)
; #define PG8_LDA(dst, b, h) do { _Pragma("unroll") for (int m = 0; m < 4; ++m) _Pragma("unroll") for (int k = 0; k < 2; ++k) dst[m][k] = *(const PG8_LAS bf16x8*)(lds + PG8_SA(b, h) + aoff + m * 2048 + k * 1024); } while (0)
; #define PG8_LDB(dst, b, h) do { _Pragma("unroll") for (int n = 0; n < 2; ++n) _Pragma("unroll") for (int k = 0; k < 2; ++k) dst[n][k] = *(const PG8_LAS bf16x8*)(lds + PG8_SB(b, h) + boff + n * 2048 + k * 1024); } while (0)
; #define PG8_MMA(ai, bj, At, Bt) do { __builtin_amdgcn_s_setprio(1); _Pragma("unroll") for (int m = 0; m < 4; ++m) _Pragma("unroll") for (int n = 0; n < 2; ++n) _Pragma("unroll") for (int k = 0; k < 2; ++k) \
;         acc[ai][bj][m][n] = __builtin_amdgcn_mfma_f32_16x16x32_bf16(Bt[n][k], At[m][k], acc[ai][bj][m][n], 0, 0, 0); __builtin_amdgcn_s_setprio(0); } while (0)
; #define PG8_WAIT_V(n) asm volatile("s_waitcnt vmcnt(" #n ")" ::: "memory")
; #define PG8_WAIT_L(n) asm volatile("s_waitcnt lgkmcnt(" #n ")" ::: "memory")
; #define PG8_BAR __builtin_amdgcn_s_barrier()
; #define PG8_SCHED __builtin_amdgcn_sched_barrier(0)
; template <class Epi, class Sched, bool ALIGN_EPI = false, bool SP2 = false>
; __device__ __forceinline__ void gemm_phase(PG8_LAS unsigned char* lds, const Gemm g, const Sched& S, const Epi& E, const int wid_in) {
;     ...
;             PG8_LDB(B0, 1, 0); PG8_LDB(B1, 1, 1); PG8_SCHED; PG8_LDA(At, 1, 0); PG8_STAGE(PG8_SA(0, 1), a2 + hstep, voffA);
;             PG8_WAIT_V(8); PG8_WAIT_L(0); PG8_BAR; PG8_MMA(0, 0, At, B0); PG8_MMA(0, 1, At, B1); PG8_BAR; PG8_SCHED;
	s_add_i32 s2, 0, 0x18000
	s_add_i32 s8, 0, 0x1c000
	v_add_u32_e32 v156, s2, v142
	v_add_u32_e32 v172, s8, v142
	ds_read_b128 v[144:147], v156
	ds_read_b128 v[148:151], v156 offset:1024
	ds_read_b128 v[152:155], v156 offset:2048
	ds_read_b128 v[156:159], v156 offset:3072
	ds_read_b128 v[160:163], v172
	ds_read_b128 v[164:167], v172 offset:1024
	ds_read_b128 v[168:171], v172 offset:2048
	ds_read_b128 v[172:175], v172 offset:3072
	s_add_u32 s22, s52, 0x40000
	s_addc_u32 s23, s53, 0
	s_mov_b32 m0, s12
	v_lshl_add_u64 v[236:237], s[22:23], 0, v[134:135]
	ds_read_b128 v[190:193], v143 offset:32768
	ds_read_b128 v[194:197], v143 offset:33792
	ds_read_b128 v[198:201], v143 offset:34816
	ds_read_b128 v[212:215], v143 offset:35840
	ds_read_b128 v[216:219], v143 offset:36864
	ds_read_b128 v[220:223], v143 offset:37888
	ds_read_b128 v[224:227], v143 offset:38912
	ds_read_b128 v[228:231], v143 offset:39936
	global_load_lds_dwordx4 v[236:237], off
	v_lshl_add_u64 v[236:237], s[22:23], 0, v[132:133]
	s_mov_b32 m0, s13
	s_nop 0
	global_load_lds_dwordx4 v[236:237], off
	s_waitcnt vmcnt(8)
	s_waitcnt lgkmcnt(0)
	s_barrier
	s_waitcnt lgkmcnt(0)
	v_mfma_f32_16x16x32_bf16 v[126:129], v[144:147], v[190:193], v[126:129]
	v_mfma_f32_16x16x32_bf16 v[122:125], v[152:155], v[190:193], v[122:125]
	v_mfma_f32_16x16x32_bf16 v[118:121], v[144:147], v[198:201], v[118:121]
	v_mfma_f32_16x16x32_bf16 v[110:113], v[152:155], v[198:201], v[110:113]
	v_mfma_f32_16x16x32_bf16 v[102:105], v[144:147], v[216:219], v[102:105]
	v_mfma_f32_16x16x32_bf16 v[94:97], v[152:155], v[216:219], v[94:97]
	v_mfma_f32_16x16x32_bf16 v[82:85], v[144:147], v[224:227], v[82:85]
	v_mfma_f32_16x16x32_bf16 v[74:77], v[152:155], v[224:227], v[74:77]
	v_mfma_f32_16x16x32_bf16 v[126:129], v[148:151], v[194:197], v[126:129]
	v_mfma_f32_16x16x32_bf16 v[122:125], v[156:159], v[194:197], v[122:125]
	v_mfma_f32_16x16x32_bf16 v[118:121], v[148:151], v[212:215], v[118:121]
	v_mfma_f32_16x16x32_bf16 v[110:113], v[156:159], v[212:215], v[110:113]
	v_mfma_f32_16x16x32_bf16 v[102:105], v[148:151], v[220:223], v[102:105]
	v_mfma_f32_16x16x32_bf16 v[94:97], v[156:159], v[220:223], v[94:97]
	v_mfma_f32_16x16x32_bf16 v[82:85], v[148:151], v[228:231], v[82:85]
	v_mfma_f32_16x16x32_bf16 v[74:77], v[156:159], v[228:231], v[74:77]
	v_mfma_f32_16x16x32_bf16 v[114:117], v[160:163], v[190:193], v[114:117]
	v_mfma_f32_16x16x32_bf16 v[106:109], v[168:171], v[190:193], v[106:109]
	v_mfma_f32_16x16x32_bf16 v[98:101], v[160:163], v[198:201], v[98:101]
	v_mfma_f32_16x16x32_bf16 v[90:93], v[168:171], v[198:201], v[90:93]
	v_mfma_f32_16x16x32_bf16 v[86:89], v[160:163], v[216:219], v[86:89]
	v_mfma_f32_16x16x32_bf16 v[78:81], v[168:171], v[216:219], v[78:81]
	v_mfma_f32_16x16x32_bf16 v[70:73], v[160:163], v[224:227], v[70:73]
	v_mfma_f32_16x16x32_bf16 v[66:69], v[168:171], v[224:227], v[66:69]
	v_mfma_f32_16x16x32_bf16 v[114:117], v[164:167], v[194:197], v[114:117]
	v_mfma_f32_16x16x32_bf16 v[106:109], v[172:175], v[194:197], v[106:109]
	v_mfma_f32_16x16x32_bf16 v[98:101], v[164:167], v[212:215], v[98:101]
	v_mfma_f32_16x16x32_bf16 v[90:93], v[172:175], v[212:215], v[90:93]
	v_mfma_f32_16x16x32_bf16 v[86:89], v[164:167], v[220:223], v[86:89]
	v_mfma_f32_16x16x32_bf16 v[78:81], v[172:175], v[220:223], v[78:81]
	v_mfma_f32_16x16x32_bf16 v[70:73], v[164:167], v[228:231], v[70:73]
	v_mfma_f32_16x16x32_bf16 v[66:69], v[172:175], v[228:231], v[66:69]
	s_barrier
; #define PG8_STAGE(bufoff, gbase, voff) do { _Pragma("unroll") for (int _i = 0; _i < 2; ++_i) \
;         __builtin_amdgcn_global_load_lds((const unsigned*)((const char*)(gbase) + (voff)[_i]), (PG8_LAS unsigned*)(lds + (bufoff) + ldsw + _i * 8192), 16, 0, 0); } while (0)
; #define PG8_LDA(dst, b, h) do { _Pragma("unroll") for (int m = 0; m < 4; ++m) _Pragma("unroll") for (int k = 0; k < 2; ++k) dst[m][k] = *(const PG8_LAS bf16x8*)(lds + PG8_SA(b, h) + aoff + m * 2048 + k * 1024); } while (0)
; #define PG8_MMA(ai, bj, At, Bt) do { __builtin_amdgcn_s_setprio(1); _Pragma("unroll") for (int m = 0; m < 4; ++m) _Pragma("unroll") for (int n = 0; n < 2; ++n) _Pragma("unroll") for (int k = 0; k < 2; ++k) \
;         acc[ai][bj][m][n] = __builtin_amdgcn_mfma_f32_16x16x32_bf16(Bt[n][k], At[m][k], acc[ai][bj][m][n], 0, 0, 0); __builtin_amdgcn_s_setprio(0); } while (0)
; #define PG8_WAIT_V(n) asm volatile("s_waitcnt vmcnt(" #n ")" ::: "memory")
; #define PG8_WAIT_L(n) asm volatile("s_waitcnt lgkmcnt(" #n ")" ::: "memory")
; #define PG8_BAR __builtin_amdgcn_s_barrier()
; #define PG8_SCHED __builtin_amdgcn_sched_barrier(0)
; template <class Epi, class Sched, bool ALIGN_EPI = false, bool SP2 = false>
; __device__ __forceinline__ void gemm_phase(PG8_LAS unsigned char* lds, const Gemm g, const Sched& S, const Epi& E, const int wid_in) {
;     ...
;             PG8_LDA(At, 1, 1); PG8_STAGE(PG8_SB(1, 0), b3, voffB); PG8_STAGE(PG8_SB(1, 1), b3 + hstep, voffB); PG8_STAGE(PG8_SA(1, 0), a3, voffA);
;             PG8_WAIT_V(8); PG8_WAIT_L(0); PG8_BAR; PG8_MMA(1, 0, At, B0); PG8_MMA(1, 1, At, B1); PG8_BAR; PG8_SCHED;
;     ...
;         }
;         if constexpr (ALIGN_EPI) { if (wr == 0) PG8_BAR; }
	s_add_i32 s2, s2, s3
	v_lshl_add_u64 v[140:141], v[140:141], 0, s[64:65]
	s_mov_b32 m0, s2
	ds_read_b128 v[190:193], v143 offset:49152
	ds_read_b128 v[194:197], v143 offset:50176
	ds_read_b128 v[198:201], v143 offset:51200
	ds_read_b128 v[212:215], v143 offset:52224
	ds_read_b128 v[216:219], v143 offset:53248
	ds_read_b128 v[220:223], v143 offset:54272
	ds_read_b128 v[224:227], v143 offset:55296
	ds_read_b128 v[228:231], v143 offset:56320
	global_load_lds_dwordx4 v[140:141], off
	s_add_i32 m0, s2, 0x2000
	s_add_u32 s22, s50, 0x40080
	v_lshl_add_u64 v[140:141], v[176:177], 0, s[64:65]
	s_addc_u32 s23, s51, 0
	s_add_i32 s2, s8, s3
	global_load_lds_dwordx4 v[140:141], off
	v_lshl_add_u64 v[140:141], s[22:23], 0, v[0:1]
	s_mov_b32 m0, s2
	s_nop 0
	global_load_lds_dwordx4 v[140:141], off
	v_lshl_add_u64 v[140:141], s[22:23], 0, v[130:131]
	s_add_i32 m0, s2, 0x2000
	s_nop 0
	global_load_lds_dwordx4 v[140:141], off
	v_lshl_add_u64 v[140:141], v[232:233], 0, s[64:65]
	s_mov_b32 m0, s36
	s_nop 0
	global_load_lds_dwordx4 v[140:141], off
	v_lshl_add_u64 v[140:141], v[234:235], 0, s[64:65]
	s_mov_b32 m0, s37
	s_nop 0
	global_load_lds_dwordx4 v[140:141], off
	s_waitcnt vmcnt(8)
	s_waitcnt lgkmcnt(0)
	s_barrier
	s_waitcnt lgkmcnt(0)
	v_mfma_f32_16x16x32_bf16 v[62:65], v[144:147], v[190:193], v[62:65]
	v_mfma_f32_16x16x32_bf16 v[58:61], v[152:155], v[190:193], v[58:61]
	v_mfma_f32_16x16x32_bf16 v[54:57], v[144:147], v[198:201], v[54:57]
	v_mfma_f32_16x16x32_bf16 v[46:49], v[152:155], v[198:201], v[46:49]
	v_mfma_f32_16x16x32_bf16 v[38:41], v[144:147], v[216:219], v[38:41]
	v_mfma_f32_16x16x32_bf16 v[30:33], v[152:155], v[216:219], v[30:33]
	v_mfma_f32_16x16x32_bf16 v[22:25], v[144:147], v[224:227], v[22:25]
	v_mfma_f32_16x16x32_bf16 v[14:17], v[152:155], v[224:227], v[14:17]
	v_mfma_f32_16x16x32_bf16 v[62:65], v[148:151], v[194:197], v[62:65]
	v_mfma_f32_16x16x32_bf16 v[58:61], v[156:159], v[194:197], v[58:61]
	v_mfma_f32_16x16x32_bf16 v[54:57], v[148:151], v[212:215], v[54:57]
	v_mfma_f32_16x16x32_bf16 v[46:49], v[156:159], v[212:215], v[46:49]
	v_mfma_f32_16x16x32_bf16 v[38:41], v[148:151], v[220:223], v[38:41]
	v_mfma_f32_16x16x32_bf16 v[30:33], v[156:159], v[220:223], v[30:33]
	v_mfma_f32_16x16x32_bf16 v[22:25], v[148:151], v[228:231], v[22:25]
	v_mfma_f32_16x16x32_bf16 v[14:17], v[156:159], v[228:231], v[14:17]
	v_mfma_f32_16x16x32_bf16 v[50:53], v[160:163], v[190:193], v[50:53]
	v_mfma_f32_16x16x32_bf16 v[42:45], v[168:171], v[190:193], v[42:45]
	v_mfma_f32_16x16x32_bf16 v[34:37], v[160:163], v[198:201], v[34:37]
	v_mfma_f32_16x16x32_bf16 v[26:29], v[168:171], v[198:201], v[26:29]
	v_mfma_f32_16x16x32_bf16 v[18:21], v[160:163], v[216:219], v[18:21]
	v_mfma_f32_16x16x32_bf16 v[10:13], v[168:171], v[216:219], v[10:13]
	v_mfma_f32_16x16x32_bf16 v[6:9], v[160:163], v[224:227], v[6:9]
	v_mfma_f32_16x16x32_bf16 v[2:5], v[168:171], v[224:227], v[2:5]
	v_mfma_f32_16x16x32_bf16 v[50:53], v[164:167], v[194:197], v[50:53]
	v_mfma_f32_16x16x32_bf16 v[42:45], v[172:175], v[194:197], v[42:45]
	v_mfma_f32_16x16x32_bf16 v[34:37], v[164:167], v[212:215], v[34:37]
	v_mfma_f32_16x16x32_bf16 v[26:29], v[172:175], v[212:215], v[26:29]
	v_mfma_f32_16x16x32_bf16 v[18:21], v[164:167], v[220:223], v[18:21]
	v_mfma_f32_16x16x32_bf16 v[10:13], v[172:175], v[220:223], v[10:13]
	v_mfma_f32_16x16x32_bf16 v[6:9], v[164:167], v[228:231], v[6:9]
	v_mfma_f32_16x16x32_bf16 v[2:5], v[172:175], v[228:231], v[2:5]
	s_barrier
	s_add_i32 s60, s60, 2
	s_add_u32 s48, s48, 0x100
	s_addc_u32 s49, s49, 0
	s_add_u32 s58, s58, 0x100
	s_addc_u32 s59, s59, 0
	s_cmp_gt_u32 s60, 13
	s_cbranch_scc0 .LBB0_537
	s_setprio 0
	v_readlane_b32 s8, v243, 63
	v_readlane_b32 s9, v242, 0
	s_and_b64 vcc, exec, s[8:9]
	s_cbranch_vccz .LBB0_540
	s_barrier

; #define PG8_STAGE(bufoff, gbase, voff) do { _Pragma("unroll") for (int _i = 0; _i < 2; ++_i) \
;         __builtin_amdgcn_global_load_lds((const unsigned*)((const char*)(gbase) + (voff)[_i]), (PG8_LAS unsigned*)(lds + (bufoff) + ldsw + _i * 8192), 16, 0, 0); } while (0)
; #define PG8_LDA(dst, b, h) do { _Pragma("unroll") for (int m = 0; m < 4; ++m) _Pragma("unroll") for (int k = 0; k < 2; ++k) dst[m][k] = *(const PG8_LAS bf16x8*)(lds + PG8_SA(b, h) + aoff + m * 2048 + k * 1024); } while (0)
; #define PG8_LDB(dst, b, h) do { _Pragma("unroll") for (int n = 0; n < 2; ++n) _Pragma("unroll") for (int k = 0; k < 2; ++k) dst[n][k] = *(const PG8_LAS bf16x8*)(lds + PG8_SB(b, h) + boff + n * 2048 + k * 1024); } while (0)
; #define PG8_MMA(ai, bj, At, Bt) do { __builtin_amdgcn_s_setprio(1); _Pragma("unroll") for (int m = 0; m < 4; ++m) _Pragma("unroll") for (int n = 0; n < 2; ++n) _Pragma("unroll") for (int k = 0; k < 2; ++k) \
;         acc[ai][bj][m][n] = __builtin_amdgcn_mfma_f32_16x16x32_bf16(Bt[n][k], At[m][k], acc[ai][bj][m][n], 0, 0, 0); __builtin_amdgcn_s_setprio(0); } while (0)
; template <class Epi, class Sched, bool ALIGN_EPI = false, bool SP2 = false>
; __device__ __forceinline__ void gemm_phase(PG8_LAS unsigned char* lds, const Gemm g, const Sched& S, const Epi& E, const int wid_in) {
;     ...
;         const bool has_next = S.next(ui + 1, nxt);
;         const char* nA = has_next ? (const char*)g.A + (size_t)nxt.pm * tstep : cA; const char* nB = has_next ? (const char*)g.Bt + (size_t)nxt.pn * tstep : cB;
; #pragma unroll 1
;         for (int t = 0; t < nt; t += 2) {
;             const bool last = (t == nt - 2);
;             const char* a1 = cA + (size_t)(t + 1) * kstep;
;             const char* a2 = last ? nA : cA + (size_t)(t + 2) * kstep; const char* b2 = last ? nB : cB + (size_t)(t + 2) * kstep;
;             const char* a3 = a2 + kstep; const char* b3 = b2 + kstep;
;             if (last && has_next) S.a_ready(nxt);
;             if constexpr (SP2) {
;             PG8_LDB(B0, 0, 0); PG8_LDB(B1, 0, 1); PG8_SCHED; PG8_LDA(At, 0, 0); PG8_STAGE(PG8_SA(1, 1), a1 + hstep, voffA);
;             PG8_WAIT_V(8); PG8_WAIT_L(0); PG8_BAR; PG8_MMA(0, 0, At, B0); PG8_MMA(0, 1, At, B1); PG8_BAR; PG8_SCHED;
;             PG8_LDA(At, 0, 1); PG8_STAGE(PG8_SB(0, 0), b2, voffB); PG8_STAGE(PG8_SB(0, 1), b2 + hstep, voffB); PG8_STAGE(PG8_SA(0, 0), a2, voffA);
.LBB0_704:
	s_ashr_i32 s61, s60, 31
	s_lshl_b64 s[22:23], s[60:61], 19
	v_readlane_b32 s8, v243, 52
	v_readlane_b32 s9, v243, 53
	s_add_u32 s38, s8, s22
	s_addc_u32 s39, s9, s23
	s_and_b64 s[22:23], s[40:41], exec
	s_cselect_b32 s48, s39, s43
	s_cselect_b32 s49, s38, s42
	s_ashr_i32 s59, s58, 31
	s_lshl_b64 s[22:23], s[58:59], 19
	v_readlane_b32 s2, v243, 24
	s_add_u32 s52, s2, s22
	v_readlane_b32 s2, v243, 25
	s_addc_u32 s53, s2, s23
	s_and_b64 s[22:23], s[40:41], exec
	s_cselect_b32 s16, s53, s45
	s_cselect_b32 s59, s52, s44
	s_add_u32 s42, s42, 0x40080
	s_addc_u32 s43, s43, 0
	s_add_u32 s61, s44, 0x100
	s_addc_u32 s62, s45, 0
	s_mov_b32 vcc_lo, -2
	v_readlane_b32 s100, v243, 63
	v_readlane_b32 s101, v242, 0
	s_cmp_lg_u64 s[100:101], 0
	s_cbranch_scc1 .Lprio_done_705
	s_setprio 1
.Lprio_done_705:
	s_add_u32 s2, s42, 0xfffc0080
	s_addc_u32 s8, s43, -1
	s_add_i32 s9, 0, 0x10000
	s_cmp_eq_u32 vcc_lo, 12
	s_cselect_b32 s47, s48, s8
	s_cselect_b32 s46, s49, s2
	s_cselect_b32 s45, s16, s62
	s_cselect_b32 s44, s59, s61
	s_add_i32 s2, 0, 0x14000
	v_add_u32_e32 v142, s9, v211
	v_add_u32_e32 v158, s2, v211
	ds_read_b128 v[130:133], v142
	ds_read_b128 v[134:137], v142 offset:1024
	ds_read_b128 v[138:141], v142 offset:2048
	ds_read_b128 v[142:145], v142 offset:3072
	ds_read_b128 v[146:149], v158
	ds_read_b128 v[150:153], v158 offset:1024
	ds_read_b128 v[154:157], v158 offset:2048
	ds_read_b128 v[158:161], v158 offset:3072
	v_lshl_add_u64 v[200:201], s[42:43], 0, v[196:197]
	s_add_i32 m0, s12, 0xc000
	ds_read_b128 v[162:165], v212
	ds_read_b128 v[166:169], v212 offset:1024
	ds_read_b128 v[170:173], v212 offset:2048
	ds_read_b128 v[174:177], v212 offset:3072
	ds_read_b128 v[214:217], v212 offset:4096
	ds_read_b128 v[218:221], v212 offset:5120
	ds_read_b128 v[222:225], v212 offset:6144
	ds_read_b128 v[226:229], v212 offset:7168
	global_load_lds_dwordx4 v[200:201], off
	v_lshl_add_u64 v[200:201], s[42:43], 0, v[198:199]
	s_add_i32 m0, s12, 0xe000
	s_nop 0
	global_load_lds_dwordx4 v[200:201], off
	s_waitcnt vmcnt(8)
	s_waitcnt lgkmcnt(0)
	s_barrier
	s_waitcnt lgkmcnt(0)
	v_mfma_f32_16x16x32_bf16 v[126:129], v[130:133], v[162:165], 0
	v_mfma_f32_16x16x32_bf16 v[94:97], v[138:141], v[162:165], 0
	v_mfma_f32_16x16x32_bf16 v[118:121], v[130:133], v[170:173], 0
	v_mfma_f32_16x16x32_bf16 v[86:89], v[138:141], v[170:173], 0
	v_mfma_f32_16x16x32_bf16 v[110:113], v[130:133], v[214:217], 0
	v_mfma_f32_16x16x32_bf16 v[78:81], v[138:141], v[214:217], 0
	v_mfma_f32_16x16x32_bf16 v[102:105], v[130:133], v[222:225], 0
	v_mfma_f32_16x16x32_bf16 v[70:73], v[138:141], v[222:225], 0
	v_mfma_f32_16x16x32_bf16 v[126:129], v[134:137], v[166:169], v[126:129]
	v_mfma_f32_16x16x32_bf16 v[94:97], v[142:145], v[166:169], v[94:97]
	v_mfma_f32_16x16x32_bf16 v[118:121], v[134:137], v[174:177], v[118:121]
	v_mfma_f32_16x16x32_bf16 v[86:89], v[142:145], v[174:177], v[86:89]
	v_mfma_f32_16x16x32_bf16 v[110:113], v[134:137], v[218:221], v[110:113]
	v_mfma_f32_16x16x32_bf16 v[78:81], v[142:145], v[218:221], v[78:81]
	v_mfma_f32_16x16x32_bf16 v[102:105], v[134:137], v[226:229], v[102:105]
	v_mfma_f32_16x16x32_bf16 v[70:73], v[142:145], v[226:229], v[70:73]
	v_mfma_f32_16x16x32_bf16 v[122:125], v[146:149], v[162:165], 0
	v_mfma_f32_16x16x32_bf16 v[90:93], v[154:157], v[162:165], 0
	v_mfma_f32_16x16x32_bf16 v[114:117], v[146:149], v[170:173], 0
	v_mfma_f32_16x16x32_bf16 v[82:85], v[154:157], v[170:173], 0
	v_mfma_f32_16x16x32_bf16 v[106:109], v[146:149], v[214:217], 0
	v_mfma_f32_16x16x32_bf16 v[74:77], v[154:157], v[214:217], 0
	v_mfma_f32_16x16x32_bf16 v[98:101], v[146:149], v[222:225], 0
	v_mfma_f32_16x16x32_bf16 v[66:69], v[154:157], v[222:225], 0
	v_mfma_f32_16x16x32_bf16 v[122:125], v[150:153], v[166:169], v[122:125]
	v_mfma_f32_16x16x32_bf16 v[90:93], v[158:161], v[166:169], v[90:93]
	v_mfma_f32_16x16x32_bf16 v[114:117], v[150:153], v[174:177], v[114:117]
	v_mfma_f32_16x16x32_bf16 v[82:85], v[158:161], v[174:177], v[82:85]
	v_mfma_f32_16x16x32_bf16 v[106:109], v[150:153], v[218:221], v[106:109]
	v_mfma_f32_16x16x32_bf16 v[74:77], v[158:161], v[218:221], v[74:77]
	v_mfma_f32_16x16x32_bf16 v[98:101], v[150:153], v[226:229], v[98:101]
	v_mfma_f32_16x16x32_bf16 v[66:69], v[158:161], v[226:229], v[66:69]
	s_barrier
	s_add_i32 s8, s9, s3
	v_lshl_add_u64 v[200:201], s[44:45], 0, v[0:1]
	s_mov_b32 m0, s8
	ds_read_b128 v[162:165], v212 offset:16384
	ds_read_b128 v[166:169], v212 offset:17408
	ds_read_b128 v[170:173], v212 offset:18432
	ds_read_b128 v[174:177], v212 offset:19456
	ds_read_b128 v[214:217], v212 offset:20480
	ds_read_b128 v[218:221], v212 offset:21504
	ds_read_b128 v[222:225], v212 offset:22528
	ds_read_b128 v[226:229], v212 offset:23552
	global_load_lds_dwordx4 v[200:201], off
	s_add_i32 m0, s8, 0x2000
	s_add_u32 s22, s44, 0x40000
	v_lshl_add_u64 v[230:231], s[44:45], 0, v[194:195]
	s_addc_u32 s23, s45, 0
	s_add_i32 s2, s2, s3
	global_load_lds_dwordx4 v[230:231], off
	v_lshl_add_u64 v[232:233], s[22:23], 0, v[0:1]
	s_mov_b32 m0, s2
	v_lshl_add_u64 v[234:235], s[46:47], 0, v[192:193]
	global_load_lds_dwordx4 v[232:233], off
	v_lshl_add_u64 v[232:233], s[22:23], 0, v[194:195]
	s_add_i32 m0, s2, 0x2000
	s_nop 0
	global_load_lds_dwordx4 v[232:233], off
	v_lshl_add_u64 v[232:233], s[46:47], 0, v[190:191]
	s_mov_b32 m0, s12
	s_nop 0
	global_load_lds_dwordx4 v[232:233], off
	s_mov_b32 m0, s13
	s_nop 0
	global_load_lds_dwordx4 v[234:235], off
	s_waitcnt vmcnt(8)
	s_waitcnt lgkmcnt(0)
	s_barrier
; #define PG8_STAGE(bufoff, gbase, voff) do { _Pragma("unroll") for (int _i = 0; _i < 2; ++_i) \
;         __builtin_amdgcn_global_load_lds((const unsigned*)((const char*)(gbase) + (voff)[_i]), (PG8_LAS unsigned*)(lds + (bufoff) + ldsw + _i * 8192), 16, 0, 0); } while (0)
; #define PG8_LDA(dst, b, h) do { _Pragma("unroll") for (int m = 0; m < 4; ++m) _Pragma("unroll") for (int k = 0; k < 2; ++k) dst[m][k] = *(const PG8_LAS bf16x8*)(lds + PG8_SA(b, h) + aoff + m * 2048 + k * 1024); } while (0)
; #define PG8_LDB(dst, b, h) do { _Pragma("unroll") for (int n = 0; n < 2; ++n) _Pragma("unroll") for (int k = 0; k < 2; ++k) dst[n][k] = *(const PG8_LAS bf16x8*)(lds + PG8_SB(b, h) + boff + n * 2048 + k * 1024); } while (0)
; #define PG8_MMA(ai, bj, At, Bt) do { __builtin_amdgcn_s_setprio(1); _Pragma("unroll") for (int m = 0; m < 4; ++m) _Pragma("unroll") for (int n = 0; n < 2; ++n) _Pragma("unroll") for (int k = 0; k < 2; ++k) \
;         acc[ai][bj][m][n] = __builtin_amdgcn_mfma_f32_16x16x32_bf16(Bt[n][k], At[m][k], acc[ai][bj][m][n], 0, 0, 0); __builtin_amdgcn_s_setprio(0); } while (0)
; #define PG8_WAIT_V(n) asm volatile("s_waitcnt vmcnt(" #n ")" ::: "memory")
; #define PG8_WAIT_L(n) asm volatile("s_waitcnt lgkmcnt(" #n ")" ::: "memory")
; #define PG8_BAR __builtin_amdgcn_s_barrier()
; #define PG8_SCHED __builtin_amdgcn_sched_barrier(0)
; template <class Epi, class Sched, bool ALIGN_EPI = false, bool SP2 = false>
; __device__ __forceinline__ void gemm_phase(PG8_LAS unsigned char* lds, const Gemm g, const Sched& S, const Epi& E, const int wid_in) {
;     ...
;             PG8_WAIT_V(8); PG8_WAIT_L(0); PG8_BAR; PG8_MMA(0, 0, At, B0); PG8_MMA(0, 1, At, B1); PG8_BAR; PG8_SCHED;
;             PG8_LDA(At, 0, 1); PG8_STAGE(PG8_SB(0, 0), b2, voffB); PG8_STAGE(PG8_SB(0, 1), b2 + hstep, voffB); PG8_STAGE(PG8_SA(0, 0), a2, voffA);
;             PG8_WAIT_V(8); PG8_WAIT_L(0); PG8_BAR; PG8_MMA(1, 0, At, B0); PG8_MMA(1, 1, At, B1); PG8_BAR; PG8_SCHED;
;             PG8_LDB(B0, 1, 0); PG8_LDB(B1, 1, 1); PG8_SCHED; PG8_LDA(At, 1, 0); PG8_STAGE(PG8_SA(0, 1), a2 + hstep, voffA);
;             PG8_WAIT_V(8); PG8_WAIT_L(0); PG8_BAR; PG8_MMA(0, 0, At, B0); PG8_MMA(0, 1, At, B1); PG8_BAR; PG8_SCHED;
	s_waitcnt lgkmcnt(0)
	v_mfma_f32_16x16x32_bf16 v[62:65], v[130:133], v[162:165], 0
	v_mfma_f32_16x16x32_bf16 v[30:33], v[138:141], v[162:165], 0
	v_mfma_f32_16x16x32_bf16 v[54:57], v[130:133], v[170:173], 0
	v_mfma_f32_16x16x32_bf16 v[22:25], v[138:141], v[170:173], 0
	v_mfma_f32_16x16x32_bf16 v[46:49], v[130:133], v[214:217], 0
	v_mfma_f32_16x16x32_bf16 v[14:17], v[138:141], v[214:217], 0
	v_mfma_f32_16x16x32_bf16 v[38:41], v[130:133], v[222:225], 0
	v_mfma_f32_16x16x32_bf16 v[6:9], v[138:141], v[222:225], 0
	v_mfma_f32_16x16x32_bf16 v[62:65], v[134:137], v[166:169], v[62:65]
	v_mfma_f32_16x16x32_bf16 v[30:33], v[142:145], v[166:169], v[30:33]
	v_mfma_f32_16x16x32_bf16 v[54:57], v[134:137], v[174:177], v[54:57]
	v_mfma_f32_16x16x32_bf16 v[22:25], v[142:145], v[174:177], v[22:25]
	v_mfma_f32_16x16x32_bf16 v[46:49], v[134:137], v[218:221], v[46:49]
	v_mfma_f32_16x16x32_bf16 v[14:17], v[142:145], v[218:221], v[14:17]
	v_mfma_f32_16x16x32_bf16 v[38:41], v[134:137], v[226:229], v[38:41]
	v_mfma_f32_16x16x32_bf16 v[6:9], v[142:145], v[226:229], v[6:9]
	v_mfma_f32_16x16x32_bf16 v[58:61], v[146:149], v[162:165], 0
	v_mfma_f32_16x16x32_bf16 v[26:29], v[154:157], v[162:165], 0
	v_mfma_f32_16x16x32_bf16 v[50:53], v[146:149], v[170:173], 0
	v_mfma_f32_16x16x32_bf16 v[18:21], v[154:157], v[170:173], 0
	v_mfma_f32_16x16x32_bf16 v[42:45], v[146:149], v[214:217], 0
	v_mfma_f32_16x16x32_bf16 v[10:13], v[154:157], v[214:217], 0
	v_mfma_f32_16x16x32_bf16 v[34:37], v[146:149], v[222:225], 0
	v_mfma_f32_16x16x32_bf16 v[2:5], v[154:157], v[222:225], 0
	v_mfma_f32_16x16x32_bf16 v[58:61], v[150:153], v[166:169], v[58:61]
	v_mfma_f32_16x16x32_bf16 v[26:29], v[158:161], v[166:169], v[26:29]
	v_mfma_f32_16x16x32_bf16 v[50:53], v[150:153], v[174:177], v[50:53]
	v_mfma_f32_16x16x32_bf16 v[18:21], v[158:161], v[174:177], v[18:21]
	v_mfma_f32_16x16x32_bf16 v[42:45], v[150:153], v[218:221], v[42:45]
	v_mfma_f32_16x16x32_bf16 v[10:13], v[158:161], v[218:221], v[10:13]
	v_mfma_f32_16x16x32_bf16 v[34:37], v[150:153], v[226:229], v[34:37]
	v_mfma_f32_16x16x32_bf16 v[2:5], v[158:161], v[226:229], v[2:5]
	s_barrier
	s_add_i32 s2, 0, 0x18000
	s_add_i32 s8, 0, 0x1c000
	v_add_u32_e32 v142, s2, v211
	v_add_u32_e32 v158, s8, v211
	ds_read_b128 v[130:133], v142
	ds_read_b128 v[134:137], v142 offset:1024
	ds_read_b128 v[138:141], v142 offset:2048
	ds_read_b128 v[142:145], v142 offset:3072
	ds_read_b128 v[146:149], v158
	ds_read_b128 v[150:153], v158 offset:1024
	ds_read_b128 v[154:157], v158 offset:2048
	ds_read_b128 v[158:161], v158 offset:3072
	s_add_u32 s22, s46, 0x40000
	s_addc_u32 s23, s47, 0
	s_mov_b32 m0, s36
	v_lshl_add_u64 v[236:237], s[22:23], 0, v[190:191]
	ds_read_b128 v[162:165], v212 offset:32768
	ds_read_b128 v[166:169], v212 offset:33792
	ds_read_b128 v[170:173], v212 offset:34816
	ds_read_b128 v[174:177], v212 offset:35840
	ds_read_b128 v[214:217], v212 offset:36864
	ds_read_b128 v[218:221], v212 offset:37888
	ds_read_b128 v[222:225], v212 offset:38912
	ds_read_b128 v[226:229], v212 offset:39936
	global_load_lds_dwordx4 v[236:237], off
	v_lshl_add_u64 v[236:237], s[22:23], 0, v[192:193]
	s_mov_b32 m0, s37
	s_nop 0
	global_load_lds_dwordx4 v[236:237], off
	s_waitcnt vmcnt(8)
	s_waitcnt lgkmcnt(0)
	s_barrier
	s_waitcnt lgkmcnt(0)
	v_mfma_f32_16x16x32_bf16 v[126:129], v[130:133], v[162:165], v[126:129]
	v_mfma_f32_16x16x32_bf16 v[94:97], v[138:141], v[162:165], v[94:97]
	v_mfma_f32_16x16x32_bf16 v[118:121], v[130:133], v[170:173], v[118:121]
	v_mfma_f32_16x16x32_bf16 v[86:89], v[138:141], v[170:173], v[86:89]
	v_mfma_f32_16x16x32_bf16 v[110:113], v[130:133], v[214:217], v[110:113]
	v_mfma_f32_16x16x32_bf16 v[78:81], v[138:141], v[214:217], v[78:81]
	v_mfma_f32_16x16x32_bf16 v[102:105], v[130:133], v[222:225], v[102:105]
	v_mfma_f32_16x16x32_bf16 v[70:73], v[138:141], v[222:225], v[70:73]
	v_mfma_f32_16x16x32_bf16 v[126:129], v[134:137], v[166:169], v[126:129]
	v_mfma_f32_16x16x32_bf16 v[94:97], v[142:145], v[166:169], v[94:97]
	v_mfma_f32_16x16x32_bf16 v[118:121], v[134:137], v[174:177], v[118:121]
	v_mfma_f32_16x16x32_bf16 v[86:89], v[142:145], v[174:177], v[86:89]
	v_mfma_f32_16x16x32_bf16 v[110:113], v[134:137], v[218:221], v[110:113]
	v_mfma_f32_16x16x32_bf16 v[78:81], v[142:145], v[218:221], v[78:81]
	v_mfma_f32_16x16x32_bf16 v[102:105], v[134:137], v[226:229], v[102:105]
	v_mfma_f32_16x16x32_bf16 v[70:73], v[142:145], v[226:229], v[70:73]
	v_mfma_f32_16x16x32_bf16 v[122:125], v[146:149], v[162:165], v[122:125]
	v_mfma_f32_16x16x32_bf16 v[90:93], v[154:157], v[162:165], v[90:93]
	v_mfma_f32_16x16x32_bf16 v[114:117], v[146:149], v[170:173], v[114:117]
	v_mfma_f32_16x16x32_bf16 v[82:85], v[154:157], v[170:173], v[82:85]
	v_mfma_f32_16x16x32_bf16 v[106:109], v[146:149], v[214:217], v[106:109]
	v_mfma_f32_16x16x32_bf16 v[74:77], v[154:157], v[214:217], v[74:77]
	v_mfma_f32_16x16x32_bf16 v[98:101], v[146:149], v[222:225], v[98:101]
	v_mfma_f32_16x16x32_bf16 v[66:69], v[154:157], v[222:225], v[66:69]
	v_mfma_f32_16x16x32_bf16 v[122:125], v[150:153], v[166:169], v[122:125]
	v_mfma_f32_16x16x32_bf16 v[90:93], v[158:161], v[166:169], v[90:93]
	v_mfma_f32_16x16x32_bf16 v[114:117], v[150:153], v[174:177], v[114:117]
	v_mfma_f32_16x16x32_bf16 v[82:85], v[158:161], v[174:177], v[82:85]
	v_mfma_f32_16x16x32_bf16 v[106:109], v[150:153], v[218:221], v[106:109]
	v_mfma_f32_16x16x32_bf16 v[74:77], v[158:161], v[218:221], v[74:77]
	v_mfma_f32_16x16x32_bf16 v[98:101], v[150:153], v[226:229], v[98:101]
	v_mfma_f32_16x16x32_bf16 v[66:69], v[158:161], v[226:229], v[66:69]
	s_barrier
; #define PG8_STAGE(bufoff, gbase, voff) do { _Pragma("unroll") for (int _i = 0; _i < 2; ++_i) \
;         __builtin_amdgcn_global_load_lds((const unsigned*)((const char*)(gbase) + (voff)[_i]), (PG8_LAS unsigned*)(lds + (bufoff) + ldsw + _i * 8192), 16, 0, 0); } while (0)
; #define PG8_LDA(dst, b, h) do { _Pragma("unroll") for (int m = 0; m < 4; ++m) _Pragma("unroll") for (int k = 0; k < 2; ++k) dst[m][k] = *(const PG8_LAS bf16x8*)(lds + PG8_SA(b, h) + aoff + m * 2048 + k * 1024); } while (0)
; #define PG8_LDB(dst, b, h) do { _Pragma("unroll") for (int n = 0; n < 2; ++n) _Pragma("unroll") for (int k = 0; k < 2; ++k) dst[n][k] = *(const PG8_LAS bf16x8*)(lds + PG8_SB(b, h) + boff + n * 2048 + k * 1024); } while (0)
; #define PG8_WAIT_V(n) asm volatile("s_waitcnt vmcnt(" #n ")" ::: "memory")
; template <class Epi, class Sched, bool ALIGN_EPI = false, bool SP2 = false>
; __device__ __forceinline__ void gemm_phase(PG8_LAS unsigned char* lds, const Gemm g, const Sched& S, const Epi& E, const int wid_in) {
;     ...
;         for (int t = 0; t < nt; t += 2) {
;             const bool last = (t == nt - 2);
;             const char* a1 = cA + (size_t)(t + 1) * kstep;
;             const char* a2 = last ? nA : cA + (size_t)(t + 2) * kstep; const char* b2 = last ? nB : cB + (size_t)(t + 2) * kstep;
;             const char* a3 = a2 + kstep; const char* b3 = b2 + kstep;
;             if (last && has_next) S.a_ready(nxt);
;             if constexpr (SP2) {
;             PG8_LDB(B0, 0, 0); PG8_LDB(B1, 0, 1); PG8_SCHED; PG8_LDA(At, 0, 0); PG8_STAGE(PG8_SA(1, 1), a1 + hstep, voffA);
;             PG8_WAIT_V(8); PG8_WAIT_L(0); PG8_BAR; PG8_MMA(0, 0, At, B0); PG8_MMA(0, 1, At, B1); PG8_BAR; PG8_SCHED;
;             PG8_LDA(At, 0, 1); PG8_STAGE(PG8_SB(0, 0), b2, voffB); PG8_STAGE(PG8_SB(0, 1), b2 + hstep, voffB); PG8_STAGE(PG8_SA(0, 0), a2, voffA);
;             PG8_WAIT_V(8); PG8_WAIT_L(0); PG8_BAR; PG8_MMA(1, 0, At, B0); PG8_MMA(1, 1, At, B1); PG8_BAR; PG8_SCHED;
;             PG8_LDB(B0, 1, 0); PG8_LDB(B1, 1, 1); PG8_SCHED; PG8_LDA(At, 1, 0); PG8_STAGE(PG8_SA(0, 1), a2 + hstep, voffA);
;             PG8_WAIT_V(8); PG8_WAIT_L(0); PG8_BAR; PG8_MMA(0, 0, At, B0); PG8_MMA(0, 1, At, B1); PG8_BAR; PG8_SCHED;
;             PG8_LDA(At, 1, 1); PG8_STAGE(PG8_SB(1, 0), b3, voffB); PG8_STAGE(PG8_SB(1, 1), b3 + hstep, voffB); PG8_STAGE(PG8_SA(1, 0), a3, voffA);
	s_add_i32 s2, s2, s3
	v_lshl_add_u64 v[200:201], v[200:201], 0, s[64:65]
	s_mov_b32 m0, s2
	ds_read_b128 v[162:165], v212 offset:49152
	ds_read_b128 v[166:169], v212 offset:50176
	ds_read_b128 v[170:173], v212 offset:51200
	ds_read_b128 v[174:177], v212 offset:52224
	ds_read_b128 v[214:217], v212 offset:53248
	ds_read_b128 v[218:221], v212 offset:54272
	ds_read_b128 v[222:225], v212 offset:55296
	ds_read_b128 v[226:229], v212 offset:56320
	global_load_lds_dwordx4 v[200:201], off
	s_add_i32 m0, s2, 0x2000
	s_add_u32 s22, s44, 0x40080
	v_lshl_add_u64 v[200:201], v[230:231], 0, s[64:65]
	s_addc_u32 s23, s45, 0
	s_add_i32 s2, s8, s3
	global_load_lds_dwordx4 v[200:201], off
	v_lshl_add_u64 v[200:201], s[22:23], 0, v[0:1]
	s_mov_b32 m0, s2
	s_nop 0
	global_load_lds_dwordx4 v[200:201], off
	v_lshl_add_u64 v[200:201], s[22:23], 0, v[194:195]
	s_add_i32 m0, s2, 0x2000
	s_nop 0
	global_load_lds_dwordx4 v[200:201], off
	v_lshl_add_u64 v[200:201], v[232:233], 0, s[64:65]
	s_mov_b32 m0, s78
	s_nop 0
	global_load_lds_dwordx4 v[200:201], off
	v_lshl_add_u64 v[200:201], v[234:235], 0, s[64:65]
	s_mov_b32 m0, s79
	s_nop 0
	global_load_lds_dwordx4 v[200:201], off
	s_waitcnt vmcnt(8)
	s_waitcnt lgkmcnt(0)
	s_barrier
	s_waitcnt lgkmcnt(0)
	v_mfma_f32_16x16x32_bf16 v[62:65], v[130:133], v[162:165], v[62:65]
	v_mfma_f32_16x16x32_bf16 v[30:33], v[138:141], v[162:165], v[30:33]
	v_mfma_f32_16x16x32_bf16 v[54:57], v[130:133], v[170:173], v[54:57]
	v_mfma_f32_16x16x32_bf16 v[22:25], v[138:141], v[170:173], v[22:25]
	v_mfma_f32_16x16x32_bf16 v[46:49], v[130:133], v[214:217], v[46:49]
	v_mfma_f32_16x16x32_bf16 v[14:17], v[138:141], v[214:217], v[14:17]
	v_mfma_f32_16x16x32_bf16 v[38:41], v[130:133], v[222:225], v[38:41]
	v_mfma_f32_16x16x32_bf16 v[6:9], v[138:141], v[222:225], v[6:9]
	v_mfma_f32_16x16x32_bf16 v[62:65], v[134:137], v[166:169], v[62:65]
	v_mfma_f32_16x16x32_bf16 v[30:33], v[142:145], v[166:169], v[30:33]
	v_mfma_f32_16x16x32_bf16 v[54:57], v[134:137], v[174:177], v[54:57]
	v_mfma_f32_16x16x32_bf16 v[22:25], v[142:145], v[174:177], v[22:25]
	v_mfma_f32_16x16x32_bf16 v[46:49], v[134:137], v[218:221], v[46:49]
	v_mfma_f32_16x16x32_bf16 v[14:17], v[142:145], v[218:221], v[14:17]
	v_mfma_f32_16x16x32_bf16 v[38:41], v[134:137], v[226:229], v[38:41]
	v_mfma_f32_16x16x32_bf16 v[6:9], v[142:145], v[226:229], v[6:9]
	v_mfma_f32_16x16x32_bf16 v[58:61], v[146:149], v[162:165], v[58:61]
	v_mfma_f32_16x16x32_bf16 v[26:29], v[154:157], v[162:165], v[26:29]
	v_mfma_f32_16x16x32_bf16 v[50:53], v[146:149], v[170:173], v[50:53]
	v_mfma_f32_16x16x32_bf16 v[18:21], v[154:157], v[170:173], v[18:21]
	v_mfma_f32_16x16x32_bf16 v[42:45], v[146:149], v[214:217], v[42:45]
	v_mfma_f32_16x16x32_bf16 v[10:13], v[154:157], v[214:217], v[10:13]
	v_mfma_f32_16x16x32_bf16 v[34:37], v[146:149], v[222:225], v[34:37]
	v_mfma_f32_16x16x32_bf16 v[2:5], v[154:157], v[222:225], v[2:5]
	v_mfma_f32_16x16x32_bf16 v[58:61], v[150:153], v[166:169], v[58:61]
	v_mfma_f32_16x16x32_bf16 v[26:29], v[158:161], v[166:169], v[26:29]
	v_mfma_f32_16x16x32_bf16 v[50:53], v[150:153], v[174:177], v[50:53]
	v_mfma_f32_16x16x32_bf16 v[18:21], v[158:161], v[174:177], v[18:21]
	v_mfma_f32_16x16x32_bf16 v[42:45], v[150:153], v[218:221], v[42:45]
	v_mfma_f32_16x16x32_bf16 v[10:13], v[158:161], v[218:221], v[10:13]
	v_mfma_f32_16x16x32_bf16 v[34:37], v[150:153], v[226:229], v[34:37]
	v_mfma_f32_16x16x32_bf16 v[2:5], v[158:161], v[226:229], v[2:5]
	s_barrier
	s_add_i32 vcc_lo, vcc_lo, 2
	s_add_u32 s42, s42, 0x100
	s_addc_u32 s43, s43, 0
	s_add_u32 s61, s61, 0x100
	s_addc_u32 s62, s62, 0
	s_cmp_gt_u32 vcc_lo, 13
.LBB0_705:
	s_add_u32 s2, s42, 0xfffc0080
	s_addc_u32 s8, s43, -1
	s_add_i32 s9, 0, 0x10000
	s_cmp_eq_u32 vcc_lo, 12
	s_cselect_b32 s47, s48, s8
	s_cselect_b32 s46, s49, s2
	s_cselect_b32 s45, s16, s62
	s_cselect_b32 s44, s59, s61
	s_add_i32 s2, 0, 0x14000
	v_add_u32_e32 v142, s9, v211
	v_add_u32_e32 v158, s2, v211
	ds_read_b128 v[130:133], v142
	ds_read_b128 v[134:137], v142 offset:1024
	ds_read_b128 v[138:141], v142 offset:2048
	ds_read_b128 v[142:145], v142 offset:3072
	ds_read_b128 v[146:149], v158
	ds_read_b128 v[150:153], v158 offset:1024
	ds_read_b128 v[154:157], v158 offset:2048
	ds_read_b128 v[158:161], v158 offset:3072
	v_lshl_add_u64 v[200:201], s[42:43], 0, v[196:197]
	s_add_i32 m0, s12, 0xc000
	ds_read_b128 v[162:165], v212
	ds_read_b128 v[166:169], v212 offset:1024
	ds_read_b128 v[170:173], v212 offset:2048
	ds_read_b128 v[174:177], v212 offset:3072
	ds_read_b128 v[214:217], v212 offset:4096
	ds_read_b128 v[218:221], v212 offset:5120
	ds_read_b128 v[222:225], v212 offset:6144
	ds_read_b128 v[226:229], v212 offset:7168
	global_load_lds_dwordx4 v[200:201], off
	v_lshl_add_u64 v[200:201], s[42:43], 0, v[198:199]
	s_add_i32 m0, s12, 0xe000
	s_nop 0
	global_load_lds_dwordx4 v[200:201], off
	s_waitcnt vmcnt(8)
	s_waitcnt lgkmcnt(0)
	s_barrier
; #define PG8_STAGE(bufoff, gbase, voff) do { _Pragma("unroll") for (int _i = 0; _i < 2; ++_i) \
;         __builtin_amdgcn_global_load_lds((const unsigned*)((const char*)(gbase) + (voff)[_i]), (PG8_LAS unsigned*)(lds + (bufoff) + ldsw + _i * 8192), 16, 0, 0); } while (0)
; #define PG8_LDA(dst, b, h) do { _Pragma("unroll") for (int m = 0; m < 4; ++m) _Pragma("unroll") for (int k = 0; k < 2; ++k) dst[m][k] = *(const PG8_LAS bf16x8*)(lds + PG8_SA(b, h) + aoff + m * 2048 + k * 1024); } while (0)
; #define PG8_LDB(dst, b, h) do { _Pragma("unroll") for (int n = 0; n < 2; ++n) _Pragma("unroll") for (int k = 0; k < 2; ++k) dst[n][k] = *(const PG8_LAS bf16x8*)(lds + PG8_SB(b, h) + boff + n * 2048 + k * 1024); } while (0)
; #define PG8_MMA(ai, bj, At, Bt) do { __builtin_amdgcn_s_setprio(1); _Pragma("unroll") for (int m = 0; m < 4; ++m) _Pragma("unroll") for (int n = 0; n < 2; ++n) _Pragma("unroll") for (int k = 0; k < 2; ++k) \
;         acc[ai][bj][m][n] = __builtin_amdgcn_mfma_f32_16x16x32_bf16(Bt[n][k], At[m][k], acc[ai][bj][m][n], 0, 0, 0); __builtin_amdgcn_s_setprio(0); } while (0)
; #define PG8_WAIT_V(n) asm volatile("s_waitcnt vmcnt(" #n ")" ::: "memory")
; #define PG8_WAIT_L(n) asm volatile("s_waitcnt lgkmcnt(" #n ")" ::: "memory")
; #define PG8_BAR __builtin_amdgcn_s_barrier()
; #define PG8_SCHED __builtin_amdgcn_sched_barrier(0)
; template <class Epi, class Sched, bool ALIGN_EPI = false, bool SP2 = false>
; __device__ __forceinline__ void gemm_phase(PG8_LAS unsigned char* lds, const Gemm g, const Sched& S, const Epi& E, const int wid_in) {
;     ...
;             PG8_LDB(B0, 0, 0); PG8_LDB(B1, 0, 1); PG8_SCHED; PG8_LDA(At, 0, 0); PG8_STAGE(PG8_SA(1, 1), a1 + hstep, voffA);
;             PG8_WAIT_V(8); PG8_WAIT_L(0); PG8_BAR; PG8_MMA(0, 0, At, B0); PG8_MMA(0, 1, At, B1); PG8_BAR; PG8_SCHED;
;             PG8_LDA(At, 0, 1); PG8_STAGE(PG8_SB(0, 0), b2, voffB); PG8_STAGE(PG8_SB(0, 1), b2 + hstep, voffB); PG8_STAGE(PG8_SA(0, 0), a2, voffA);
;             PG8_WAIT_V(8); PG8_WAIT_L(0); PG8_BAR; PG8_MMA(1, 0, At, B0); PG8_MMA(1, 1, At, B1); PG8_BAR; PG8_SCHED;
	s_waitcnt lgkmcnt(0)
	v_mfma_f32_16x16x32_bf16 v[126:129], v[130:133], v[162:165], v[126:129]
	v_mfma_f32_16x16x32_bf16 v[94:97], v[138:141], v[162:165], v[94:97]
	v_mfma_f32_16x16x32_bf16 v[118:121], v[130:133], v[170:173], v[118:121]
	v_mfma_f32_16x16x32_bf16 v[86:89], v[138:141], v[170:173], v[86:89]
	v_mfma_f32_16x16x32_bf16 v[110:113], v[130:133], v[214:217], v[110:113]
	v_mfma_f32_16x16x32_bf16 v[78:81], v[138:141], v[214:217], v[78:81]
	v_mfma_f32_16x16x32_bf16 v[102:105], v[130:133], v[222:225], v[102:105]
	v_mfma_f32_16x16x32_bf16 v[70:73], v[138:141], v[222:225], v[70:73]
	v_mfma_f32_16x16x32_bf16 v[126:129], v[134:137], v[166:169], v[126:129]
	v_mfma_f32_16x16x32_bf16 v[94:97], v[142:145], v[166:169], v[94:97]
	v_mfma_f32_16x16x32_bf16 v[118:121], v[134:137], v[174:177], v[118:121]
	v_mfma_f32_16x16x32_bf16 v[86:89], v[142:145], v[174:177], v[86:89]
	v_mfma_f32_16x16x32_bf16 v[110:113], v[134:137], v[218:221], v[110:113]
	v_mfma_f32_16x16x32_bf16 v[78:81], v[142:145], v[218:221], v[78:81]
	v_mfma_f32_16x16x32_bf16 v[102:105], v[134:137], v[226:229], v[102:105]
	v_mfma_f32_16x16x32_bf16 v[70:73], v[142:145], v[226:229], v[70:73]
	v_mfma_f32_16x16x32_bf16 v[122:125], v[146:149], v[162:165], v[122:125]
	v_mfma_f32_16x16x32_bf16 v[90:93], v[154:157], v[162:165], v[90:93]
	v_mfma_f32_16x16x32_bf16 v[114:117], v[146:149], v[170:173], v[114:117]
	v_mfma_f32_16x16x32_bf16 v[82:85], v[154:157], v[170:173], v[82:85]
	v_mfma_f32_16x16x32_bf16 v[106:109], v[146:149], v[214:217], v[106:109]
	v_mfma_f32_16x16x32_bf16 v[74:77], v[154:157], v[214:217], v[74:77]
	v_mfma_f32_16x16x32_bf16 v[98:101], v[146:149], v[222:225], v[98:101]
	v_mfma_f32_16x16x32_bf16 v[66:69], v[154:157], v[222:225], v[66:69]
	v_mfma_f32_16x16x32_bf16 v[122:125], v[150:153], v[166:169], v[122:125]
	v_mfma_f32_16x16x32_bf16 v[90:93], v[158:161], v[166:169], v[90:93]
	v_mfma_f32_16x16x32_bf16 v[114:117], v[150:153], v[174:177], v[114:117]
	v_mfma_f32_16x16x32_bf16 v[82:85], v[158:161], v[174:177], v[82:85]
	v_mfma_f32_16x16x32_bf16 v[106:109], v[150:153], v[218:221], v[106:109]
	v_mfma_f32_16x16x32_bf16 v[74:77], v[158:161], v[218:221], v[74:77]
	v_mfma_f32_16x16x32_bf16 v[98:101], v[150:153], v[226:229], v[98:101]
	v_mfma_f32_16x16x32_bf16 v[66:69], v[158:161], v[226:229], v[66:69]
	s_barrier
	s_add_i32 s8, s9, s3
	v_lshl_add_u64 v[200:201], s[44:45], 0, v[0:1]
	s_mov_b32 m0, s8
	ds_read_b128 v[162:165], v212 offset:16384
	ds_read_b128 v[166:169], v212 offset:17408
	ds_read_b128 v[170:173], v212 offset:18432
	ds_read_b128 v[174:177], v212 offset:19456
	ds_read_b128 v[214:217], v212 offset:20480
	ds_read_b128 v[218:221], v212 offset:21504
	ds_read_b128 v[222:225], v212 offset:22528
	ds_read_b128 v[226:229], v212 offset:23552
	global_load_lds_dwordx4 v[200:201], off
	s_add_i32 m0, s8, 0x2000
	s_add_u32 s22, s44, 0x40000
	v_lshl_add_u64 v[230:231], s[44:45], 0, v[194:195]
	s_addc_u32 s23, s45, 0
	s_add_i32 s2, s2, s3
	global_load_lds_dwordx4 v[230:231], off
	v_lshl_add_u64 v[232:233], s[22:23], 0, v[0:1]
	s_mov_b32 m0, s2
	v_lshl_add_u64 v[234:235], s[46:47], 0, v[192:193]
	global_load_lds_dwordx4 v[232:233], off
	v_lshl_add_u64 v[232:233], s[22:23], 0, v[194:195]
	s_add_i32 m0, s2, 0x2000
	s_nop 0
	global_load_lds_dwordx4 v[232:233], off
	v_lshl_add_u64 v[232:233], s[46:47], 0, v[190:191]
	s_mov_b32 m0, s12
	s_nop 0
	global_load_lds_dwordx4 v[232:233], off
	s_mov_b32 m0, s13
	s_nop 0
	global_load_lds_dwordx4 v[234:235], off
	s_waitcnt vmcnt(8)
	s_waitcnt lgkmcnt(0)
	s_barrier
	s_waitcnt lgkmcnt(0)
	v_mfma_f32_16x16x32_bf16 v[62:65], v[130:133], v[162:165], v[62:65]
	v_mfma_f32_16x16x32_bf16 v[30:33], v[138:141], v[162:165], v[30:33]
	v_mfma_f32_16x16x32_bf16 v[54:57], v[130:133], v[170:173], v[54:57]
	v_mfma_f32_16x16x32_bf16 v[22:25], v[138:141], v[170:173], v[22:25]
	v_mfma_f32_16x16x32_bf16 v[46:49], v[130:133], v[214:217], v[46:49]
	v_mfma_f32_16x16x32_bf16 v[14:17], v[138:141], v[214:217], v[14:17]
	v_mfma_f32_16x16x32_bf16 v[38:41], v[130:133], v[222:225], v[38:41]
	v_mfma_f32_16x16x32_bf16 v[6:9], v[138:141], v[222:225], v[6:9]
	v_mfma_f32_16x16x32_bf16 v[62:65], v[134:137], v[166:169], v[62:65]
	v_mfma_f32_16x16x32_bf16 v[30:33], v[142:145], v[166:169], v[30:33]
	v_mfma_f32_16x16x32_bf16 v[54:57], v[134:137], v[174:177], v[54:57]
	v_mfma_f32_16x16x32_bf16 v[22:25], v[142:145], v[174:177], v[22:25]
	v_mfma_f32_16x16x32_bf16 v[46:49], v[134:137], v[218:221], v[46:49]
	v_mfma_f32_16x16x32_bf16 v[14:17], v[142:145], v[218:221], v[14:17]
	v_mfma_f32_16x16x32_bf16 v[38:41], v[134:137], v[226:229], v[38:41]
	v_mfma_f32_16x16x32_bf16 v[6:9], v[142:145], v[226:229], v[6:9]
	v_mfma_f32_16x16x32_bf16 v[58:61], v[146:149], v[162:165], v[58:61]
	v_mfma_f32_16x16x32_bf16 v[26:29], v[154:157], v[162:165], v[26:29]
	v_mfma_f32_16x16x32_bf16 v[50:53], v[146:149], v[170:173], v[50:53]
	v_mfma_f32_16x16x32_bf16 v[18:21], v[154:157], v[170:173], v[18:21]
	v_mfma_f32_16x16x32_bf16 v[42:45], v[146:149], v[214:217], v[42:45]
	v_mfma_f32_16x16x32_bf16 v[10:13], v[154:157], v[214:217], v[10:13]
	v_mfma_f32_16x16x32_bf16 v[34:37], v[146:149], v[222:225], v[34:37]
	v_mfma_f32_16x16x32_bf16 v[2:5], v[154:157], v[222:225], v[2:5]
	v_mfma_f32_16x16x32_bf16 v[58:61], v[150:153], v[166:169], v[58:61]
	v_mfma_f32_16x16x32_bf16 v[26:29], v[158:161], v[166:169], v[26:29]
	v_mfma_f32_16x16x32_bf16 v[50:53], v[150:153], v[174:177], v[50:53]
	v_mfma_f32_16x16x32_bf16 v[18:21], v[158:161], v[174:177], v[18:21]
	v_mfma_f32_16x16x32_bf16 v[42:45], v[150:153], v[218:221], v[42:45]
	v_mfma_f32_16x16x32_bf16 v[10:13], v[158:161], v[218:221], v[10:13]
	v_mfma_f32_16x16x32_bf16 v[34:37], v[150:153], v[226:229], v[34:37]
	v_mfma_f32_16x16x32_bf16 v[2:5], v[158:161], v[226:229], v[2:5]
	s_barrier
; #define PG8_STAGE(bufoff, gbase, voff) do { _Pragma("unroll") for (int _i = 0; _i < 2; ++_i) \
;         __builtin_amdgcn_global_load_lds((const unsigned*)((const char*)(gbase) + (voff)[_i]), (PG8_LAS unsigned*)(lds + (bufoff) + ldsw + _i * 8192), 16, 0, 0); } while (0)
; #define PG8_LDA(dst, b, h) do { _Pragma("unroll") for (int m = 0; m < 4; ++m) _Pragma("unroll") for (int k = 0; k < 2; ++k) dst[m][k] = *(const PG8_LAS bf16x8*)(lds + PG8_SA(b, h) + aoff + m * 2048 + k * 1024); } while (0)
; #define PG8_LDB(dst, b, h) do { _Pragma("unroll") for (int n = 0; n < 2; ++n) _Pragma("unroll") for (int k = 0; k < 2; ++k) dst[n][k] = *(const PG8_LAS bf16x8*)(lds + PG8_SB(b, h) + boff + n * 2048 + k * 1024); } while (0)
; #define PG8_MMA(ai, bj, At, Bt) do { __builtin_amdgcn_s_setprio(1); _Pragma("unroll") for (int m = 0; m < 4; ++m) _Pragma("unroll") for (int n = 0; n < 2; ++n) _Pragma("unroll") for (int k = 0; k < 2; ++k) \
;         acc[ai][bj][m][n] = __builtin_amdgcn_mfma_f32_16x16x32_bf16(Bt[n][k], At[m][k], acc[ai][bj][m][n], 0, 0, 0); __builtin_amdgcn_s_setprio(0); } while (0)
; #define PG8_WAIT_V(n) asm volatile("s_waitcnt vmcnt(" #n ")" ::: "memory")
; #define PG8_WAIT_L(n) asm volatile("s_waitcnt lgkmcnt(" #n ")" ::: "memory")
; #define PG8_BAR __builtin_amdgcn_s_barrier()
; #define PG8_SCHED __builtin_amdgcn_sched_barrier(0)
; template <class Epi, class Sched, bool ALIGN_EPI = false, bool SP2 = false>
; __device__ __forceinline__ void gemm_phase(PG8_LAS unsigned char* lds, const Gemm g, const Sched& S, const Epi& E, const int wid_in) {
;     ...
;             PG8_LDB(B0, 1, 0); PG8_LDB(B1, 1, 1); PG8_SCHED; PG8_LDA(At, 1, 0); PG8_STAGE(PG8_SA(0, 1), a2 + hstep, voffA);
;             PG8_WAIT_V(8); PG8_WAIT_L(0); PG8_BAR; PG8_MMA(0, 0, At, B0); PG8_MMA(0, 1, At, B1); PG8_BAR; PG8_SCHED;
	s_add_i32 s2, 0, 0x18000
	s_add_i32 s8, 0, 0x1c000
	v_add_u32_e32 v142, s2, v211
	v_add_u32_e32 v158, s8, v211
	ds_read_b128 v[130:133], v142
	ds_read_b128 v[134:137], v142 offset:1024
	ds_read_b128 v[138:141], v142 offset:2048
	ds_read_b128 v[142:145], v142 offset:3072
	ds_read_b128 v[146:149], v158
	ds_read_b128 v[150:153], v158 offset:1024
	ds_read_b128 v[154:157], v158 offset:2048
	ds_read_b128 v[158:161], v158 offset:3072
	s_add_u32 s22, s46, 0x40000
	s_addc_u32 s23, s47, 0
	s_mov_b32 m0, s36
	v_lshl_add_u64 v[236:237], s[22:23], 0, v[190:191]
	ds_read_b128 v[162:165], v212 offset:32768
	ds_read_b128 v[166:169], v212 offset:33792
	ds_read_b128 v[170:173], v212 offset:34816
	ds_read_b128 v[174:177], v212 offset:35840
	ds_read_b128 v[214:217], v212 offset:36864
	ds_read_b128 v[218:221], v212 offset:37888
	ds_read_b128 v[222:225], v212 offset:38912
	ds_read_b128 v[226:229], v212 offset:39936
	global_load_lds_dwordx4 v[236:237], off
	v_lshl_add_u64 v[236:237], s[22:23], 0, v[192:193]
	s_mov_b32 m0, s37
	s_nop 0
	global_load_lds_dwordx4 v[236:237], off
	s_waitcnt vmcnt(8)
	s_waitcnt lgkmcnt(0)
	s_barrier
	s_waitcnt lgkmcnt(0)
	v_mfma_f32_16x16x32_bf16 v[126:129], v[130:133], v[162:165], v[126:129]
	v_mfma_f32_16x16x32_bf16 v[94:97], v[138:141], v[162:165], v[94:97]
	v_mfma_f32_16x16x32_bf16 v[118:121], v[130:133], v[170:173], v[118:121]
	v_mfma_f32_16x16x32_bf16 v[86:89], v[138:141], v[170:173], v[86:89]
	v_mfma_f32_16x16x32_bf16 v[110:113], v[130:133], v[214:217], v[110:113]
	v_mfma_f32_16x16x32_bf16 v[78:81], v[138:141], v[214:217], v[78:81]
	v_mfma_f32_16x16x32_bf16 v[102:105], v[130:133], v[222:225], v[102:105]
	v_mfma_f32_16x16x32_bf16 v[70:73], v[138:141], v[222:225], v[70:73]
	v_mfma_f32_16x16x32_bf16 v[126:129], v[134:137], v[166:169], v[126:129]
	v_mfma_f32_16x16x32_bf16 v[94:97], v[142:145], v[166:169], v[94:97]
	v_mfma_f32_16x16x32_bf16 v[118:121], v[134:137], v[174:177], v[118:121]
	v_mfma_f32_16x16x32_bf16 v[86:89], v[142:145], v[174:177], v[86:89]
	v_mfma_f32_16x16x32_bf16 v[110:113], v[134:137], v[218:221], v[110:113]
	v_mfma_f32_16x16x32_bf16 v[78:81], v[142:145], v[218:221], v[78:81]
	v_mfma_f32_16x16x32_bf16 v[102:105], v[134:137], v[226:229], v[102:105]
	v_mfma_f32_16x16x32_bf16 v[70:73], v[142:145], v[226:229], v[70:73]
	v_mfma_f32_16x16x32_bf16 v[122:125], v[146:149], v[162:165], v[122:125]
	v_mfma_f32_16x16x32_bf16 v[90:93], v[154:157], v[162:165], v[90:93]
	v_mfma_f32_16x16x32_bf16 v[114:117], v[146:149], v[170:173], v[114:117]
	v_mfma_f32_16x16x32_bf16 v[82:85], v[154:157], v[170:173], v[82:85]
	v_mfma_f32_16x16x32_bf16 v[106:109], v[146:149], v[214:217], v[106:109]
	v_mfma_f32_16x16x32_bf16 v[74:77], v[154:157], v[214:217], v[74:77]
	v_mfma_f32_16x16x32_bf16 v[98:101], v[146:149], v[222:225], v[98:101]
	v_mfma_f32_16x16x32_bf16 v[66:69], v[154:157], v[222:225], v[66:69]
	v_mfma_f32_16x16x32_bf16 v[122:125], v[150:153], v[166:169], v[122:125]
	v_mfma_f32_16x16x32_bf16 v[90:93], v[158:161], v[166:169], v[90:93]
	v_mfma_f32_16x16x32_bf16 v[114:117], v[150:153], v[174:177], v[114:117]
	v_mfma_f32_16x16x32_bf16 v[82:85], v[158:161], v[174:177], v[82:85]
	v_mfma_f32_16x16x32_bf16 v[106:109], v[150:153], v[218:221], v[106:109]
	v_mfma_f32_16x16x32_bf16 v[74:77], v[158:161], v[218:221], v[74:77]
	v_mfma_f32_16x16x32_bf16 v[98:101], v[150:153], v[226:229], v[98:101]
	v_mfma_f32_16x16x32_bf16 v[66:69], v[158:161], v[226:229], v[66:69]
	s_barrier
; #define PG8_STAGE(bufoff, gbase, voff) do { _Pragma("unroll") for (int _i = 0; _i < 2; ++_i) \
;         __builtin_amdgcn_global_load_lds((const unsigned*)((const char*)(gbase) + (voff)[_i]), (PG8_LAS unsigned*)(lds + (bufoff) + ldsw + _i * 8192), 16, 0, 0); } while (0)
; #define PG8_LDA(dst, b, h) do { _Pragma("unroll") for (int m = 0; m < 4; ++m) _Pragma("unroll") for (int k = 0; k < 2; ++k) dst[m][k] = *(const PG8_LAS bf16x8*)(lds + PG8_SA(b, h) + aoff + m * 2048 + k * 1024); } while (0)
; #define PG8_MMA(ai, bj, At, Bt) do { __builtin_amdgcn_s_setprio(1); _Pragma("unroll") for (int m = 0; m < 4; ++m) _Pragma("unroll") for (int n = 0; n < 2; ++n) _Pragma("unroll") for (int k = 0; k < 2; ++k) \
;         acc[ai][bj][m][n] = __builtin_amdgcn_mfma_f32_16x16x32_bf16(Bt[n][k], At[m][k], acc[ai][bj][m][n], 0, 0, 0); __builtin_amdgcn_s_setprio(0); } while (0)
; #define PG8_WAIT_V(n) asm volatile("s_waitcnt vmcnt(" #n ")" ::: "memory")
; #define PG8_WAIT_L(n) asm volatile("s_waitcnt lgkmcnt(" #n ")" ::: "memory")
; #define PG8_BAR __builtin_amdgcn_s_barrier()
; #define PG8_SCHED __builtin_amdgcn_sched_barrier(0)
; template <class Epi, class Sched, bool ALIGN_EPI = false, bool SP2 = false>
; __device__ __forceinline__ void gemm_phase(PG8_LAS unsigned char* lds, const Gemm g, const Sched& S, const Epi& E, const int wid_in) {
;     ...
;             PG8_LDA(At, 1, 1); PG8_STAGE(PG8_SB(1, 0), b3, voffB); PG8_STAGE(PG8_SB(1, 1), b3 + hstep, voffB); PG8_STAGE(PG8_SA(1, 0), a3, voffA);
;             PG8_WAIT_V(8); PG8_WAIT_L(0); PG8_BAR; PG8_MMA(1, 0, At, B0); PG8_MMA(1, 1, At, B1); PG8_BAR; PG8_SCHED;
;     ...
;         }
;         if constexpr (ALIGN_EPI) { if (wr == 0) PG8_BAR; }
	s_add_i32 s2, s2, s3
	v_lshl_add_u64 v[200:201], v[200:201], 0, s[64:65]
	s_mov_b32 m0, s2
	ds_read_b128 v[162:165], v212 offset:49152
	ds_read_b128 v[166:169], v212 offset:50176
	ds_read_b128 v[170:173], v212 offset:51200
	ds_read_b128 v[174:177], v212 offset:52224
	ds_read_b128 v[214:217], v212 offset:53248
	ds_read_b128 v[218:221], v212 offset:54272
	ds_read_b128 v[222:225], v212 offset:55296
	ds_read_b128 v[226:229], v212 offset:56320
	global_load_lds_dwordx4 v[200:201], off
	s_add_i32 m0, s2, 0x2000
	s_add_u32 s22, s44, 0x40080
	v_lshl_add_u64 v[200:201], v[230:231], 0, s[64:65]
	s_addc_u32 s23, s45, 0
	s_add_i32 s2, s8, s3
	global_load_lds_dwordx4 v[200:201], off
	v_lshl_add_u64 v[200:201], s[22:23], 0, v[0:1]
	s_mov_b32 m0, s2
	s_nop 0
	global_load_lds_dwordx4 v[200:201], off
	v_lshl_add_u64 v[200:201], s[22:23], 0, v[194:195]
	s_add_i32 m0, s2, 0x2000
	s_nop 0
	global_load_lds_dwordx4 v[200:201], off
	v_lshl_add_u64 v[200:201], v[232:233], 0, s[64:65]
	s_mov_b32 m0, s78
	s_nop 0
	global_load_lds_dwordx4 v[200:201], off
	v_lshl_add_u64 v[200:201], v[234:235], 0, s[64:65]
	s_mov_b32 m0, s79
	s_nop 0
	global_load_lds_dwordx4 v[200:201], off
	s_waitcnt vmcnt(8)
	s_waitcnt lgkmcnt(0)
	s_barrier
	s_waitcnt lgkmcnt(0)
	v_mfma_f32_16x16x32_bf16 v[62:65], v[130:133], v[162:165], v[62:65]
	v_mfma_f32_16x16x32_bf16 v[30:33], v[138:141], v[162:165], v[30:33]
	v_mfma_f32_16x16x32_bf16 v[54:57], v[130:133], v[170:173], v[54:57]
	v_mfma_f32_16x16x32_bf16 v[22:25], v[138:141], v[170:173], v[22:25]
	v_mfma_f32_16x16x32_bf16 v[46:49], v[130:133], v[214:217], v[46:49]
	v_mfma_f32_16x16x32_bf16 v[14:17], v[138:141], v[214:217], v[14:17]
	v_mfma_f32_16x16x32_bf16 v[38:41], v[130:133], v[222:225], v[38:41]
	v_mfma_f32_16x16x32_bf16 v[6:9], v[138:141], v[222:225], v[6:9]
	v_mfma_f32_16x16x32_bf16 v[62:65], v[134:137], v[166:169], v[62:65]
	v_mfma_f32_16x16x32_bf16 v[30:33], v[142:145], v[166:169], v[30:33]
	v_mfma_f32_16x16x32_bf16 v[54:57], v[134:137], v[174:177], v[54:57]
	v_mfma_f32_16x16x32_bf16 v[22:25], v[142:145], v[174:177], v[22:25]
	v_mfma_f32_16x16x32_bf16 v[46:49], v[134:137], v[218:221], v[46:49]
	v_mfma_f32_16x16x32_bf16 v[14:17], v[142:145], v[218:221], v[14:17]
	v_mfma_f32_16x16x32_bf16 v[38:41], v[134:137], v[226:229], v[38:41]
	v_mfma_f32_16x16x32_bf16 v[6:9], v[142:145], v[226:229], v[6:9]
	v_mfma_f32_16x16x32_bf16 v[58:61], v[146:149], v[162:165], v[58:61]
	v_mfma_f32_16x16x32_bf16 v[26:29], v[154:157], v[162:165], v[26:29]
	v_mfma_f32_16x16x32_bf16 v[50:53], v[146:149], v[170:173], v[50:53]
	v_mfma_f32_16x16x32_bf16 v[18:21], v[154:157], v[170:173], v[18:21]
	v_mfma_f32_16x16x32_bf16 v[42:45], v[146:149], v[214:217], v[42:45]
	v_mfma_f32_16x16x32_bf16 v[10:13], v[154:157], v[214:217], v[10:13]
	v_mfma_f32_16x16x32_bf16 v[34:37], v[146:149], v[222:225], v[34:37]
	v_mfma_f32_16x16x32_bf16 v[2:5], v[154:157], v[222:225], v[2:5]
	v_mfma_f32_16x16x32_bf16 v[58:61], v[150:153], v[166:169], v[58:61]
	v_mfma_f32_16x16x32_bf16 v[26:29], v[158:161], v[166:169], v[26:29]
	v_mfma_f32_16x16x32_bf16 v[50:53], v[150:153], v[174:177], v[50:53]
	v_mfma_f32_16x16x32_bf16 v[18:21], v[158:161], v[174:177], v[18:21]
	v_mfma_f32_16x16x32_bf16 v[42:45], v[150:153], v[218:221], v[42:45]
	v_mfma_f32_16x16x32_bf16 v[10:13], v[158:161], v[218:221], v[10:13]
	v_mfma_f32_16x16x32_bf16 v[34:37], v[150:153], v[226:229], v[34:37]
	v_mfma_f32_16x16x32_bf16 v[2:5], v[158:161], v[226:229], v[2:5]
	s_barrier
	s_add_i32 vcc_lo, vcc_lo, 2
	s_add_u32 s42, s42, 0x100
	s_addc_u32 s43, s43, 0
	s_add_u32 s61, s61, 0x100
	s_addc_u32 s62, s62, 0
	s_cmp_gt_u32 vcc_lo, 13
	s_cbranch_scc0 .LBB0_705
	s_setprio 0
	v_readlane_b32 s8, v243, 63
	v_readlane_b32 s9, v242, 0
	s_and_b64 vcc, exec, s[8:9]
	s_cbranch_vccz .LBB0_708
	s_barrier

; #define PG8_STAGE(bufoff, gbase, voff) do { _Pragma("unroll") for (int _i = 0; _i < 2; ++_i) \
;         __builtin_amdgcn_global_load_lds((const unsigned*)((const char*)(gbase) + (voff)[_i]), (PG8_LAS unsigned*)(lds + (bufoff) + ldsw + _i * 8192), 16, 0, 0); } while (0)
; #define PG8_LDA(dst, b, h) do { _Pragma("unroll") for (int m = 0; m < 4; ++m) _Pragma("unroll") for (int k = 0; k < 2; ++k) dst[m][k] = *(const PG8_LAS bf16x8*)(lds + PG8_SA(b, h) + aoff + m * 2048 + k * 1024); } while (0)
; #define PG8_LDB(dst, b, h) do { _Pragma("unroll") for (int n = 0; n < 2; ++n) _Pragma("unroll") for (int k = 0; k < 2; ++k) dst[n][k] = *(const PG8_LAS bf16x8*)(lds + PG8_SB(b, h) + boff + n * 2048 + k * 1024); } while (0)
; #define PG8_MMA(ai, bj, At, Bt) do { __builtin_amdgcn_s_setprio(1); _Pragma("unroll") for (int m = 0; m < 4; ++m) _Pragma("unroll") for (int n = 0; n < 2; ++n) _Pragma("unroll") for (int k = 0; k < 2; ++k) \
;         acc[ai][bj][m][n] = __builtin_amdgcn_mfma_f32_16x16x32_bf16(Bt[n][k], At[m][k], acc[ai][bj][m][n], 0, 0, 0); __builtin_amdgcn_s_setprio(0); } while (0)
; #define PG8_WAIT_V(n) asm volatile("s_waitcnt vmcnt(" #n ")" ::: "memory")
; #define PG8_WAIT_L(n) asm volatile("s_waitcnt lgkmcnt(" #n ")" ::: "memory")
; #define PG8_BAR __builtin_amdgcn_s_barrier()
; template <class Epi, class Sched, bool ALIGN_EPI = false, bool SP2 = false>
; __device__ __forceinline__ void gemm_phase(PG8_LAS unsigned char* lds, const Gemm g, const Sched& S, const Epi& E, const int wid_in) {
;     ...
;         for (int t = 0; t < nt; t += 2) {
;             const bool last = (t == nt - 2);
;             const char* a1 = cA + (size_t)(t + 1) * kstep;
;             const char* a2 = last ? nA : cA + (size_t)(t + 2) * kstep; const char* b2 = last ? nB : cB + (size_t)(t + 2) * kstep;
;             const char* a3 = a2 + kstep; const char* b3 = b2 + kstep;
;             if (last && has_next) S.a_ready(nxt);
;             if constexpr (SP2) {
;             PG8_LDB(B0, 0, 0); PG8_LDB(B1, 0, 1); PG8_SCHED; PG8_LDA(At, 0, 0); PG8_STAGE(PG8_SA(1, 1), a1 + hstep, voffA);
;             PG8_WAIT_V(8); PG8_WAIT_L(0); PG8_BAR; PG8_MMA(0, 0, At, B0); PG8_MMA(0, 1, At, B1); PG8_BAR; PG8_SCHED;
;             PG8_LDA(At, 0, 1); PG8_STAGE(PG8_SB(0, 0), b2, voffB); PG8_STAGE(PG8_SB(0, 1), b2 + hstep, voffB); PG8_STAGE(PG8_SA(0, 0), a2, voffA);
.LBB0_822:
	s_add_u32 s16, s46, 0x100
	s_addc_u32 s57, s47, 0
	s_mov_b32 s58, -2
	v_readlane_b32 s100, v243, 63
	v_readlane_b32 s101, v242, 0
	s_cmp_lg_u64 s[100:101], 0
	s_cbranch_scc1 .Lprio_done_823
	s_setprio 1
.Lprio_done_823:
	s_add_u32 s46, s44, 0x100
	s_addc_u32 s47, s45, 0
	s_add_i32 s2, 0, 0x10000
	s_cmp_eq_u32 s58, 40
	s_cselect_b32 s51, s41, s47
	s_cselect_b32 s50, s40, s46
	v_add_u32_e32 v140, s2, v142
	s_cselect_b32 s49, s43, s57
	s_cselect_b32 s48, s42, s16
	s_add_i32 s8, 0, 0x14000
	ds_read_b128 v[144:147], v140
	ds_read_b128 v[148:151], v140 offset:1024
	ds_read_b128 v[152:155], v140 offset:2048
	ds_read_b128 v[156:159], v140 offset:3072
	v_add_u32_e32 v140, s8, v142
	ds_read_b128 v[160:163], v140
	ds_read_b128 v[164:167], v140 offset:1024
	ds_read_b128 v[168:171], v140 offset:2048
	ds_read_b128 v[172:175], v140 offset:3072
	v_lshl_add_u64 v[140:141], s[44:45], 0, v[136:137]
	s_add_i32 m0, s4, 0xc000
	ds_read_b128 v[190:193], v143
	ds_read_b128 v[194:197], v143 offset:1024
	ds_read_b128 v[198:201], v143 offset:2048
	ds_read_b128 v[212:215], v143 offset:3072
	ds_read_b128 v[216:219], v143 offset:4096
	ds_read_b128 v[220:223], v143 offset:5120
	ds_read_b128 v[224:227], v143 offset:6144
	ds_read_b128 v[228:231], v143 offset:7168
	global_load_lds_dwordx4 v[140:141], off
	v_lshl_add_u64 v[140:141], s[44:45], 0, v[138:139]
	s_add_i32 m0, s4, 0xe000
	s_nop 0
	global_load_lds_dwordx4 v[140:141], off
	s_waitcnt vmcnt(8)
	s_waitcnt lgkmcnt(0)
	s_barrier
	s_waitcnt lgkmcnt(0)
	v_mfma_f32_16x16x32_bf16 v[126:129], v[144:147], v[190:193], 0
	v_mfma_f32_16x16x32_bf16 v[122:125], v[152:155], v[190:193], 0
	v_mfma_f32_16x16x32_bf16 v[118:121], v[144:147], v[198:201], 0
	v_mfma_f32_16x16x32_bf16 v[110:113], v[152:155], v[198:201], 0
	v_mfma_f32_16x16x32_bf16 v[102:105], v[144:147], v[216:219], 0
	v_mfma_f32_16x16x32_bf16 v[94:97], v[152:155], v[216:219], 0
	v_mfma_f32_16x16x32_bf16 v[82:85], v[144:147], v[224:227], 0
	v_mfma_f32_16x16x32_bf16 v[74:77], v[152:155], v[224:227], 0
	v_mfma_f32_16x16x32_bf16 v[126:129], v[148:151], v[194:197], v[126:129]
	v_mfma_f32_16x16x32_bf16 v[122:125], v[156:159], v[194:197], v[122:125]
	v_mfma_f32_16x16x32_bf16 v[118:121], v[148:151], v[212:215], v[118:121]
	v_mfma_f32_16x16x32_bf16 v[110:113], v[156:159], v[212:215], v[110:113]
	v_mfma_f32_16x16x32_bf16 v[102:105], v[148:151], v[220:223], v[102:105]
	v_mfma_f32_16x16x32_bf16 v[94:97], v[156:159], v[220:223], v[94:97]
	v_mfma_f32_16x16x32_bf16 v[82:85], v[148:151], v[228:231], v[82:85]
	v_mfma_f32_16x16x32_bf16 v[74:77], v[156:159], v[228:231], v[74:77]
	v_mfma_f32_16x16x32_bf16 v[114:117], v[160:163], v[190:193], 0
	v_mfma_f32_16x16x32_bf16 v[106:109], v[168:171], v[190:193], 0
	v_mfma_f32_16x16x32_bf16 v[98:101], v[160:163], v[198:201], 0
	v_mfma_f32_16x16x32_bf16 v[90:93], v[168:171], v[198:201], 0
	v_mfma_f32_16x16x32_bf16 v[86:89], v[160:163], v[216:219], 0
	v_mfma_f32_16x16x32_bf16 v[78:81], v[168:171], v[216:219], 0
	v_mfma_f32_16x16x32_bf16 v[70:73], v[160:163], v[224:227], 0
	v_mfma_f32_16x16x32_bf16 v[66:69], v[168:171], v[224:227], 0
	v_mfma_f32_16x16x32_bf16 v[114:117], v[164:167], v[194:197], v[114:117]
	v_mfma_f32_16x16x32_bf16 v[106:109], v[172:175], v[194:197], v[106:109]
	v_mfma_f32_16x16x32_bf16 v[98:101], v[164:167], v[212:215], v[98:101]
	v_mfma_f32_16x16x32_bf16 v[90:93], v[172:175], v[212:215], v[90:93]
	v_mfma_f32_16x16x32_bf16 v[86:89], v[164:167], v[220:223], v[86:89]
	v_mfma_f32_16x16x32_bf16 v[78:81], v[172:175], v[220:223], v[78:81]
	v_mfma_f32_16x16x32_bf16 v[70:73], v[164:167], v[228:231], v[70:73]
	v_mfma_f32_16x16x32_bf16 v[66:69], v[172:175], v[228:231], v[66:69]
	s_barrier
	s_add_i32 s2, s2, s3
	v_lshl_add_u64 v[140:141], s[48:49], 0, v[0:1]
	s_mov_b32 m0, s2
	ds_read_b128 v[190:193], v143 offset:16384
	ds_read_b128 v[194:197], v143 offset:17408
	ds_read_b128 v[198:201], v143 offset:18432
	ds_read_b128 v[212:215], v143 offset:19456
	ds_read_b128 v[216:219], v143 offset:20480
	ds_read_b128 v[220:223], v143 offset:21504
	ds_read_b128 v[224:227], v143 offset:22528
	ds_read_b128 v[228:231], v143 offset:23552
	global_load_lds_dwordx4 v[140:141], off
	s_add_i32 m0, s2, 0x2000
	s_add_u32 s22, s48, 0xb0000
	v_lshl_add_u64 v[176:177], s[48:49], 0, v[130:131]
	s_addc_u32 s23, s49, 0
	s_add_i32 s2, s8, s3
	global_load_lds_dwordx4 v[176:177], off
	v_lshl_add_u64 v[232:233], s[22:23], 0, v[0:1]
	s_mov_b32 m0, s2
	v_lshl_add_u64 v[234:235], s[50:51], 0, v[132:133]
	global_load_lds_dwordx4 v[232:233], off
	v_lshl_add_u64 v[232:233], s[22:23], 0, v[130:131]
	s_add_i32 m0, s2, 0x2000
	s_nop 0
	global_load_lds_dwordx4 v[232:233], off
	v_lshl_add_u64 v[232:233], s[50:51], 0, v[134:135]
	s_mov_b32 m0, s4
	s_nop 0
	global_load_lds_dwordx4 v[232:233], off
	s_mov_b32 m0, s5
	s_nop 0
	global_load_lds_dwordx4 v[234:235], off
	s_waitcnt vmcnt(8)
	s_waitcnt lgkmcnt(0)
	s_barrier
; #define PG8_STAGE(bufoff, gbase, voff) do { _Pragma("unroll") for (int _i = 0; _i < 2; ++_i) \
;         __builtin_amdgcn_global_load_lds((const unsigned*)((const char*)(gbase) + (voff)[_i]), (PG8_LAS unsigned*)(lds + (bufoff) + ldsw + _i * 8192), 16, 0, 0); } while (0)
; #define PG8_LDA(dst, b, h) do { _Pragma("unroll") for (int m = 0; m < 4; ++m) _Pragma("unroll") for (int k = 0; k < 2; ++k) dst[m][k] = *(const PG8_LAS bf16x8*)(lds + PG8_SA(b, h) + aoff + m * 2048 + k * 1024); } while (0)
; #define PG8_LDB(dst, b, h) do { _Pragma("unroll") for (int n = 0; n < 2; ++n) _Pragma("unroll") for (int k = 0; k < 2; ++k) dst[n][k] = *(const PG8_LAS bf16x8*)(lds + PG8_SB(b, h) + boff + n * 2048 + k * 1024); } while (0)
; #define PG8_MMA(ai, bj, At, Bt) do { __builtin_amdgcn_s_setprio(1); _Pragma("unroll") for (int m = 0; m < 4; ++m) _Pragma("unroll") for (int n = 0; n < 2; ++n) _Pragma("unroll") for (int k = 0; k < 2; ++k) \
;         acc[ai][bj][m][n] = __builtin_amdgcn_mfma_f32_16x16x32_bf16(Bt[n][k], At[m][k], acc[ai][bj][m][n], 0, 0, 0); __builtin_amdgcn_s_setprio(0); } while (0)
; #define PG8_WAIT_V(n) asm volatile("s_waitcnt vmcnt(" #n ")" ::: "memory")
; #define PG8_WAIT_L(n) asm volatile("s_waitcnt lgkmcnt(" #n ")" ::: "memory")
; #define PG8_BAR __builtin_amdgcn_s_barrier()
; #define PG8_SCHED __builtin_amdgcn_sched_barrier(0)
; template <class Epi, class Sched, bool ALIGN_EPI = false, bool SP2 = false>
; __device__ __forceinline__ void gemm_phase(PG8_LAS unsigned char* lds, const Gemm g, const Sched& S, const Epi& E, const int wid_in) {
;     ...
;             PG8_WAIT_V(8); PG8_WAIT_L(0); PG8_BAR; PG8_MMA(0, 0, At, B0); PG8_MMA(0, 1, At, B1); PG8_BAR; PG8_SCHED;
;             PG8_LDA(At, 0, 1); PG8_STAGE(PG8_SB(0, 0), b2, voffB); PG8_STAGE(PG8_SB(0, 1), b2 + hstep, voffB); PG8_STAGE(PG8_SA(0, 0), a2, voffA);
;             PG8_WAIT_V(8); PG8_WAIT_L(0); PG8_BAR; PG8_MMA(1, 0, At, B0); PG8_MMA(1, 1, At, B1); PG8_BAR; PG8_SCHED;
;             PG8_LDB(B0, 1, 0); PG8_LDB(B1, 1, 1); PG8_SCHED; PG8_LDA(At, 1, 0); PG8_STAGE(PG8_SA(0, 1), a2 + hstep, voffA);
;             PG8_WAIT_V(8); PG8_WAIT_L(0); PG8_BAR; PG8_MMA(0, 0, At, B0); PG8_MMA(0, 1, At, B1); PG8_BAR; PG8_SCHED;
	s_waitcnt lgkmcnt(0)
	v_mfma_f32_16x16x32_bf16 v[62:65], v[144:147], v[190:193], 0
	v_mfma_f32_16x16x32_bf16 v[58:61], v[152:155], v[190:193], 0
	v_mfma_f32_16x16x32_bf16 v[54:57], v[144:147], v[198:201], 0
	v_mfma_f32_16x16x32_bf16 v[46:49], v[152:155], v[198:201], 0
	v_mfma_f32_16x16x32_bf16 v[38:41], v[144:147], v[216:219], 0
	v_mfma_f32_16x16x32_bf16 v[30:33], v[152:155], v[216:219], 0
	v_mfma_f32_16x16x32_bf16 v[22:25], v[144:147], v[224:227], 0
	v_mfma_f32_16x16x32_bf16 v[14:17], v[152:155], v[224:227], 0
	v_mfma_f32_16x16x32_bf16 v[62:65], v[148:151], v[194:197], v[62:65]
	v_mfma_f32_16x16x32_bf16 v[58:61], v[156:159], v[194:197], v[58:61]
	v_mfma_f32_16x16x32_bf16 v[54:57], v[148:151], v[212:215], v[54:57]
	v_mfma_f32_16x16x32_bf16 v[46:49], v[156:159], v[212:215], v[46:49]
	v_mfma_f32_16x16x32_bf16 v[38:41], v[148:151], v[220:223], v[38:41]
	v_mfma_f32_16x16x32_bf16 v[30:33], v[156:159], v[220:223], v[30:33]
	v_mfma_f32_16x16x32_bf16 v[22:25], v[148:151], v[228:231], v[22:25]
	v_mfma_f32_16x16x32_bf16 v[14:17], v[156:159], v[228:231], v[14:17]
	v_mfma_f32_16x16x32_bf16 v[50:53], v[160:163], v[190:193], 0
	v_mfma_f32_16x16x32_bf16 v[42:45], v[168:171], v[190:193], 0
	v_mfma_f32_16x16x32_bf16 v[34:37], v[160:163], v[198:201], 0
	v_mfma_f32_16x16x32_bf16 v[26:29], v[168:171], v[198:201], 0
	v_mfma_f32_16x16x32_bf16 v[18:21], v[160:163], v[216:219], 0
	v_mfma_f32_16x16x32_bf16 v[10:13], v[168:171], v[216:219], 0
	v_mfma_f32_16x16x32_bf16 v[6:9], v[160:163], v[224:227], 0
	v_mfma_f32_16x16x32_bf16 v[2:5], v[168:171], v[224:227], 0
	v_mfma_f32_16x16x32_bf16 v[50:53], v[164:167], v[194:197], v[50:53]
	v_mfma_f32_16x16x32_bf16 v[42:45], v[172:175], v[194:197], v[42:45]
	v_mfma_f32_16x16x32_bf16 v[34:37], v[164:167], v[212:215], v[34:37]
	v_mfma_f32_16x16x32_bf16 v[26:29], v[172:175], v[212:215], v[26:29]
	v_mfma_f32_16x16x32_bf16 v[18:21], v[164:167], v[220:223], v[18:21]
	v_mfma_f32_16x16x32_bf16 v[10:13], v[172:175], v[220:223], v[10:13]
	v_mfma_f32_16x16x32_bf16 v[6:9], v[164:167], v[228:231], v[6:9]
	v_mfma_f32_16x16x32_bf16 v[2:5], v[172:175], v[228:231], v[2:5]
	s_barrier
	s_add_i32 s2, 0, 0x18000
	s_add_i32 s8, 0, 0x1c000
	v_add_u32_e32 v156, s2, v142
	v_add_u32_e32 v172, s8, v142
	ds_read_b128 v[144:147], v156
	ds_read_b128 v[148:151], v156 offset:1024
	ds_read_b128 v[152:155], v156 offset:2048
	ds_read_b128 v[156:159], v156 offset:3072
	ds_read_b128 v[160:163], v172
	ds_read_b128 v[164:167], v172 offset:1024
	ds_read_b128 v[168:171], v172 offset:2048
	ds_read_b128 v[172:175], v172 offset:3072
	s_add_u32 s22, s50, 0xb0000
	s_addc_u32 s23, s51, 0
	s_mov_b32 m0, s12
	v_lshl_add_u64 v[236:237], s[22:23], 0, v[134:135]
	ds_read_b128 v[190:193], v143 offset:32768
	ds_read_b128 v[194:197], v143 offset:33792
	ds_read_b128 v[198:201], v143 offset:34816
	ds_read_b128 v[212:215], v143 offset:35840
	ds_read_b128 v[216:219], v143 offset:36864
	ds_read_b128 v[220:223], v143 offset:37888
	ds_read_b128 v[224:227], v143 offset:38912
	ds_read_b128 v[228:231], v143 offset:39936
	global_load_lds_dwordx4 v[236:237], off
	v_lshl_add_u64 v[236:237], s[22:23], 0, v[132:133]
	s_mov_b32 m0, s13
	s_nop 0
	global_load_lds_dwordx4 v[236:237], off
	s_waitcnt vmcnt(8)
	s_waitcnt lgkmcnt(0)
	s_barrier
	s_waitcnt lgkmcnt(0)
	v_mfma_f32_16x16x32_bf16 v[126:129], v[144:147], v[190:193], v[126:129]
	v_mfma_f32_16x16x32_bf16 v[122:125], v[152:155], v[190:193], v[122:125]
	v_mfma_f32_16x16x32_bf16 v[118:121], v[144:147], v[198:201], v[118:121]
	v_mfma_f32_16x16x32_bf16 v[110:113], v[152:155], v[198:201], v[110:113]
	v_mfma_f32_16x16x32_bf16 v[102:105], v[144:147], v[216:219], v[102:105]
	v_mfma_f32_16x16x32_bf16 v[94:97], v[152:155], v[216:219], v[94:97]
	v_mfma_f32_16x16x32_bf16 v[82:85], v[144:147], v[224:227], v[82:85]
	v_mfma_f32_16x16x32_bf16 v[74:77], v[152:155], v[224:227], v[74:77]
	v_mfma_f32_16x16x32_bf16 v[126:129], v[148:151], v[194:197], v[126:129]
	v_mfma_f32_16x16x32_bf16 v[122:125], v[156:159], v[194:197], v[122:125]
	v_mfma_f32_16x16x32_bf16 v[118:121], v[148:151], v[212:215], v[118:121]
	v_mfma_f32_16x16x32_bf16 v[110:113], v[156:159], v[212:215], v[110:113]
	v_mfma_f32_16x16x32_bf16 v[102:105], v[148:151], v[220:223], v[102:105]
	v_mfma_f32_16x16x32_bf16 v[94:97], v[156:159], v[220:223], v[94:97]
	v_mfma_f32_16x16x32_bf16 v[82:85], v[148:151], v[228:231], v[82:85]
	v_mfma_f32_16x16x32_bf16 v[74:77], v[156:159], v[228:231], v[74:77]
	v_mfma_f32_16x16x32_bf16 v[114:117], v[160:163], v[190:193], v[114:117]
	v_mfma_f32_16x16x32_bf16 v[106:109], v[168:171], v[190:193], v[106:109]
	v_mfma_f32_16x16x32_bf16 v[98:101], v[160:163], v[198:201], v[98:101]
	v_mfma_f32_16x16x32_bf16 v[90:93], v[168:171], v[198:201], v[90:93]
	v_mfma_f32_16x16x32_bf16 v[86:89], v[160:163], v[216:219], v[86:89]
	v_mfma_f32_16x16x32_bf16 v[78:81], v[168:171], v[216:219], v[78:81]
	v_mfma_f32_16x16x32_bf16 v[70:73], v[160:163], v[224:227], v[70:73]
	v_mfma_f32_16x16x32_bf16 v[66:69], v[168:171], v[224:227], v[66:69]
	v_mfma_f32_16x16x32_bf16 v[114:117], v[164:167], v[194:197], v[114:117]
	v_mfma_f32_16x16x32_bf16 v[106:109], v[172:175], v[194:197], v[106:109]
	v_mfma_f32_16x16x32_bf16 v[98:101], v[164:167], v[212:215], v[98:101]
	v_mfma_f32_16x16x32_bf16 v[90:93], v[172:175], v[212:215], v[90:93]
	v_mfma_f32_16x16x32_bf16 v[86:89], v[164:167], v[220:223], v[86:89]
	v_mfma_f32_16x16x32_bf16 v[78:81], v[172:175], v[220:223], v[78:81]
	v_mfma_f32_16x16x32_bf16 v[70:73], v[164:167], v[228:231], v[70:73]
	v_mfma_f32_16x16x32_bf16 v[66:69], v[172:175], v[228:231], v[66:69]
	s_barrier
; #define PG8_STAGE(bufoff, gbase, voff) do { _Pragma("unroll") for (int _i = 0; _i < 2; ++_i) \
;         __builtin_amdgcn_global_load_lds((const unsigned*)((const char*)(gbase) + (voff)[_i]), (PG8_LAS unsigned*)(lds + (bufoff) + ldsw + _i * 8192), 16, 0, 0); } while (0)
; #define PG8_LDA(dst, b, h) do { _Pragma("unroll") for (int m = 0; m < 4; ++m) _Pragma("unroll") for (int k = 0; k < 2; ++k) dst[m][k] = *(const PG8_LAS bf16x8*)(lds + PG8_SA(b, h) + aoff + m * 2048 + k * 1024); } while (0)
; #define PG8_LDB(dst, b, h) do { _Pragma("unroll") for (int n = 0; n < 2; ++n) _Pragma("unroll") for (int k = 0; k < 2; ++k) dst[n][k] = *(const PG8_LAS bf16x8*)(lds + PG8_SB(b, h) + boff + n * 2048 + k * 1024); } while (0)
; #define PG8_WAIT_V(n) asm volatile("s_waitcnt vmcnt(" #n ")" ::: "memory")
; template <class Epi, class Sched, bool ALIGN_EPI = false, bool SP2 = false>
; __device__ __forceinline__ void gemm_phase(PG8_LAS unsigned char* lds, const Gemm g, const Sched& S, const Epi& E, const int wid_in) {
;     ...
;         for (int t = 0; t < nt; t += 2) {
;             const bool last = (t == nt - 2);
;             const char* a1 = cA + (size_t)(t + 1) * kstep;
;             const char* a2 = last ? nA : cA + (size_t)(t + 2) * kstep; const char* b2 = last ? nB : cB + (size_t)(t + 2) * kstep;
;             const char* a3 = a2 + kstep; const char* b3 = b2 + kstep;
;             if (last && has_next) S.a_ready(nxt);
;             if constexpr (SP2) {
;             PG8_LDB(B0, 0, 0); PG8_LDB(B1, 0, 1); PG8_SCHED; PG8_LDA(At, 0, 0); PG8_STAGE(PG8_SA(1, 1), a1 + hstep, voffA);
;             PG8_WAIT_V(8); PG8_WAIT_L(0); PG8_BAR; PG8_MMA(0, 0, At, B0); PG8_MMA(0, 1, At, B1); PG8_BAR; PG8_SCHED;
;             PG8_LDA(At, 0, 1); PG8_STAGE(PG8_SB(0, 0), b2, voffB); PG8_STAGE(PG8_SB(0, 1), b2 + hstep, voffB); PG8_STAGE(PG8_SA(0, 0), a2, voffA);
;             PG8_WAIT_V(8); PG8_WAIT_L(0); PG8_BAR; PG8_MMA(1, 0, At, B0); PG8_MMA(1, 1, At, B1); PG8_BAR; PG8_SCHED;
;             PG8_LDB(B0, 1, 0); PG8_LDB(B1, 1, 1); PG8_SCHED; PG8_LDA(At, 1, 0); PG8_STAGE(PG8_SA(0, 1), a2 + hstep, voffA);
;             PG8_WAIT_V(8); PG8_WAIT_L(0); PG8_BAR; PG8_MMA(0, 0, At, B0); PG8_MMA(0, 1, At, B1); PG8_BAR; PG8_SCHED;
;             PG8_LDA(At, 1, 1); PG8_STAGE(PG8_SB(1, 0), b3, voffB); PG8_STAGE(PG8_SB(1, 1), b3 + hstep, voffB); PG8_STAGE(PG8_SA(1, 0), a3, voffA);
	s_add_i32 s2, s2, s3
	v_lshl_add_u64 v[140:141], v[140:141], 0, s[64:65]
	s_mov_b32 m0, s2
	ds_read_b128 v[190:193], v143 offset:49152
	ds_read_b128 v[194:197], v143 offset:50176
	ds_read_b128 v[198:201], v143 offset:51200
	ds_read_b128 v[212:215], v143 offset:52224
	ds_read_b128 v[216:219], v143 offset:53248
	ds_read_b128 v[220:223], v143 offset:54272
	ds_read_b128 v[224:227], v143 offset:55296
	ds_read_b128 v[228:231], v143 offset:56320
	global_load_lds_dwordx4 v[140:141], off
	s_add_i32 m0, s2, 0x2000
	s_add_u32 s22, s48, 0xb0080
	v_lshl_add_u64 v[140:141], v[176:177], 0, s[64:65]
	s_addc_u32 s23, s49, 0
	s_add_i32 s2, s8, s3
	global_load_lds_dwordx4 v[140:141], off
	v_lshl_add_u64 v[140:141], s[22:23], 0, v[0:1]
	s_mov_b32 m0, s2
	s_nop 0
	global_load_lds_dwordx4 v[140:141], off
	v_lshl_add_u64 v[140:141], s[22:23], 0, v[130:131]
	s_add_i32 m0, s2, 0x2000
	s_nop 0
	global_load_lds_dwordx4 v[140:141], off
	v_lshl_add_u64 v[140:141], v[232:233], 0, s[64:65]
	s_mov_b32 m0, s36
	s_nop 0
	global_load_lds_dwordx4 v[140:141], off
	v_lshl_add_u64 v[140:141], v[234:235], 0, s[64:65]
	s_mov_b32 m0, s37
	s_nop 0
	global_load_lds_dwordx4 v[140:141], off
	s_waitcnt vmcnt(8)
	s_waitcnt lgkmcnt(0)
	s_barrier
	s_waitcnt lgkmcnt(0)
	v_mfma_f32_16x16x32_bf16 v[62:65], v[144:147], v[190:193], v[62:65]
	v_mfma_f32_16x16x32_bf16 v[58:61], v[152:155], v[190:193], v[58:61]
	v_mfma_f32_16x16x32_bf16 v[54:57], v[144:147], v[198:201], v[54:57]
	v_mfma_f32_16x16x32_bf16 v[46:49], v[152:155], v[198:201], v[46:49]
	v_mfma_f32_16x16x32_bf16 v[38:41], v[144:147], v[216:219], v[38:41]
	v_mfma_f32_16x16x32_bf16 v[30:33], v[152:155], v[216:219], v[30:33]
	v_mfma_f32_16x16x32_bf16 v[22:25], v[144:147], v[224:227], v[22:25]
	v_mfma_f32_16x16x32_bf16 v[14:17], v[152:155], v[224:227], v[14:17]
	v_mfma_f32_16x16x32_bf16 v[62:65], v[148:151], v[194:197], v[62:65]
	v_mfma_f32_16x16x32_bf16 v[58:61], v[156:159], v[194:197], v[58:61]
	v_mfma_f32_16x16x32_bf16 v[54:57], v[148:151], v[212:215], v[54:57]
	v_mfma_f32_16x16x32_bf16 v[46:49], v[156:159], v[212:215], v[46:49]
	v_mfma_f32_16x16x32_bf16 v[38:41], v[148:151], v[220:223], v[38:41]
	v_mfma_f32_16x16x32_bf16 v[30:33], v[156:159], v[220:223], v[30:33]
	v_mfma_f32_16x16x32_bf16 v[22:25], v[148:151], v[228:231], v[22:25]
	v_mfma_f32_16x16x32_bf16 v[14:17], v[156:159], v[228:231], v[14:17]
	v_mfma_f32_16x16x32_bf16 v[50:53], v[160:163], v[190:193], v[50:53]
	v_mfma_f32_16x16x32_bf16 v[42:45], v[168:171], v[190:193], v[42:45]
	v_mfma_f32_16x16x32_bf16 v[34:37], v[160:163], v[198:201], v[34:37]
	v_mfma_f32_16x16x32_bf16 v[26:29], v[168:171], v[198:201], v[26:29]
	v_mfma_f32_16x16x32_bf16 v[18:21], v[160:163], v[216:219], v[18:21]
	v_mfma_f32_16x16x32_bf16 v[10:13], v[168:171], v[216:219], v[10:13]
	v_mfma_f32_16x16x32_bf16 v[6:9], v[160:163], v[224:227], v[6:9]
	v_mfma_f32_16x16x32_bf16 v[2:5], v[168:171], v[224:227], v[2:5]
	v_mfma_f32_16x16x32_bf16 v[50:53], v[164:167], v[194:197], v[50:53]
	v_mfma_f32_16x16x32_bf16 v[42:45], v[172:175], v[194:197], v[42:45]
	v_mfma_f32_16x16x32_bf16 v[34:37], v[164:167], v[212:215], v[34:37]
	v_mfma_f32_16x16x32_bf16 v[26:29], v[172:175], v[212:215], v[26:29]
	v_mfma_f32_16x16x32_bf16 v[18:21], v[164:167], v[220:223], v[18:21]
	v_mfma_f32_16x16x32_bf16 v[10:13], v[172:175], v[220:223], v[10:13]
	v_mfma_f32_16x16x32_bf16 v[6:9], v[164:167], v[228:231], v[6:9]
	v_mfma_f32_16x16x32_bf16 v[2:5], v[172:175], v[228:231], v[2:5]
	s_barrier
	s_add_i32 s58, s58, 2
	s_add_u32 s16, s16, 0x100
	s_addc_u32 s57, s57, 0
	s_cmp_gt_u32 s58, 41
	s_mov_b64 s[44:45], s[46:47]
.LBB0_823:
	s_add_u32 s46, s44, 0x100
	s_addc_u32 s47, s45, 0
	s_add_i32 s2, 0, 0x10000
	s_cmp_eq_u32 s58, 40
	s_cselect_b32 s51, s41, s47
	s_cselect_b32 s50, s40, s46
	v_add_u32_e32 v140, s2, v142
	s_cselect_b32 s49, s43, s57
	s_cselect_b32 s48, s42, s16
	s_add_i32 s8, 0, 0x14000
	ds_read_b128 v[144:147], v140
	ds_read_b128 v[148:151], v140 offset:1024
	ds_read_b128 v[152:155], v140 offset:2048
	ds_read_b128 v[156:159], v140 offset:3072
	v_add_u32_e32 v140, s8, v142
	ds_read_b128 v[160:163], v140
	ds_read_b128 v[164:167], v140 offset:1024
	ds_read_b128 v[168:171], v140 offset:2048
	ds_read_b128 v[172:175], v140 offset:3072
	v_lshl_add_u64 v[140:141], s[44:45], 0, v[136:137]
	s_add_i32 m0, s4, 0xc000
	ds_read_b128 v[190:193], v143
	ds_read_b128 v[194:197], v143 offset:1024
	ds_read_b128 v[198:201], v143 offset:2048
	ds_read_b128 v[212:215], v143 offset:3072
	ds_read_b128 v[216:219], v143 offset:4096
	ds_read_b128 v[220:223], v143 offset:5120
	ds_read_b128 v[224:227], v143 offset:6144
	ds_read_b128 v[228:231], v143 offset:7168
	global_load_lds_dwordx4 v[140:141], off
	v_lshl_add_u64 v[140:141], s[44:45], 0, v[138:139]
	s_add_i32 m0, s4, 0xe000
	s_nop 0
	global_load_lds_dwordx4 v[140:141], off
	s_waitcnt vmcnt(8)
	s_waitcnt lgkmcnt(0)
	s_barrier
; #define PG8_STAGE(bufoff, gbase, voff) do { _Pragma("unroll") for (int _i = 0; _i < 2; ++_i) \
;         __builtin_amdgcn_global_load_lds((const unsigned*)((const char*)(gbase) + (voff)[_i]), (PG8_LAS unsigned*)(lds + (bufoff) + ldsw + _i * 8192), 16, 0, 0); } while (0)
; #define PG8_LDA(dst, b, h) do { _Pragma("unroll") for (int m = 0; m < 4; ++m) _Pragma("unroll") for (int k = 0; k < 2; ++k) dst[m][k] = *(const PG8_LAS bf16x8*)(lds + PG8_SA(b, h) + aoff + m * 2048 + k * 1024); } while (0)
; #define PG8_LDB(dst, b, h) do { _Pragma("unroll") for (int n = 0; n < 2; ++n) _Pragma("unroll") for (int k = 0; k < 2; ++k) dst[n][k] = *(const PG8_LAS bf16x8*)(lds + PG8_SB(b, h) + boff + n * 2048 + k * 1024); } while (0)
; #define PG8_MMA(ai, bj, At, Bt) do { __builtin_amdgcn_s_setprio(1); _Pragma("unroll") for (int m = 0; m < 4; ++m) _Pragma("unroll") for (int n = 0; n < 2; ++n) _Pragma("unroll") for (int k = 0; k < 2; ++k) \
;         acc[ai][bj][m][n] = __builtin_amdgcn_mfma_f32_16x16x32_bf16(Bt[n][k], At[m][k], acc[ai][bj][m][n], 0, 0, 0); __builtin_amdgcn_s_setprio(0); } while (0)
; #define PG8_WAIT_V(n) asm volatile("s_waitcnt vmcnt(" #n ")" ::: "memory")
; #define PG8_WAIT_L(n) asm volatile("s_waitcnt lgkmcnt(" #n ")" ::: "memory")
; #define PG8_BAR __builtin_amdgcn_s_barrier()
; #define PG8_SCHED __builtin_amdgcn_sched_barrier(0)
; template <class Epi, class Sched, bool ALIGN_EPI = false, bool SP2 = false>
; __device__ __forceinline__ void gemm_phase(PG8_LAS unsigned char* lds, const Gemm g, const Sched& S, const Epi& E, const int wid_in) {
;     ...
;             PG8_LDB(B0, 0, 0); PG8_LDB(B1, 0, 1); PG8_SCHED; PG8_LDA(At, 0, 0); PG8_STAGE(PG8_SA(1, 1), a1 + hstep, voffA);
;             PG8_WAIT_V(8); PG8_WAIT_L(0); PG8_BAR; PG8_MMA(0, 0, At, B0); PG8_MMA(0, 1, At, B1); PG8_BAR; PG8_SCHED;
;             PG8_LDA(At, 0, 1); PG8_STAGE(PG8_SB(0, 0), b2, voffB); PG8_STAGE(PG8_SB(0, 1), b2 + hstep, voffB); PG8_STAGE(PG8_SA(0, 0), a2, voffA);
;             PG8_WAIT_V(8); PG8_WAIT_L(0); PG8_BAR; PG8_MMA(1, 0, At, B0); PG8_MMA(1, 1, At, B1); PG8_BAR; PG8_SCHED;
	s_waitcnt lgkmcnt(0)
	v_mfma_f32_16x16x32_bf16 v[126:129], v[144:147], v[190:193], v[126:129]
	v_mfma_f32_16x16x32_bf16 v[122:125], v[152:155], v[190:193], v[122:125]
	v_mfma_f32_16x16x32_bf16 v[118:121], v[144:147], v[198:201], v[118:121]
	v_mfma_f32_16x16x32_bf16 v[110:113], v[152:155], v[198:201], v[110:113]
	v_mfma_f32_16x16x32_bf16 v[102:105], v[144:147], v[216:219], v[102:105]
	v_mfma_f32_16x16x32_bf16 v[94:97], v[152:155], v[216:219], v[94:97]
	v_mfma_f32_16x16x32_bf16 v[82:85], v[144:147], v[224:227], v[82:85]
	v_mfma_f32_16x16x32_bf16 v[74:77], v[152:155], v[224:227], v[74:77]
	v_mfma_f32_16x16x32_bf16 v[126:129], v[148:151], v[194:197], v[126:129]
	v_mfma_f32_16x16x32_bf16 v[122:125], v[156:159], v[194:197], v[122:125]
	v_mfma_f32_16x16x32_bf16 v[118:121], v[148:151], v[212:215], v[118:121]
	v_mfma_f32_16x16x32_bf16 v[110:113], v[156:159], v[212:215], v[110:113]
	v_mfma_f32_16x16x32_bf16 v[102:105], v[148:151], v[220:223], v[102:105]
	v_mfma_f32_16x16x32_bf16 v[94:97], v[156:159], v[220:223], v[94:97]
	v_mfma_f32_16x16x32_bf16 v[82:85], v[148:151], v[228:231], v[82:85]
	v_mfma_f32_16x16x32_bf16 v[74:77], v[156:159], v[228:231], v[74:77]
	v_mfma_f32_16x16x32_bf16 v[114:117], v[160:163], v[190:193], v[114:117]
	v_mfma_f32_16x16x32_bf16 v[106:109], v[168:171], v[190:193], v[106:109]
	v_mfma_f32_16x16x32_bf16 v[98:101], v[160:163], v[198:201], v[98:101]
	v_mfma_f32_16x16x32_bf16 v[90:93], v[168:171], v[198:201], v[90:93]
	v_mfma_f32_16x16x32_bf16 v[86:89], v[160:163], v[216:219], v[86:89]
	v_mfma_f32_16x16x32_bf16 v[78:81], v[168:171], v[216:219], v[78:81]
	v_mfma_f32_16x16x32_bf16 v[70:73], v[160:163], v[224:227], v[70:73]
	v_mfma_f32_16x16x32_bf16 v[66:69], v[168:171], v[224:227], v[66:69]
	v_mfma_f32_16x16x32_bf16 v[114:117], v[164:167], v[194:197], v[114:117]
	v_mfma_f32_16x16x32_bf16 v[106:109], v[172:175], v[194:197], v[106:109]
	v_mfma_f32_16x16x32_bf16 v[98:101], v[164:167], v[212:215], v[98:101]
	v_mfma_f32_16x16x32_bf16 v[90:93], v[172:175], v[212:215], v[90:93]
	v_mfma_f32_16x16x32_bf16 v[86:89], v[164:167], v[220:223], v[86:89]
	v_mfma_f32_16x16x32_bf16 v[78:81], v[172:175], v[220:223], v[78:81]
	v_mfma_f32_16x16x32_bf16 v[70:73], v[164:167], v[228:231], v[70:73]
	v_mfma_f32_16x16x32_bf16 v[66:69], v[172:175], v[228:231], v[66:69]
	s_barrier
	s_add_i32 s2, s2, s3
	v_lshl_add_u64 v[140:141], s[48:49], 0, v[0:1]
	s_mov_b32 m0, s2
	ds_read_b128 v[190:193], v143 offset:16384
	ds_read_b128 v[194:197], v143 offset:17408
	ds_read_b128 v[198:201], v143 offset:18432
	ds_read_b128 v[212:215], v143 offset:19456
	ds_read_b128 v[216:219], v143 offset:20480
	ds_read_b128 v[220:223], v143 offset:21504
	ds_read_b128 v[224:227], v143 offset:22528
	ds_read_b128 v[228:231], v143 offset:23552
	global_load_lds_dwordx4 v[140:141], off
	s_add_i32 m0, s2, 0x2000
	s_add_u32 s22, s48, 0xb0000
	v_lshl_add_u64 v[176:177], s[48:49], 0, v[130:131]
	s_addc_u32 s23, s49, 0
	s_add_i32 s2, s8, s3
	global_load_lds_dwordx4 v[176:177], off
	v_lshl_add_u64 v[232:233], s[22:23], 0, v[0:1]
	s_mov_b32 m0, s2
	v_lshl_add_u64 v[234:235], s[50:51], 0, v[132:133]
	global_load_lds_dwordx4 v[232:233], off
	v_lshl_add_u64 v[232:233], s[22:23], 0, v[130:131]
	s_add_i32 m0, s2, 0x2000
	s_nop 0
	global_load_lds_dwordx4 v[232:233], off
	v_lshl_add_u64 v[232:233], s[50:51], 0, v[134:135]
	s_mov_b32 m0, s4
	s_nop 0
	global_load_lds_dwordx4 v[232:233], off
	s_mov_b32 m0, s5
	s_nop 0
	global_load_lds_dwordx4 v[234:235], off
	s_waitcnt vmcnt(8)
	s_waitcnt lgkmcnt(0)
	s_barrier
	s_waitcnt lgkmcnt(0)
	v_mfma_f32_16x16x32_bf16 v[62:65], v[144:147], v[190:193], v[62:65]
	v_mfma_f32_16x16x32_bf16 v[58:61], v[152:155], v[190:193], v[58:61]
	v_mfma_f32_16x16x32_bf16 v[54:57], v[144:147], v[198:201], v[54:57]
	v_mfma_f32_16x16x32_bf16 v[46:49], v[152:155], v[198:201], v[46:49]
	v_mfma_f32_16x16x32_bf16 v[38:41], v[144:147], v[216:219], v[38:41]
	v_mfma_f32_16x16x32_bf16 v[30:33], v[152:155], v[216:219], v[30:33]
	v_mfma_f32_16x16x32_bf16 v[22:25], v[144:147], v[224:227], v[22:25]
	v_mfma_f32_16x16x32_bf16 v[14:17], v[152:155], v[224:227], v[14:17]
	v_mfma_f32_16x16x32_bf16 v[62:65], v[148:151], v[194:197], v[62:65]
	v_mfma_f32_16x16x32_bf16 v[58:61], v[156:159], v[194:197], v[58:61]
	v_mfma_f32_16x16x32_bf16 v[54:57], v[148:151], v[212:215], v[54:57]
	v_mfma_f32_16x16x32_bf16 v[46:49], v[156:159], v[212:215], v[46:49]
	v_mfma_f32_16x16x32_bf16 v[38:41], v[148:151], v[220:223], v[38:41]
	v_mfma_f32_16x16x32_bf16 v[30:33], v[156:159], v[220:223], v[30:33]
	v_mfma_f32_16x16x32_bf16 v[22:25], v[148:151], v[228:231], v[22:25]
	v_mfma_f32_16x16x32_bf16 v[14:17], v[156:159], v[228:231], v[14:17]
	v_mfma_f32_16x16x32_bf16 v[50:53], v[160:163], v[190:193], v[50:53]
	v_mfma_f32_16x16x32_bf16 v[42:45], v[168:171], v[190:193], v[42:45]
	v_mfma_f32_16x16x32_bf16 v[34:37], v[160:163], v[198:201], v[34:37]
	v_mfma_f32_16x16x32_bf16 v[26:29], v[168:171], v[198:201], v[26:29]
	v_mfma_f32_16x16x32_bf16 v[18:21], v[160:163], v[216:219], v[18:21]
	v_mfma_f32_16x16x32_bf16 v[10:13], v[168:171], v[216:219], v[10:13]
	v_mfma_f32_16x16x32_bf16 v[6:9], v[160:163], v[224:227], v[6:9]
	v_mfma_f32_16x16x32_bf16 v[2:5], v[168:171], v[224:227], v[2:5]
	v_mfma_f32_16x16x32_bf16 v[50:53], v[164:167], v[194:197], v[50:53]
	v_mfma_f32_16x16x32_bf16 v[42:45], v[172:175], v[194:197], v[42:45]
	v_mfma_f32_16x16x32_bf16 v[34:37], v[164:167], v[212:215], v[34:37]
	v_mfma_f32_16x16x32_bf16 v[26:29], v[172:175], v[212:215], v[26:29]
	v_mfma_f32_16x16x32_bf16 v[18:21], v[164:167], v[220:223], v[18:21]
	v_mfma_f32_16x16x32_bf16 v[10:13], v[172:175], v[220:223], v[10:13]
	v_mfma_f32_16x16x32_bf16 v[6:9], v[164:167], v[228:231], v[6:9]
	v_mfma_f32_16x16x32_bf16 v[2:5], v[172:175], v[228:231], v[2:5]
	s_barrier
; #define PG8_STAGE(bufoff, gbase, voff) do { _Pragma("unroll") for (int _i = 0; _i < 2; ++_i) \
;         __builtin_amdgcn_global_load_lds((const unsigned*)((const char*)(gbase) + (voff)[_i]), (PG8_LAS unsigned*)(lds + (bufoff) + ldsw + _i * 8192), 16, 0, 0); } while (0)
; #define PG8_LDA(dst, b, h) do { _Pragma("unroll") for (int m = 0; m < 4; ++m) _Pragma("unroll") for (int k = 0; k < 2; ++k) dst[m][k] = *(const PG8_LAS bf16x8*)(lds + PG8_SA(b, h) + aoff + m * 2048 + k * 1024); } while (0)
; #define PG8_LDB(dst, b, h) do { _Pragma("unroll") for (int n = 0; n < 2; ++n) _Pragma("unroll") for (int k = 0; k < 2; ++k) dst[n][k] = *(const PG8_LAS bf16x8*)(lds + PG8_SB(b, h) + boff + n * 2048 + k * 1024); } while (0)
; #define PG8_MMA(ai, bj, At, Bt) do { __builtin_amdgcn_s_setprio(1); _Pragma("unroll") for (int m = 0; m < 4; ++m) _Pragma("unroll") for (int n = 0; n < 2; ++n) _Pragma("unroll") for (int k = 0; k < 2; ++k) \
;         acc[ai][bj][m][n] = __builtin_amdgcn_mfma_f32_16x16x32_bf16(Bt[n][k], At[m][k], acc[ai][bj][m][n], 0, 0, 0); __builtin_amdgcn_s_setprio(0); } while (0)
; #define PG8_WAIT_V(n) asm volatile("s_waitcnt vmcnt(" #n ")" ::: "memory")
; #define PG8_WAIT_L(n) asm volatile("s_waitcnt lgkmcnt(" #n ")" ::: "memory")
; #define PG8_BAR __builtin_amdgcn_s_barrier()
; #define PG8_SCHED __builtin_amdgcn_sched_barrier(0)
; template <class Epi, class Sched, bool ALIGN_EPI = false, bool SP2 = false>
; __device__ __forceinline__ void gemm_phase(PG8_LAS unsigned char* lds, const Gemm g, const Sched& S, const Epi& E, const int wid_in) {
;     ...
;             PG8_LDB(B0, 1, 0); PG8_LDB(B1, 1, 1); PG8_SCHED; PG8_LDA(At, 1, 0); PG8_STAGE(PG8_SA(0, 1), a2 + hstep, voffA);
;             PG8_WAIT_V(8); PG8_WAIT_L(0); PG8_BAR; PG8_MMA(0, 0, At, B0); PG8_MMA(0, 1, At, B1); PG8_BAR; PG8_SCHED;
	s_add_i32 s2, 0, 0x18000
	s_add_i32 s8, 0, 0x1c000
	v_add_u32_e32 v156, s2, v142
	v_add_u32_e32 v172, s8, v142
	ds_read_b128 v[144:147], v156
	ds_read_b128 v[148:151], v156 offset:1024
	ds_read_b128 v[152:155], v156 offset:2048
	ds_read_b128 v[156:159], v156 offset:3072
	ds_read_b128 v[160:163], v172
	ds_read_b128 v[164:167], v172 offset:1024
	ds_read_b128 v[168:171], v172 offset:2048
	ds_read_b128 v[172:175], v172 offset:3072
	s_add_u32 s22, s50, 0xb0000
	s_addc_u32 s23, s51, 0
	s_mov_b32 m0, s12
	v_lshl_add_u64 v[236:237], s[22:23], 0, v[134:135]
	ds_read_b128 v[190:193], v143 offset:32768
	ds_read_b128 v[194:197], v143 offset:33792
	ds_read_b128 v[198:201], v143 offset:34816
	ds_read_b128 v[212:215], v143 offset:35840
	ds_read_b128 v[216:219], v143 offset:36864
	ds_read_b128 v[220:223], v143 offset:37888
	ds_read_b128 v[224:227], v143 offset:38912
	ds_read_b128 v[228:231], v143 offset:39936
	global_load_lds_dwordx4 v[236:237], off
	v_lshl_add_u64 v[236:237], s[22:23], 0, v[132:133]
	s_mov_b32 m0, s13
	s_nop 0
	global_load_lds_dwordx4 v[236:237], off
	s_waitcnt vmcnt(8)
	s_waitcnt lgkmcnt(0)
	s_barrier
	s_waitcnt lgkmcnt(0)
	v_mfma_f32_16x16x32_bf16 v[126:129], v[144:147], v[190:193], v[126:129]
	v_mfma_f32_16x16x32_bf16 v[122:125], v[152:155], v[190:193], v[122:125]
	v_mfma_f32_16x16x32_bf16 v[118:121], v[144:147], v[198:201], v[118:121]
	v_mfma_f32_16x16x32_bf16 v[110:113], v[152:155], v[198:201], v[110:113]
	v_mfma_f32_16x16x32_bf16 v[102:105], v[144:147], v[216:219], v[102:105]
	v_mfma_f32_16x16x32_bf16 v[94:97], v[152:155], v[216:219], v[94:97]
	v_mfma_f32_16x16x32_bf16 v[82:85], v[144:147], v[224:227], v[82:85]
	v_mfma_f32_16x16x32_bf16 v[74:77], v[152:155], v[224:227], v[74:77]
	v_mfma_f32_16x16x32_bf16 v[126:129], v[148:151], v[194:197], v[126:129]
	v_mfma_f32_16x16x32_bf16 v[122:125], v[156:159], v[194:197], v[122:125]
	v_mfma_f32_16x16x32_bf16 v[118:121], v[148:151], v[212:215], v[118:121]
	v_mfma_f32_16x16x32_bf16 v[110:113], v[156:159], v[212:215], v[110:113]
	v_mfma_f32_16x16x32_bf16 v[102:105], v[148:151], v[220:223], v[102:105]
	v_mfma_f32_16x16x32_bf16 v[94:97], v[156:159], v[220:223], v[94:97]
	v_mfma_f32_16x16x32_bf16 v[82:85], v[148:151], v[228:231], v[82:85]
	v_mfma_f32_16x16x32_bf16 v[74:77], v[156:159], v[228:231], v[74:77]
	v_mfma_f32_16x16x32_bf16 v[114:117], v[160:163], v[190:193], v[114:117]
	v_mfma_f32_16x16x32_bf16 v[106:109], v[168:171], v[190:193], v[106:109]
	v_mfma_f32_16x16x32_bf16 v[98:101], v[160:163], v[198:201], v[98:101]
	v_mfma_f32_16x16x32_bf16 v[90:93], v[168:171], v[198:201], v[90:93]
	v_mfma_f32_16x16x32_bf16 v[86:89], v[160:163], v[216:219], v[86:89]
	v_mfma_f32_16x16x32_bf16 v[78:81], v[168:171], v[216:219], v[78:81]
	v_mfma_f32_16x16x32_bf16 v[70:73], v[160:163], v[224:227], v[70:73]
	v_mfma_f32_16x16x32_bf16 v[66:69], v[168:171], v[224:227], v[66:69]
	v_mfma_f32_16x16x32_bf16 v[114:117], v[164:167], v[194:197], v[114:117]
	v_mfma_f32_16x16x32_bf16 v[106:109], v[172:175], v[194:197], v[106:109]
	v_mfma_f32_16x16x32_bf16 v[98:101], v[164:167], v[212:215], v[98:101]
	v_mfma_f32_16x16x32_bf16 v[90:93], v[172:175], v[212:215], v[90:93]
	v_mfma_f32_16x16x32_bf16 v[86:89], v[164:167], v[220:223], v[86:89]
	v_mfma_f32_16x16x32_bf16 v[78:81], v[172:175], v[220:223], v[78:81]
	v_mfma_f32_16x16x32_bf16 v[70:73], v[164:167], v[228:231], v[70:73]
	v_mfma_f32_16x16x32_bf16 v[66:69], v[172:175], v[228:231], v[66:69]
	s_barrier
; #define PG8_STAGE(bufoff, gbase, voff) do { _Pragma("unroll") for (int _i = 0; _i < 2; ++_i) \
;         __builtin_amdgcn_global_load_lds((const unsigned*)((const char*)(gbase) + (voff)[_i]), (PG8_LAS unsigned*)(lds + (bufoff) + ldsw + _i * 8192), 16, 0, 0); } while (0)
; #define PG8_LDA(dst, b, h) do { _Pragma("unroll") for (int m = 0; m < 4; ++m) _Pragma("unroll") for (int k = 0; k < 2; ++k) dst[m][k] = *(const PG8_LAS bf16x8*)(lds + PG8_SA(b, h) + aoff + m * 2048 + k * 1024); } while (0)
; #define PG8_MMA(ai, bj, At, Bt) do { __builtin_amdgcn_s_setprio(1); _Pragma("unroll") for (int m = 0; m < 4; ++m) _Pragma("unroll") for (int n = 0; n < 2; ++n) _Pragma("unroll") for (int k = 0; k < 2; ++k) \
;         acc[ai][bj][m][n] = __builtin_amdgcn_mfma_f32_16x16x32_bf16(Bt[n][k], At[m][k], acc[ai][bj][m][n], 0, 0, 0); __builtin_amdgcn_s_setprio(0); } while (0)
; #define PG8_WAIT_V(n) asm volatile("s_waitcnt vmcnt(" #n ")" ::: "memory")
; #define PG8_WAIT_L(n) asm volatile("s_waitcnt lgkmcnt(" #n ")" ::: "memory")
; #define PG8_BAR __builtin_amdgcn_s_barrier()
; #define PG8_SCHED __builtin_amdgcn_sched_barrier(0)
; template <class Epi, class Sched, bool ALIGN_EPI = false, bool SP2 = false>
; __device__ __forceinline__ void gemm_phase(PG8_LAS unsigned char* lds, const Gemm g, const Sched& S, const Epi& E, const int wid_in) {
;     ...
;             PG8_LDA(At, 1, 1); PG8_STAGE(PG8_SB(1, 0), b3, voffB); PG8_STAGE(PG8_SB(1, 1), b3 + hstep, voffB); PG8_STAGE(PG8_SA(1, 0), a3, voffA);
;             PG8_WAIT_V(8); PG8_WAIT_L(0); PG8_BAR; PG8_MMA(1, 0, At, B0); PG8_MMA(1, 1, At, B1); PG8_BAR; PG8_SCHED;
;     ...
;         }
;         if constexpr (ALIGN_EPI) { if (wr == 0) PG8_BAR; }
	s_add_i32 s2, s2, s3
	v_lshl_add_u64 v[140:141], v[140:141], 0, s[64:65]
	s_mov_b32 m0, s2
	ds_read_b128 v[190:193], v143 offset:49152
	ds_read_b128 v[194:197], v143 offset:50176
	ds_read_b128 v[198:201], v143 offset:51200
	ds_read_b128 v[212:215], v143 offset:52224
	ds_read_b128 v[216:219], v143 offset:53248
	ds_read_b128 v[220:223], v143 offset:54272
	ds_read_b128 v[224:227], v143 offset:55296
	ds_read_b128 v[228:231], v143 offset:56320
	global_load_lds_dwordx4 v[140:141], off
	s_add_i32 m0, s2, 0x2000
	s_add_u32 s22, s48, 0xb0080
	v_lshl_add_u64 v[140:141], v[176:177], 0, s[64:65]
	s_addc_u32 s23, s49, 0
	s_add_i32 s2, s8, s3
	global_load_lds_dwordx4 v[140:141], off
	v_lshl_add_u64 v[140:141], s[22:23], 0, v[0:1]
	s_mov_b32 m0, s2
	s_nop 0
	global_load_lds_dwordx4 v[140:141], off
	v_lshl_add_u64 v[140:141], s[22:23], 0, v[130:131]
	s_add_i32 m0, s2, 0x2000
	s_nop 0
	global_load_lds_dwordx4 v[140:141], off
	v_lshl_add_u64 v[140:141], v[232:233], 0, s[64:65]
	s_mov_b32 m0, s36
	s_nop 0
	global_load_lds_dwordx4 v[140:141], off
	v_lshl_add_u64 v[140:141], v[234:235], 0, s[64:65]
	s_mov_b32 m0, s37
	s_nop 0
	global_load_lds_dwordx4 v[140:141], off
	s_waitcnt vmcnt(8)
	s_waitcnt lgkmcnt(0)
	s_barrier
	s_waitcnt lgkmcnt(0)
	v_mfma_f32_16x16x32_bf16 v[62:65], v[144:147], v[190:193], v[62:65]
	v_mfma_f32_16x16x32_bf16 v[58:61], v[152:155], v[190:193], v[58:61]
	v_mfma_f32_16x16x32_bf16 v[54:57], v[144:147], v[198:201], v[54:57]
	v_mfma_f32_16x16x32_bf16 v[46:49], v[152:155], v[198:201], v[46:49]
	v_mfma_f32_16x16x32_bf16 v[38:41], v[144:147], v[216:219], v[38:41]
	v_mfma_f32_16x16x32_bf16 v[30:33], v[152:155], v[216:219], v[30:33]
	v_mfma_f32_16x16x32_bf16 v[22:25], v[144:147], v[224:227], v[22:25]
	v_mfma_f32_16x16x32_bf16 v[14:17], v[152:155], v[224:227], v[14:17]
	v_mfma_f32_16x16x32_bf16 v[62:65], v[148:151], v[194:197], v[62:65]
	v_mfma_f32_16x16x32_bf16 v[58:61], v[156:159], v[194:197], v[58:61]
	v_mfma_f32_16x16x32_bf16 v[54:57], v[148:151], v[212:215], v[54:57]
	v_mfma_f32_16x16x32_bf16 v[46:49], v[156:159], v[212:215], v[46:49]
	v_mfma_f32_16x16x32_bf16 v[38:41], v[148:151], v[220:223], v[38:41]
	v_mfma_f32_16x16x32_bf16 v[30:33], v[156:159], v[220:223], v[30:33]
	v_mfma_f32_16x16x32_bf16 v[22:25], v[148:151], v[228:231], v[22:25]
	v_mfma_f32_16x16x32_bf16 v[14:17], v[156:159], v[228:231], v[14:17]
	v_mfma_f32_16x16x32_bf16 v[50:53], v[160:163], v[190:193], v[50:53]
	v_mfma_f32_16x16x32_bf16 v[42:45], v[168:171], v[190:193], v[42:45]
	v_mfma_f32_16x16x32_bf16 v[34:37], v[160:163], v[198:201], v[34:37]
	v_mfma_f32_16x16x32_bf16 v[26:29], v[168:171], v[198:201], v[26:29]
	v_mfma_f32_16x16x32_bf16 v[18:21], v[160:163], v[216:219], v[18:21]
	v_mfma_f32_16x16x32_bf16 v[10:13], v[168:171], v[216:219], v[10:13]
	v_mfma_f32_16x16x32_bf16 v[6:9], v[160:163], v[224:227], v[6:9]
	v_mfma_f32_16x16x32_bf16 v[2:5], v[168:171], v[224:227], v[2:5]
	v_mfma_f32_16x16x32_bf16 v[50:53], v[164:167], v[194:197], v[50:53]
	v_mfma_f32_16x16x32_bf16 v[42:45], v[172:175], v[194:197], v[42:45]
	v_mfma_f32_16x16x32_bf16 v[34:37], v[164:167], v[212:215], v[34:37]
	v_mfma_f32_16x16x32_bf16 v[26:29], v[172:175], v[212:215], v[26:29]
	v_mfma_f32_16x16x32_bf16 v[18:21], v[164:167], v[220:223], v[18:21]
	v_mfma_f32_16x16x32_bf16 v[10:13], v[172:175], v[220:223], v[10:13]
	v_mfma_f32_16x16x32_bf16 v[6:9], v[164:167], v[228:231], v[6:9]
	v_mfma_f32_16x16x32_bf16 v[2:5], v[172:175], v[228:231], v[2:5]
	s_barrier
	s_add_i32 s58, s58, 2
	s_add_u32 s16, s16, 0x100
	s_addc_u32 s57, s57, 0
	s_cmp_gt_u32 s58, 41
	s_mov_b64 s[44:45], s[46:47]
	s_cbranch_scc0 .LBB0_823
	s_setprio 0
	v_readlane_b32 s8, v243, 63
	v_readlane_b32 s9, v242, 0
	s_and_b64 vcc, exec, s[8:9]
	s_cbranch_vccz .LBB0_826
	s_barrier
